# scan-wave loop unrolled x8 with immediate ring-slot offsets; reads kept clumped; output butterfly interleaved with head of next group
# speedup vs baseline: 1.0025x; 1.0025x over previous
; #define LAS3 __attribute__((address_space(3)))
; DEV void rwkv_helper(const Params& p, const Ctx& cx, int l, int unit, int lane, char* ring) {
;   const int d = unit & 1, h = (unit >> 1) & 15, b = unit >> 5;
;   const int j = lane >> 4, s = lane & 15;
;   const h16* SC = (const h16*)(p.ws + OFF_SCAN);
;   const char* pR = (const char*)(SC + 0 * ARR + h * 64);
;   const char* pK = (const char*)(SC + 1 * ARR + h * 64);
;   const char* pV = (const char*)(SC + 2 * ARR + h * 64);
;   const char* pKK = (const char*)(SC + 3 * ARR + h * 64);
;   const char* pA = (const char*)(SC + (size_t)(4 + d) * ARR + h * 64);
;   const char* pW = (const char*)(SC + (size_t)(6 + d) * ARR + h * 64);
;   const int jm = d ? 3 - j : j;
;   const unsigned vo0 = (unsigned)(jm * 2048 + s * 8);
;   f4v ka4, om4;
;   {
;     float4 t = *(const float4*)(p.rwkv_k_a + (size_t)l * 1024 + h * 64 + 4 * s);
;     ka4 = f4v{t.x, t.y, t.z, t.w};
;     om4 = 1.f - ka4;
;   }
;   struct RGH { u2v w, a, kk, k, r, v; };
;   RGH q0, q1, q2, q3, q4, q5, q6, q7;
;   const unsigned wofs = (unsigned)(j * 128 + s * 8);
;   const unsigned vwofs = (unsigned)(2560 + j * 128 + s * 8);
;   LAS3 volatile int* pflag = (LAS3 volatile int*)(ring + RW_FLAGS);
;   LAS3 volatile int* cflag = (LAS3 volatile int*)(ring + RW_FLAGS + 64);
;   int cmin = 0;
;     ...
;   RH_LOAD(q0, 0); RH_LOAD(q1, 1); RH_LOAD(q2, 2); RH_LOAD(q3, 3); RH_LOAD(q4, 4); RH_LOAD(q5, 5); RH_LOAD(q6, 6); RH_LOAD(q7, 7);
.LBB0_177:
	s_waitcnt lgkmcnt(0)
	s_barrier
	s_and_saveexec_b64 s[42:43], s[70:71]
	ds_write_b32 v118, v129 offset:49152
	s_or_b64 exec, exec, s[42:43]
	s_and_b32 s34, s31, 63
	s_and_b64 vcc, exec, s[72:73]
	s_waitcnt lgkmcnt(0)
	s_barrier
	s_cbranch_vccz .LBB0_223
	s_mov_b64 s[88:89], 0
	s_and_b64 vcc, exec, s[68:69]
	s_mov_b64 s[42:43], 0
	s_cbranch_vccz .LBB0_224
	s_setprio 1
	v_lshl_add_u32 v183, v116, 1, v116
	v_mul_u32_u24_e32 v182, 0x7e, v107
	v_sub_u32_e32 v182, v183, v182
	v_and_b32_e32 v186, 1, v107
	v_mul_u32_u24_e32 v186, 0x78, v186
	v_sub_u32_e32 v186, v116, v186
	s_lshl_b32 s0, s34, 5
	s_and_b32 s5, s0, 0x3c0
	s_and_b32 s23, s31, 1
	s_bfe_i32 s4, s31, 0x10000
	s_lshr_b32 s22, s34, 5
	s_lshl_b32 s10, s5, 1
	s_add_u32 s94, s2, s10
	s_addc_u32 s95, s3, 0
	v_readlane_b32 s0, v241, 30
	v_readlane_b32 s1, v241, 31
	s_add_u32 s97, s0, s10
	s_addc_u32 s99, s1, 0
	v_readlane_b32 s0, v241, 32
	v_readlane_b32 s1, v241, 33
	s_add_u32 s0, s0, s10
	s_addc_u32 s1, s1, 0
	v_readlane_b32 s36, v241, 42
	v_readlane_b32 s37, v241, 43
	s_add_u32 s8, s36, s10
	s_addc_u32 s84, s37, 0
	s_mul_i32 s33, s23, 0x4100000
	s_add_u32 s33, s2, s33
	s_addc_u32 s35, s3, 0
	s_add_u32 s10, s33, s10
	s_addc_u32 s33, s35, 0
	s_add_u32 s85, s10, 0x10400000
	s_addc_u32 s86, s33, 0
	s_add_u32 s87, s10, 0x18600000
	s_addc_u32 s35, s33, 0
	s_lshl_b32 s33, s22, 8
	s_bitset1_b32 s33, 15
	s_and_b32 s4, s4, 0xfc
	s_or_b32 s4, s33, s4
	s_lshl_b32 s10, s5, 2
	s_lshl_b32 s42, s4, 11
	s_add_u32 s4, s87, s42
	s_addc_u32 s5, s35, 0
	s_add_u32 s36, s85, s42
	s_addc_u32 s37, s86, 0
	s_add_u32 s44, s8, s42
	s_addc_u32 s45, s84, 0
	s_add_u32 s90, s97, s42
	s_addc_u32 s91, s99, 0
	s_add_u32 s92, s94, s42
	s_addc_u32 s93, s95, 0
	s_add_u32 vcc_lo, s0, s42
	s_addc_u32 vcc_hi, s1, 0
	s_cmp_eq_u32 s23, 0
	s_cselect_b64 s[42:43], -1, 0
	v_cndmask_b32_e64 v0, v109, v108, s[42:43]
	v_or_b32_e32 v119, v0, v110
	v_lshl_add_u64 v[0:1], v[80:81], 0, s[10:11]
	s_waitcnt vmcnt(0)
	v_mov_b32_e32 v8, v119
	global_load_dwordx4 v[0:3], v[0:1], off
	global_load_dwordx2 v[4:5], v8, s[4:5]
	global_load_dwordx2 v[36:37], v8, s[36:37]
	global_load_dwordx2 v[6:7], v8, s[44:45]
	global_load_dwordx2 v[44:45], v8, s[90:91]
	global_load_dwordx2 v[38:39], v8, s[92:93]
	global_load_dwordx2 v[42:43], v8, vcc
	s_and_b64 s[4:5], s[42:43], exec
	s_cselect_b32 s4, 4, 0xf8
	s_cselect_b32 s37, 8, 0xf4
	s_cselect_b32 s44, 12, 0xf0
	s_cselect_b32 s45, 16, 0xec
	s_cselect_b32 s36, 20, 0xe8
	s_cselect_b32 s23, 24, 0xe4
	s_cselect_b32 s10, 28, 0xe0
	s_or_b32 s4, s33, s4
	s_lshl_b32 s90, s4, 11
	s_add_u32 s4, s87, s90
	v_mov_b32_e32 v12, v119
	s_addc_u32 s5, s35, 0
	global_load_dwordx2 v[8:9], v12, s[4:5]
	s_add_u32 s4, s85, s90
	s_addc_u32 s5, s86, 0
	global_load_dwordx2 v[40:41], v12, s[4:5]
	s_add_u32 s4, s8, s90
	s_addc_u32 s5, s84, 0
	global_load_dwordx2 v[10:11], v12, s[4:5]
	s_add_u32 s4, s97, s90
	s_addc_u32 s5, s99, 0
	global_load_dwordx2 v[52:53], v12, s[4:5]
	s_add_u32 s4, s94, s90
	s_addc_u32 s5, s95, 0
	global_load_dwordx2 v[46:47], v12, s[4:5]
	s_add_u32 s4, s0, s90
	s_addc_u32 s5, s1, 0
	global_load_dwordx2 v[50:51], v12, s[4:5]
	s_or_b32 s4, s33, s37
	s_lshl_b32 s37, s4, 11
	s_add_u32 s4, s87, s37
	v_mov_b32_e32 v16, v119
	s_addc_u32 s5, s35, 0
	global_load_dwordx2 v[12:13], v16, s[4:5]
	s_add_u32 s4, s85, s37
	s_addc_u32 s5, s86, 0
	global_load_dwordx2 v[48:49], v16, s[4:5]
	s_add_u32 s4, s8, s37
	s_addc_u32 s5, s84, 0
	global_load_dwordx2 v[14:15], v16, s[4:5]
	s_add_u32 s4, s97, s37
	s_addc_u32 s5, s99, 0
	global_load_dwordx2 v[60:61], v16, s[4:5]
	s_add_u32 s4, s94, s37
	s_addc_u32 s5, s95, 0
	global_load_dwordx2 v[54:55], v16, s[4:5]
	s_add_u32 s4, s0, s37
	s_addc_u32 s5, s1, 0
	global_load_dwordx2 v[58:59], v16, s[4:5]
	s_or_b32 s4, s33, s44
	s_lshl_b32 s37, s4, 11
	s_add_u32 s4, s87, s37
	v_mov_b32_e32 v20, v119
	s_addc_u32 s5, s35, 0
	global_load_dwordx2 v[16:17], v20, s[4:5]
	s_add_u32 s4, s85, s37
	s_addc_u32 s5, s86, 0
	global_load_dwordx2 v[56:57], v20, s[4:5]
	s_add_u32 s4, s8, s37
	s_addc_u32 s5, s84, 0
	global_load_dwordx2 v[18:19], v20, s[4:5]
	s_add_u32 s4, s97, s37
	s_addc_u32 s5, s99, 0
	global_load_dwordx2 v[66:67], v20, s[4:5]
	s_add_u32 s4, s94, s37
	s_addc_u32 s5, s95, 0
	global_load_dwordx2 v[62:63], v20, s[4:5]
	s_add_u32 s4, s0, s37
	s_addc_u32 s5, s1, 0
	global_load_dwordx2 v[68:69], v20, s[4:5]
	s_or_b32 s4, s33, s45
	s_lshl_b32 s37, s4, 11
	s_add_u32 s4, s87, s37
	v_mov_b32_e32 v24, v119
	s_addc_u32 s5, s35, 0
	global_load_dwordx2 v[20:21], v24, s[4:5]
	s_add_u32 s4, s85, s37
	s_addc_u32 s5, s86, 0
	global_load_dwordx2 v[64:65], v24, s[4:5]
	s_add_u32 s4, s8, s37
	s_addc_u32 s5, s84, 0
	global_load_dwordx2 v[22:23], v24, s[4:5]
	s_add_u32 s4, s97, s37
	s_addc_u32 s5, s99, 0
	global_load_dwordx2 v[76:77], v24, s[4:5]
	s_add_u32 s4, s94, s37
	s_addc_u32 s5, s95, 0
	global_load_dwordx2 v[70:71], v24, s[4:5]
	s_add_u32 s4, s0, s37
	s_addc_u32 s5, s1, 0
	global_load_dwordx2 v[74:75], v24, s[4:5]
	s_or_b32 s4, s33, s36
	s_lshl_b32 s36, s4, 11
	s_add_u32 s4, s87, s36
	v_mov_b32_e32 v28, v119
	s_addc_u32 s5, s35, 0
	global_load_dwordx2 v[24:25], v28, s[4:5]
	s_add_u32 s4, s85, s36
	s_addc_u32 s5, s86, 0
	global_load_dwordx2 v[72:73], v28, s[4:5]
	s_add_u32 s4, s8, s36
	s_addc_u32 s5, s84, 0
	global_load_dwordx2 v[26:27], v28, s[4:5]
	s_add_u32 s4, s97, s36
	s_addc_u32 s5, s99, 0
	global_load_dwordx2 v[84:85], v28, s[4:5]
	s_add_u32 s4, s94, s36
	s_addc_u32 s5, s95, 0
	global_load_dwordx2 v[78:79], v28, s[4:5]
	s_add_u32 s4, s0, s36
	s_addc_u32 s5, s1, 0
	global_load_dwordx2 v[86:87], v28, s[4:5]
	s_or_b32 s4, s33, s23
	s_lshl_b32 s23, s4, 11
	s_add_u32 s4, s87, s23
	v_mov_b32_e32 v32, v119
	s_addc_u32 s5, s35, 0
	global_load_dwordx2 v[28:29], v32, s[4:5]
	s_add_u32 s4, s85, s23
	s_addc_u32 s5, s86, 0
	global_load_dwordx2 v[82:83], v32, s[4:5]
	s_add_u32 s4, s8, s23
	s_addc_u32 s5, s84, 0
	global_load_dwordx2 v[30:31], v32, s[4:5]
	s_add_u32 s4, s97, s23
	s_addc_u32 s5, s99, 0
	global_load_dwordx2 v[98:99], v32, s[4:5]
	s_add_u32 s4, s94, s23
	s_addc_u32 s5, s95, 0
	global_load_dwordx2 v[88:89], v32, s[4:5]
	s_add_u32 s4, s0, s23
	s_addc_u32 s5, s1, 0
	global_load_dwordx2 v[96:97], v32, s[4:5]
	s_or_b32 s4, s33, s10
	s_lshl_b32 s10, s4, 11
	s_add_u32 s4, s87, s10
	v_mov_b32_e32 v92, v119
	s_addc_u32 s5, s35, 0
	global_load_dwordx2 v[32:33], v92, s[4:5]
	s_add_u32 s4, s85, s10
	s_addc_u32 s5, s86, 0
	global_load_dwordx2 v[90:91], v92, s[4:5]
	s_add_u32 s4, s8, s10
	s_addc_u32 s5, s84, 0
	global_load_dwordx2 v[34:35], v92, s[4:5]
	s_add_u32 s4, s97, s10
	s_addc_u32 s5, s99, 0
	global_load_dwordx2 v[102:103], v92, s[4:5]
	s_add_u32 s4, s94, s10
	s_addc_u32 s5, s95, 0
	global_load_dwordx2 v[100:101], v92, s[4:5]
	s_add_u32 s4, s0, s10
	s_addc_u32 s5, s1, 0
	global_load_dwordx2 v[104:105], v92, s[4:5]
	s_mov_b32 s36, 0
	s_waitcnt vmcnt(48)
	v_sub_f32_e32 v93, 1.0, v3
	v_sub_f32_e32 v92, 1.0, v2
	v_sub_f32_e32 v95, 1.0, v1
	v_sub_f32_e32 v94, 1.0, v0
	s_lshl_b32 s10, s22, 14
	s_mov_b32 s37, 0
	s_branch .LBB0_183
.LBB0_182:
	s_min_u32 s4, s37, 0x1030
	s_lshl_b32 s4, s4, 2
	s_cmp_gt_u32 s37, 48
	s_cselect_b32 s5, 0xffffff3c, 60
	s_cselect_b32 s23, s10, s33
	s_cselect_b32 s37, s46, 0xfc
	s_add_i32 s44, s4, s5
	s_sub_i32 s37, s37, s44
	s_waitcnt vmcnt(46)
	v_cvt_f32_f16_sdwa v123, v90 dst_sel:DWORD dst_unused:UNUSED_PAD src0_sel:WORD_1
	v_cvt_f32_f16_sdwa v125, v91 dst_sel:DWORD dst_unused:UNUSED_PAD src0_sel:WORD_1
	v_cvt_f32_f16_e32 v122, v90
	v_cvt_f32_f16_e32 v124, v91
	s_and_b64 s[4:5], s[42:43], exec
	s_waitcnt vmcnt(44)
	v_cvt_f32_f16_sdwa v127, v102 dst_sel:DWORD dst_unused:UNUSED_PAD src0_sel:WORD_1
	v_cvt_f32_f16_sdwa v133, v103 dst_sel:DWORD dst_unused:UNUSED_PAD src0_sel:WORD_1
	v_cvt_f32_f16_e32 v126, v102
	v_cvt_f32_f16_e32 v132, v103
	s_cselect_b32 s4, s44, s37
	s_add_i32 s4, s4, s23
	s_ashr_i32 s5, s4, 31
	v_pk_fma_f32 v[102:103], v[2:3], v[124:125], v[92:93]
	v_pk_fma_f32 v[122:123], v[0:1], v[122:123], v[94:95]
	s_lshl_b64 s[4:5], s[4:5], 11
	v_pk_mul_f32 v[102:103], v[102:103], v[132:133]
	v_pk_mul_f32 v[126:127], v[122:123], v[126:127]
	s_add_u32 s44, s87, s4
	v_pk_mul_f16 v123, v91, v35
	v_pk_mul_f16 v122, v90, v34
	v_cvt_pk_f16_f32 v125, v102, v103
	v_cvt_pk_f16_f32 v124, v126, v127
	ds_write_b128 v120, v[32:35] offset:21504
	ds_write_b128 v120, v[122:125] offset:22528
	s_waitcnt vmcnt(42)
	v_add_u32_e32 v185, v121, v186
	ds_write_b64 v185, v[100:101] offset:23552
	v_add_u32_e32 v181, v121, v182
	ds_write_b16 v181, v104 offset:24064
	ds_write_b16_d16_hi v181, v104 offset:24072
	ds_write_b16 v181, v105 offset:24080
	ds_write_b16_d16_hi v181, v105 offset:24088
	v_mov_b32_e32 v32, s22
	v_mov_b32_e32 v104, v119
	s_addc_u32 s45, s35, s5
	s_waitcnt lgkmcnt(0)
	ds_write_b32 v161, v32 offset:49152
	global_load_dwordx2 v[32:33], v104, s[44:45]
	s_add_u32 s44, s85, s4
	s_addc_u32 s45, s86, s5
	global_load_dwordx2 v[90:91], v104, s[44:45]
	s_add_u32 s44, s8, s4
	s_addc_u32 s45, s84, s5
	global_load_dwordx2 v[34:35], v104, s[44:45]
	s_add_u32 s44, s97, s4
	s_addc_u32 s45, s99, s5
	global_load_dwordx2 v[102:103], v104, s[44:45]
	s_add_u32 s44, s94, s4
	s_addc_u32 s45, s95, s5
	s_add_u32 s4, s0, s4
	s_addc_u32 s5, s1, s5
	global_load_dwordx2 v[100:101], v104, s[44:45]
	s_nop 0
	global_load_dwordx2 v[104:105], v104, s[4:5]
	s_andn2_b64 vcc, exec, s[90:91]
	s_mov_b32 s37, s22
	s_cbranch_vccz .LBB0_242

.LBB0_185:
	s_waitcnt vmcnt(46)
	v_cvt_f32_f16_sdwa v121, v36 dst_sel:DWORD dst_unused:UNUSED_PAD src0_sel:WORD_1
	v_cvt_f32_f16_e32 v120, v36
	s_waitcnt vmcnt(44)
	v_cvt_f32_f16_sdwa v125, v44 dst_sel:DWORD dst_unused:UNUSED_PAD src0_sel:WORD_1
	v_cvt_f32_f16_e32 v124, v44
	s_and_b32 s4, s37, 8
	v_cvt_f32_f16_sdwa v123, v37 dst_sel:DWORD dst_unused:UNUSED_PAD src0_sel:WORD_1
	v_cvt_f32_f16_e32 v122, v37
	s_mulk_i32 s4, 0xc00
	s_add_i32 s4, s4, 16
	v_pk_fma_f32 v[120:121], v[0:1], v[120:121], v[94:95]
	s_or_b32 s23, s37, 1
	s_add_i32 s22, s37, 8
	v_pk_mul_f32 v[120:121], v[120:121], v[124:125]
	s_cmpk_gt_u32 s37, 0x1037
	v_cvt_f32_f16_sdwa v127, v45 dst_sel:DWORD dst_unused:UNUSED_PAD src0_sel:WORD_1
	v_cvt_f32_f16_e32 v126, v45
	v_pk_fma_f32 v[44:45], v[2:3], v[122:123], v[92:93]
	v_pk_mul_f16 v122, v36, v6
	v_cvt_pk_f16_f32 v124, v120, v121
	v_add_u32_e32 v36, s4, v113
	v_add_u32_e32 v121, s4, v111
	s_cselect_b64 s[90:91], -1, 0
	s_lshl_b32 s4, s22, 2
	s_cmpk_lt_u32 s37, 0x1038
	s_cselect_b32 s4, s4, 0x40fc
	s_add_i32 s5, s4, 0xffffff00
	s_min_u32 s44, s5, s4
	s_cmpk_gt_u32 s4, 0xff
	s_movk_i32 s4, 0x3fff
	s_cselect_b32 s4, s4, 0xff
	s_cselect_b32 s45, s10, s33
	s_sub_i32 s4, s4, s44
	s_add_i32 vcc_lo, s4, -3
	s_and_b64 s[4:5], s[42:43], exec
	s_cselect_b32 s4, s44, vcc_lo
	s_add_i32 s4, s4, s45
	s_ashr_i32 s5, s4, 31
	s_lshl_b64 s[4:5], s[4:5], 11
	v_pk_mul_f32 v[44:45], v[44:45], v[126:127]
	v_add_u32_e32 v120, v36, v128
	s_add_u32 s44, s87, s4
	v_pk_mul_f16 v123, v37, v7
	v_cvt_pk_f16_f32 v125, v44, v45
	ds_write_b128 v120, v[4:7]
	ds_write_b128 v120, v[122:125] offset:1024
	s_waitcnt vmcnt(42)
	v_add_u32_e32 v185, v121, v186
	ds_write_b64 v185, v[38:39] offset:2048
	v_add_u32_e32 v181, v121, v182
	ds_write_b16 v181, v42 offset:2560
	ds_write_b16_d16_hi v181, v42 offset:2568
	ds_write_b16 v181, v43 offset:2576
	ds_write_b16_d16_hi v181, v43 offset:2584
	v_mov_b32_e32 v4, s23
	v_mov_b32_e32 v42, v119
	s_addc_u32 s45, s35, s5
	s_waitcnt lgkmcnt(0)
	ds_write_b32 v161, v4 offset:49152
	global_load_dwordx2 v[4:5], v42, s[44:45]
	s_add_u32 s44, s85, s4
	s_addc_u32 s45, s86, s5
	global_load_dwordx2 v[36:37], v42, s[44:45]
	s_add_u32 s44, s8, s4
	s_addc_u32 s45, s84, s5
	global_load_dwordx2 v[6:7], v42, s[44:45]
	s_add_u32 s44, s97, s4
	s_addc_u32 s45, s99, s5
	global_load_dwordx2 v[44:45], v42, s[44:45]
	s_add_u32 s44, s94, s4
	s_addc_u32 s45, s95, s5
	s_add_u32 s4, s0, s4
	s_addc_u32 s5, s1, s5
	global_load_dwordx2 v[38:39], v42, s[44:45]
	s_nop 0
	global_load_dwordx2 v[42:43], v42, s[4:5]
	v_cndmask_b32_e64 v122, 0, 1, s[92:93]
	v_cmp_ne_u32_e64 s[44:45], 1, v122
	s_andn2_b64 vcc, exec, s[92:93]
	s_cbranch_vccnz .LBB0_187
	s_add_i32 s4, s37, -14
	s_cmp_ge_i32 s36, s4
	s_cbranch_scc0 .LBB0_203
.LBB0_187:
	s_waitcnt vmcnt(46)
	v_cvt_f32_f16_sdwa v123, v40 dst_sel:DWORD dst_unused:UNUSED_PAD src0_sel:WORD_1
	v_cvt_f32_f16_sdwa v125, v41 dst_sel:DWORD dst_unused:UNUSED_PAD src0_sel:WORD_1
	v_cvt_f32_f16_e32 v122, v40
	v_cvt_f32_f16_e32 v124, v41
	s_waitcnt vmcnt(44)
	v_cvt_f32_f16_sdwa v127, v52 dst_sel:DWORD dst_unused:UNUSED_PAD src0_sel:WORD_1
	v_cvt_f32_f16_sdwa v133, v53 dst_sel:DWORD dst_unused:UNUSED_PAD src0_sel:WORD_1
	v_cvt_f32_f16_e32 v126, v52
	v_cvt_f32_f16_e32 v132, v53
	s_and_b32 s4, s23, 9
	s_mulk_i32 s4, 0xc00
	s_add_i32 s4, s4, 16
	v_pk_fma_f32 v[52:53], v[2:3], v[124:125], v[92:93]
	v_pk_fma_f32 v[122:123], v[0:1], v[122:123], v[94:95]
	v_pk_mul_f32 v[52:53], v[52:53], v[132:133]
	v_pk_mul_f32 v[126:127], v[122:123], v[126:127]
	v_pk_mul_f16 v122, v40, v10
	v_add3_u32 v40, s4, v113, v128
	v_pk_mul_f16 v123, v41, v11
	v_cvt_pk_f16_f32 v125, v52, v53
	v_cvt_pk_f16_f32 v124, v126, v127
	ds_write_b128 v40, v[8:11]
	ds_write_b128 v40, v[122:125] offset:1024
	v_add_u32_e32 v8, s4, v111
	s_or_b32 s4, s37, 2
	s_waitcnt vmcnt(42)
	v_add_u32_e32 v185, v8, v186
	ds_write_b64 v185, v[46:47] offset:2048
	v_add_u32_e32 v181, v8, v182
	ds_write_b16 v181, v50 offset:2560
	ds_write_b16_d16_hi v181, v50 offset:2568
	ds_write_b16 v181, v51 offset:2576
	ds_write_b16_d16_hi v181, v51 offset:2584
	v_mov_b32_e32 v8, s4
	s_min_u32 s4, s37, 0x1036
	s_lshl_b32 s4, s4, 2
	s_cmp_gt_u32 s37, 54
	s_cselect_b32 s5, 0xffffff24, 36
	s_cselect_b32 s23, s10, s33
	s_cselect_b32 s92, s46, 0xfc
	s_add_i32 s93, s4, s5
	s_sub_i32 s92, s92, s93
	s_and_b64 s[4:5], s[42:43], exec
	s_cselect_b32 s4, s93, s92
	s_add_i32 s4, s4, s23
	s_ashr_i32 s5, s4, 31
	s_lshl_b64 s[4:5], s[4:5], 11
	s_add_u32 s92, s87, s4
	v_mov_b32_e32 v50, v119
	s_addc_u32 s93, s35, s5
	s_waitcnt lgkmcnt(0)
	ds_write_b32 v161, v8 offset:49152
	global_load_dwordx2 v[8:9], v50, s[92:93]
	s_add_u32 s92, s85, s4
	s_addc_u32 s93, s86, s5
	global_load_dwordx2 v[40:41], v50, s[92:93]
	s_add_u32 s92, s8, s4
	s_addc_u32 s93, s84, s5
	global_load_dwordx2 v[10:11], v50, s[92:93]
	s_add_u32 s92, s97, s4
	s_addc_u32 s93, s99, s5
	global_load_dwordx2 v[52:53], v50, s[92:93]
	s_add_u32 s92, s94, s4
	s_addc_u32 s93, s95, s5
	s_add_u32 s4, s0, s4
	s_addc_u32 s5, s1, s5
	global_load_dwordx2 v[46:47], v50, s[92:93]
	s_nop 0
	global_load_dwordx2 v[50:51], v50, s[4:5]
	s_and_b64 vcc, exec, s[44:45]
	s_cbranch_vccnz .LBB0_189
	s_add_i32 s4, s37, -13
	s_cmp_ge_i32 s36, s4
	s_cbranch_scc0 .LBB0_206
.LBB0_189:
	s_waitcnt vmcnt(46)
	v_cvt_f32_f16_sdwa v123, v48 dst_sel:DWORD dst_unused:UNUSED_PAD src0_sel:WORD_1
	v_cvt_f32_f16_sdwa v125, v49 dst_sel:DWORD dst_unused:UNUSED_PAD src0_sel:WORD_1
	v_cvt_f32_f16_e32 v122, v48
	v_cvt_f32_f16_e32 v124, v49
	s_waitcnt vmcnt(44)
	v_cvt_f32_f16_sdwa v127, v60 dst_sel:DWORD dst_unused:UNUSED_PAD src0_sel:WORD_1
	v_cvt_f32_f16_sdwa v133, v61 dst_sel:DWORD dst_unused:UNUSED_PAD src0_sel:WORD_1
	v_cvt_f32_f16_e32 v126, v60
	v_cvt_f32_f16_e32 v132, v61
	v_pk_fma_f32 v[60:61], v[2:3], v[124:125], v[92:93]
	v_pk_fma_f32 v[122:123], v[0:1], v[122:123], v[94:95]
	s_or_b32 s4, s37, 3
	v_pk_mul_f32 v[60:61], v[60:61], v[132:133]
	v_pk_mul_f32 v[126:127], v[122:123], v[126:127]
	v_pk_mul_f16 v123, v49, v15
	v_pk_mul_f16 v122, v48, v14
	v_cvt_pk_f16_f32 v125, v60, v61
	v_cvt_pk_f16_f32 v124, v126, v127
	ds_write_b128 v120, v[12:15] offset:6144
	ds_write_b128 v120, v[122:125] offset:7168
	s_waitcnt vmcnt(42)
	v_add_u32_e32 v185, v121, v186
	ds_write_b64 v185, v[54:55] offset:8192
	v_add_u32_e32 v181, v121, v182
	ds_write_b16 v181, v58 offset:8704
	ds_write_b16_d16_hi v181, v58 offset:8712
	ds_write_b16 v181, v59 offset:8720
	ds_write_b16_d16_hi v181, v59 offset:8728
	v_mov_b32_e32 v12, s4
	s_min_u32 s4, s37, 0x1035
	s_lshl_b32 s4, s4, 2
	s_cmp_gt_u32 s37, 53
	s_cselect_b32 s5, 0xffffff28, 40
	s_cselect_b32 s23, s10, s33
	s_cselect_b32 s92, s46, 0xfc
	s_add_i32 s93, s4, s5
	s_sub_i32 s92, s92, s93
	s_and_b64 s[4:5], s[42:43], exec
	s_cselect_b32 s4, s93, s92
	s_add_i32 s4, s4, s23
	s_ashr_i32 s5, s4, 31
	s_lshl_b64 s[4:5], s[4:5], 11
	s_add_u32 s92, s87, s4
	v_mov_b32_e32 v58, v119
	s_addc_u32 s93, s35, s5
	s_waitcnt lgkmcnt(0)
	ds_write_b32 v161, v12 offset:49152
	global_load_dwordx2 v[12:13], v58, s[92:93]
	s_add_u32 s92, s85, s4
	s_addc_u32 s93, s86, s5
	global_load_dwordx2 v[48:49], v58, s[92:93]
	s_add_u32 s92, s8, s4
	s_addc_u32 s93, s84, s5
	global_load_dwordx2 v[14:15], v58, s[92:93]
	s_add_u32 s92, s97, s4
	s_addc_u32 s93, s99, s5
	global_load_dwordx2 v[60:61], v58, s[92:93]
	s_add_u32 s92, s94, s4
	s_addc_u32 s93, s95, s5
	s_add_u32 s4, s0, s4
	s_addc_u32 s5, s1, s5
	global_load_dwordx2 v[54:55], v58, s[92:93]
	s_nop 0
	global_load_dwordx2 v[58:59], v58, s[4:5]
	s_and_b64 vcc, exec, s[44:45]
	s_cbranch_vccnz .LBB0_191
	s_add_i32 s4, s37, -12
	s_cmp_ge_i32 s36, s4
	s_cbranch_scc0 .LBB0_209
.LBB0_191:
	s_waitcnt vmcnt(46)
	v_cvt_f32_f16_sdwa v123, v56 dst_sel:DWORD dst_unused:UNUSED_PAD src0_sel:WORD_1
	v_cvt_f32_f16_sdwa v125, v57 dst_sel:DWORD dst_unused:UNUSED_PAD src0_sel:WORD_1
	v_cvt_f32_f16_e32 v122, v56
	v_cvt_f32_f16_e32 v124, v57
	s_waitcnt vmcnt(44)
	v_cvt_f32_f16_sdwa v127, v66 dst_sel:DWORD dst_unused:UNUSED_PAD src0_sel:WORD_1
	v_cvt_f32_f16_sdwa v133, v67 dst_sel:DWORD dst_unused:UNUSED_PAD src0_sel:WORD_1
	v_cvt_f32_f16_e32 v126, v66
	v_cvt_f32_f16_e32 v132, v67
	v_pk_fma_f32 v[66:67], v[2:3], v[124:125], v[92:93]
	v_pk_fma_f32 v[122:123], v[0:1], v[122:123], v[94:95]
	s_or_b32 s4, s37, 4
	v_pk_mul_f32 v[66:67], v[66:67], v[132:133]
	v_pk_mul_f32 v[126:127], v[122:123], v[126:127]
	v_pk_mul_f16 v123, v57, v19
	v_pk_mul_f16 v122, v56, v18
	v_cvt_pk_f16_f32 v125, v66, v67
	v_cvt_pk_f16_f32 v124, v126, v127
	ds_write_b128 v120, v[16:19] offset:9216
	ds_write_b128 v120, v[122:125] offset:10240
	s_waitcnt vmcnt(42)
	v_add_u32_e32 v185, v121, v186
	ds_write_b64 v185, v[62:63] offset:11264
	v_add_u32_e32 v181, v121, v182
	ds_write_b16 v181, v68 offset:11776
	ds_write_b16_d16_hi v181, v68 offset:11784
	ds_write_b16 v181, v69 offset:11792
	ds_write_b16_d16_hi v181, v69 offset:11800
	v_mov_b32_e32 v16, s4
	s_min_u32 s4, s37, 0x1034
	s_lshl_b32 s4, s4, 2
	s_cmp_gt_u32 s37, 52
	s_cselect_b32 s5, 0xffffff2c, 44
	s_cselect_b32 s23, s10, s33
	s_cselect_b32 s92, s46, 0xfc
	s_add_i32 s93, s4, s5
	s_sub_i32 s92, s92, s93
	s_and_b64 s[4:5], s[42:43], exec
	s_cselect_b32 s4, s93, s92
	s_add_i32 s4, s4, s23
	s_ashr_i32 s5, s4, 31
	s_lshl_b64 s[4:5], s[4:5], 11
	s_add_u32 s92, s87, s4
	v_mov_b32_e32 v68, v119
	s_addc_u32 s93, s35, s5
	s_waitcnt lgkmcnt(0)
	ds_write_b32 v161, v16 offset:49152
	global_load_dwordx2 v[16:17], v68, s[92:93]
	s_add_u32 s92, s85, s4
	s_addc_u32 s93, s86, s5
	global_load_dwordx2 v[56:57], v68, s[92:93]
	s_add_u32 s92, s8, s4
	s_addc_u32 s93, s84, s5
	global_load_dwordx2 v[18:19], v68, s[92:93]
	s_add_u32 s92, s97, s4
	s_addc_u32 s93, s99, s5
	global_load_dwordx2 v[66:67], v68, s[92:93]
	s_add_u32 s92, s94, s4
	s_addc_u32 s93, s95, s5
	s_add_u32 s4, s0, s4
	s_addc_u32 s5, s1, s5
	global_load_dwordx2 v[62:63], v68, s[92:93]
	s_nop 0
	global_load_dwordx2 v[68:69], v68, s[4:5]
	s_and_b64 vcc, exec, s[44:45]
	s_cbranch_vccnz .LBB0_193
	s_add_i32 s4, s37, -11
	s_cmp_ge_i32 s36, s4
	s_cbranch_scc0 .LBB0_212
.LBB0_193:
	s_waitcnt vmcnt(46)
	v_cvt_f32_f16_sdwa v123, v64 dst_sel:DWORD dst_unused:UNUSED_PAD src0_sel:WORD_1
	v_cvt_f32_f16_sdwa v125, v65 dst_sel:DWORD dst_unused:UNUSED_PAD src0_sel:WORD_1
	v_cvt_f32_f16_e32 v122, v64
	v_cvt_f32_f16_e32 v124, v65
	s_waitcnt vmcnt(44)
	v_cvt_f32_f16_sdwa v127, v76 dst_sel:DWORD dst_unused:UNUSED_PAD src0_sel:WORD_1
	v_cvt_f32_f16_sdwa v133, v77 dst_sel:DWORD dst_unused:UNUSED_PAD src0_sel:WORD_1
	v_cvt_f32_f16_e32 v126, v76
	v_cvt_f32_f16_e32 v132, v77
	v_pk_fma_f32 v[76:77], v[2:3], v[124:125], v[92:93]
	v_pk_fma_f32 v[122:123], v[0:1], v[122:123], v[94:95]
	s_or_b32 s4, s37, 5
	v_pk_mul_f32 v[76:77], v[76:77], v[132:133]
	v_pk_mul_f32 v[126:127], v[122:123], v[126:127]
	v_pk_mul_f16 v123, v65, v23
	v_pk_mul_f16 v122, v64, v22
	v_cvt_pk_f16_f32 v125, v76, v77
	v_cvt_pk_f16_f32 v124, v126, v127
	ds_write_b128 v120, v[20:23] offset:12288
	ds_write_b128 v120, v[122:125] offset:13312
	s_waitcnt vmcnt(42)
	v_add_u32_e32 v185, v121, v186
	ds_write_b64 v185, v[70:71] offset:14336
	v_add_u32_e32 v181, v121, v182
	ds_write_b16 v181, v74 offset:14848
	ds_write_b16_d16_hi v181, v74 offset:14856
	ds_write_b16 v181, v75 offset:14864
	ds_write_b16_d16_hi v181, v75 offset:14872
	v_mov_b32_e32 v20, s4
	s_min_u32 s4, s37, 0x1033
	s_lshl_b32 s4, s4, 2
	s_cmp_gt_u32 s37, 51
	s_cselect_b32 s5, 0xffffff30, 48
	s_cselect_b32 s23, s10, s33
	s_cselect_b32 s92, s46, 0xfc
	s_add_i32 s93, s4, s5
	s_sub_i32 s92, s92, s93
	s_and_b64 s[4:5], s[42:43], exec
	s_cselect_b32 s4, s93, s92
	s_add_i32 s4, s4, s23
	s_ashr_i32 s5, s4, 31
	s_lshl_b64 s[4:5], s[4:5], 11
	s_add_u32 s92, s87, s4
	v_mov_b32_e32 v74, v119
	s_addc_u32 s93, s35, s5
	s_waitcnt lgkmcnt(0)
	ds_write_b32 v161, v20 offset:49152
	global_load_dwordx2 v[20:21], v74, s[92:93]
	s_add_u32 s92, s85, s4
	s_addc_u32 s93, s86, s5
	global_load_dwordx2 v[64:65], v74, s[92:93]
	s_add_u32 s92, s8, s4
	s_addc_u32 s93, s84, s5
	global_load_dwordx2 v[22:23], v74, s[92:93]
	s_add_u32 s92, s97, s4
	s_addc_u32 s93, s99, s5
	global_load_dwordx2 v[76:77], v74, s[92:93]
	s_add_u32 s92, s94, s4
	s_addc_u32 s93, s95, s5
	s_add_u32 s4, s0, s4
	s_addc_u32 s5, s1, s5
	global_load_dwordx2 v[70:71], v74, s[92:93]
	s_nop 0
	global_load_dwordx2 v[74:75], v74, s[4:5]
	s_and_b64 vcc, exec, s[44:45]
	s_cbranch_vccnz .LBB0_195
	s_add_i32 s4, s37, -10
	s_cmp_ge_i32 s36, s4
	s_cbranch_scc0 .LBB0_215
.LBB0_195:
	s_waitcnt vmcnt(46)
	v_cvt_f32_f16_sdwa v123, v72 dst_sel:DWORD dst_unused:UNUSED_PAD src0_sel:WORD_1
	v_cvt_f32_f16_sdwa v125, v73 dst_sel:DWORD dst_unused:UNUSED_PAD src0_sel:WORD_1
	v_cvt_f32_f16_e32 v122, v72
	v_cvt_f32_f16_e32 v124, v73
	s_waitcnt vmcnt(44)
	v_cvt_f32_f16_sdwa v127, v84 dst_sel:DWORD dst_unused:UNUSED_PAD src0_sel:WORD_1
	v_cvt_f32_f16_sdwa v133, v85 dst_sel:DWORD dst_unused:UNUSED_PAD src0_sel:WORD_1
	v_cvt_f32_f16_e32 v126, v84
	v_cvt_f32_f16_e32 v132, v85
	v_pk_fma_f32 v[84:85], v[2:3], v[124:125], v[92:93]
	v_pk_fma_f32 v[122:123], v[0:1], v[122:123], v[94:95]
	s_or_b32 s4, s37, 6
	v_pk_mul_f32 v[84:85], v[84:85], v[132:133]
	v_pk_mul_f32 v[126:127], v[122:123], v[126:127]
	v_pk_mul_f16 v123, v73, v27
	v_pk_mul_f16 v122, v72, v26
	v_cvt_pk_f16_f32 v125, v84, v85
	v_cvt_pk_f16_f32 v124, v126, v127
	ds_write_b128 v120, v[24:27] offset:15360
	ds_write_b128 v120, v[122:125] offset:16384
	s_waitcnt vmcnt(42)
	v_add_u32_e32 v185, v121, v186
	ds_write_b64 v185, v[78:79] offset:17408
	v_add_u32_e32 v181, v121, v182
	ds_write_b16 v181, v86 offset:17920
	ds_write_b16_d16_hi v181, v86 offset:17928
	ds_write_b16 v181, v87 offset:17936
	ds_write_b16_d16_hi v181, v87 offset:17944
	v_mov_b32_e32 v24, s4
	s_min_u32 s4, s37, 0x1032
	s_lshl_b32 s4, s4, 2
	s_cmp_gt_u32 s37, 50
	s_cselect_b32 s5, 0xffffff34, 52
	s_cselect_b32 s23, s10, s33
	s_cselect_b32 s92, s46, 0xfc
	s_add_i32 s93, s4, s5
	s_sub_i32 s92, s92, s93
	s_and_b64 s[4:5], s[42:43], exec
	s_cselect_b32 s4, s93, s92
	s_add_i32 s4, s4, s23
	s_ashr_i32 s5, s4, 31
	s_lshl_b64 s[4:5], s[4:5], 11
	s_add_u32 s92, s87, s4
	v_mov_b32_e32 v86, v119
	s_addc_u32 s93, s35, s5
	s_waitcnt lgkmcnt(0)
	ds_write_b32 v161, v24 offset:49152
	global_load_dwordx2 v[24:25], v86, s[92:93]
	s_add_u32 s92, s85, s4
	s_addc_u32 s93, s86, s5
	global_load_dwordx2 v[72:73], v86, s[92:93]
	s_add_u32 s92, s8, s4
	s_addc_u32 s93, s84, s5
	global_load_dwordx2 v[26:27], v86, s[92:93]
	s_add_u32 s92, s97, s4
	s_addc_u32 s93, s99, s5
	global_load_dwordx2 v[84:85], v86, s[92:93]
	s_add_u32 s92, s94, s4
	s_addc_u32 s93, s95, s5
	s_add_u32 s4, s0, s4
	s_addc_u32 s5, s1, s5
	global_load_dwordx2 v[78:79], v86, s[92:93]
	s_nop 0
	global_load_dwordx2 v[86:87], v86, s[4:5]
	s_and_b64 vcc, exec, s[44:45]
	s_cbranch_vccnz .LBB0_197
	s_add_i32 s4, s37, -9
	s_cmp_ge_i32 s36, s4
	s_cbranch_scc0 .LBB0_218
.LBB0_197:
	s_waitcnt vmcnt(46)
	v_cvt_f32_f16_sdwa v123, v82 dst_sel:DWORD dst_unused:UNUSED_PAD src0_sel:WORD_1
	v_cvt_f32_f16_sdwa v125, v83 dst_sel:DWORD dst_unused:UNUSED_PAD src0_sel:WORD_1
	v_cvt_f32_f16_e32 v122, v82
	v_cvt_f32_f16_e32 v124, v83
	s_waitcnt vmcnt(44)
	v_cvt_f32_f16_sdwa v127, v98 dst_sel:DWORD dst_unused:UNUSED_PAD src0_sel:WORD_1
	v_cvt_f32_f16_sdwa v133, v99 dst_sel:DWORD dst_unused:UNUSED_PAD src0_sel:WORD_1
	v_cvt_f32_f16_e32 v126, v98
	v_cvt_f32_f16_e32 v132, v99
	v_pk_fma_f32 v[98:99], v[2:3], v[124:125], v[92:93]
	v_pk_fma_f32 v[122:123], v[0:1], v[122:123], v[94:95]
	s_or_b32 s4, s37, 7
	v_pk_mul_f32 v[98:99], v[98:99], v[132:133]
	v_pk_mul_f32 v[126:127], v[122:123], v[126:127]
	v_pk_mul_f16 v123, v83, v31
	v_pk_mul_f16 v122, v82, v30
	v_cvt_pk_f16_f32 v125, v98, v99
	v_cvt_pk_f16_f32 v124, v126, v127
	ds_write_b128 v120, v[28:31] offset:18432
	ds_write_b128 v120, v[122:125] offset:19456
	s_waitcnt vmcnt(42)
	v_add_u32_e32 v185, v121, v186
	ds_write_b64 v185, v[88:89] offset:20480
	v_add_u32_e32 v181, v121, v182
	ds_write_b16 v181, v96 offset:20992
	ds_write_b16_d16_hi v181, v96 offset:21000
	ds_write_b16 v181, v97 offset:21008
	ds_write_b16_d16_hi v181, v97 offset:21016
	v_mov_b32_e32 v28, s4
	s_min_u32 s4, s37, 0x1031
	s_lshl_b32 s4, s4, 2
	s_cmp_gt_u32 s37, 49
	s_cselect_b32 s5, 0xffffff38, 56
	s_cselect_b32 s23, s10, s33
	s_cselect_b32 s92, s46, 0xfc
	s_add_i32 s93, s4, s5
	s_sub_i32 s92, s92, s93
	s_and_b64 s[4:5], s[42:43], exec
	s_cselect_b32 s4, s93, s92
	s_add_i32 s4, s4, s23
	s_ashr_i32 s5, s4, 31
	s_lshl_b64 s[4:5], s[4:5], 11
	s_add_u32 s92, s87, s4
	v_mov_b32_e32 v96, v119
	s_addc_u32 s93, s35, s5
	s_waitcnt lgkmcnt(0)
	ds_write_b32 v161, v28 offset:49152
	global_load_dwordx2 v[28:29], v96, s[92:93]
	s_add_u32 s92, s85, s4
	s_addc_u32 s93, s86, s5
	global_load_dwordx2 v[82:83], v96, s[92:93]
	s_add_u32 s92, s8, s4
	s_addc_u32 s93, s84, s5
	global_load_dwordx2 v[30:31], v96, s[92:93]
	s_add_u32 s92, s97, s4
	s_addc_u32 s93, s99, s5
	global_load_dwordx2 v[98:99], v96, s[92:93]
	s_add_u32 s92, s94, s4
	s_addc_u32 s93, s95, s5
	s_add_u32 s4, s0, s4
	s_addc_u32 s5, s1, s5
	global_load_dwordx2 v[88:89], v96, s[92:93]
	s_nop 0
	global_load_dwordx2 v[96:97], v96, s[4:5]
	s_and_b64 vcc, exec, s[44:45]
	s_cbranch_vccnz .LBB0_182
	s_add_i32 s4, s37, -8
	s_cmp_ge_i32 s36, s4
	s_cbranch_scc0 .LBB0_221
	s_branch .LBB0_182

; #define LAS3 __attribute__((address_space(3)))
; DEV void rwkv_consumer(const Params& p, const Ctx& cx, int l, int task, int lane, const char* ring, int widx) {
;   const int unit = task >> 4, d = unit & 1, h = (unit >> 1) & 15, b = unit >> 5;
;   const int j = lane >> 4, s = lane & 15;
;   const int myrow = (task & 15) * 4 + j;
;   char* pO = (char*)((h16*)(p.ws + OFF_REG2) + (size_t)d * ARR + h * 64);
;   const int sm = d ? 3 - (s & 3) : (s & 3);
;   const unsigned vov0 = (unsigned)(sm * 2048 + myrow * 2);
;   const unsigned rofs = (unsigned)(s * 8);
;   const unsigned vrofs = (unsigned)(2560 + myrow * 2);
;   LAS3 volatile int* pflag = (LAS3 volatile int*)(ring + RW_FLAGS);
;   LAS3 volatile int* cflag = (LAS3 volatile int*)(ring + RW_FLAGS + 64) + widx;
;   float S0 = 0.f, S1 = 0.f, S2 = 0.f, S3 = 0.f;
;   int pseen = 0;
;   struct GD { u2v w[4], kk[4], kka[4], kd[4], r[4]; unsigned v[4]; };
;   GD A, B;
.LBB0_229:
	s_ashr_i32 s4, s31, 4
	s_lshl_b32 s1, s34, 4
	s_and_b32 s4, s4, -4
	s_or_b32 s1, s1, s4
	s_or_b32 s4, s1, s50
	s_lshl_b32 s1, s4, 2
	v_and_or_b32 v0, s1, 60, v107
	s_waitcnt vmcnt(0)
	v_lshlrev_b32_e32 v82, 1, v0
	v_lshlrev_b32_e32 v184, 3, v0
	v_add_u32_e32 v0, 16, v116
	v_add_u32_e32 v36, 16, v117
	v_add_u32_e32 v20, 0x800, v0
	v_add_u32_e32 v41, 16, v184
	ds_read_b128 v[0:3], v36 offset:2048
	ds_read_b128 v[4:7], v36
	ds_read_b128 v[8:11], v36 offset:256
	ds_read_b128 v[12:15], v36 offset:1024
	ds_read_b128 v[16:19], v36 offset:1280
	ds_read_b128 v[20:23], v36 offset:2304
	ds_read_b128 v[24:27], v36 offset:512
	s_waitcnt vmcnt(9)
	ds_read_b128 v[28:31], v36 offset:768
	s_waitcnt vmcnt(3)
	ds_read_b128 v[32:35], v36 offset:1536
	ds_read_b128 v[36:39], v36 offset:1792
	ds_read_b64 v[88:89], v41 offset:2560
	s_bfe_u32 s5, s4, 0x10004
	s_mul_i32 s8, s5, 0x4100000
	s_add_u32 s8, s20, s8
	s_addc_u32 s10, s21, 0
	s_and_b32 s1, s1, 0x780
	s_add_u32 s1, s8, s1
	s_addc_u32 s8, s10, 0
	s_cmp_eq_u32 s5, 0
	s_cselect_b64 s[42:43], -1, 0
	s_ashr_i32 s4, s4, 9
	v_cndmask_b32_e64 v40, v115, v114, s[42:43]
	s_lshl_b32 s22, s4, 8
	s_mov_b32 s33, 0
	v_or_b32_e32 v83, v40, v82
	s_lshl_b32 s10, s4, 14
	s_add_i32 s22, s22, 0x8000
	v_mov_b32_e32 v84, 0
	v_mov_b32_e32 v85, 0
	v_mov_b32_e32 v86, 0
	v_mov_b32_e32 v87, 0
	s_waitcnt vmcnt(0)
	s_and_b64 s[4:5], s[42:43], exec
	s_cselect_b32 s4, 0, 0xfc
	s_add_i32 s4, s22, s4
	s_lshl_b32 s4, s4, 11
	s_add_u32 s36, s1, s4
	s_addc_u32 s37, s8, 0
	s_and_b64 s[4:5], s[42:43], exec
	s_cselect_b32 s4, 0, 0x3ffc
	s_add_i32 s4, s10, s4
	s_lshl_b32 s4, s4, 11
	s_add_u32 s88, s1, s4
	s_addc_u32 s89, s8, 0
	s_and_b64 s[4:5], s[42:43], exec
	s_mov_b32 s44, 0xffffe000
	s_and_b64 s[4:5], s[42:43], exec
	s_cselect_b32 s44, 0x2000, s44
	s_cselect_b32 s45, 0, -1
	v_mov_b32_e32 v172, s9
	v_add_u32_e32 v194, 16, v117
	v_add_u32_e32 v195, 16, v184
	v_mov_b32_e32 v193, 0
.Lc_init_poll:
	s_cmp_gt_i32 s0, 1
	s_cbranch_scc1 .Lc_init_ld
	ds_read_b32 v173, v161 offset:49152
	s_waitcnt lgkmcnt(0)
	v_readfirstlane_b32 s0, v173
	s_sleep 1
	s_branch .Lc_init_poll
.Lc_init_ld:
	ds_read_b128 v[56:59], v194 offset:5120
	ds_read_b128 v[72:75], v194 offset:3072
	ds_read_b128 v[64:67], v194 offset:3328
	ds_read_b128 v[76:79], v194 offset:4096
	ds_read_b128 v[68:71], v194 offset:4352
	ds_read_b128 v[40:43], v194 offset:5376
	ds_read_b128 v[52:55], v194 offset:3584
	ds_read_b128 v[44:47], v194 offset:3840
	ds_read_b128 v[60:63], v194 offset:4608
	ds_read_b128 v[48:51], v194 offset:4864
	ds_read_b64 v[92:93], v195 offset:5632
	s_mov_b32 s35, s0
	s_waitcnt lgkmcnt(0)
	v_fma_mix_f32 v98, v84, v6, 0 op_sel:[0,0,0] op_sel_hi:[0,1,0]
	v_fma_mix_f32 v98, v85, v6, v98 op_sel:[0,1,0] op_sel_hi:[0,1,0]
	v_fma_mix_f32 v98, v86, v7, v98 op_sel:[0,0,0] op_sel_hi:[0,1,0]
	v_fma_mix_f32 v98, v87, v7, v98 op_sel:[0,1,0] op_sel_hi:[0,1,0]
	v_fma_mix_f32 v100, v88, v14, 0 op_sel:[0,0,0] op_sel_hi:[1,1,0]
	v_fma_mix_f32 v101, v88, v14, 0 op_sel:[0,1,0] op_sel_hi:[1,1,0]
	v_add_f32_dpp v98, v98, v98 quad_perm:[1,0,3,2] row_mask:0xf bank_mask:0xf bound_ctrl:1
	v_fma_mix_f32 v102, v88, v15, 0 op_sel:[0,0,0] op_sel_hi:[1,1,0]
	v_fma_mix_f32 v103, v88, v15, 0 op_sel:[0,1,0] op_sel_hi:[1,1,0]
	v_add_f32_dpp v98, v98, v98 quad_perm:[2,3,0,1] row_mask:0xf bank_mask:0xf bound_ctrl:1
	s_branch .Lc_top
.Lc_top:
	v_fma_mix_f32 v84, v84, v4, v100 op_sel:[0,0,0] op_sel_hi:[0,1,0]
	v_fma_mix_f32 v85, v85, v4, v101 op_sel:[0,1,0] op_sel_hi:[0,1,0]
	v_add_f32_dpp v98, v98, v98 row_half_mirror row_mask:0xf bank_mask:0xf bound_ctrl:1
	v_fma_mix_f32 v86, v86, v5, v102 op_sel:[0,0,0] op_sel_hi:[0,1,0]
	v_fma_mix_f32 v87, v87, v5, v103 op_sel:[0,1,0] op_sel_hi:[0,1,0]
	v_add_f32_dpp v98, v98, v98 row_mirror row_mask:0xf bank_mask:0xf bound_ctrl:1
	v_fma_mix_f32 v84, -v98, v12, v84 op_sel:[0,0,0] op_sel_hi:[0,1,0]
	v_fma_mix_f32 v85, -v98, v12, v85 op_sel:[0,1,0] op_sel_hi:[0,1,0]
	v_fma_mix_f32 v86, -v98, v13, v86 op_sel:[0,0,0] op_sel_hi:[0,1,0]
	v_fma_mix_f32 v87, -v98, v13, v87 op_sel:[0,1,0] op_sel_hi:[0,1,0]
	v_fma_mix_f32 v99, v84, v10, 0 op_sel:[0,0,0] op_sel_hi:[0,1,0]
	v_fma_mix_f32 v96, v84, v0, 0 op_sel:[0,0,0] op_sel_hi:[0,1,0]
	v_fma_mix_f32 v99, v85, v10, v99 op_sel:[0,1,0] op_sel_hi:[0,1,0]
	v_fma_mix_f32 v96, v85, v0, v96 op_sel:[0,1,0] op_sel_hi:[0,1,0]
	v_fma_mix_f32 v99, v86, v11, v99 op_sel:[0,0,0] op_sel_hi:[0,1,0]
	v_fma_mix_f32 v96, v86, v1, v96 op_sel:[0,0,0] op_sel_hi:[0,1,0]
	v_fma_mix_f32 v99, v87, v11, v99 op_sel:[0,1,0] op_sel_hi:[0,1,0]
	v_fma_mix_f32 v96, v87, v1, v96 op_sel:[0,1,0] op_sel_hi:[0,1,0]
	v_fma_mix_f32 v101, v88, v18, 0 op_sel:[1,0,0] op_sel_hi:[1,1,0]
	v_fma_mix_f32 v102, v88, v18, 0 op_sel:[1,1,0] op_sel_hi:[1,1,0]
	v_add_f32_dpp v99, v99, v99 quad_perm:[1,0,3,2] row_mask:0xf bank_mask:0xf bound_ctrl:1
	v_fma_mix_f32 v103, v88, v19, 0 op_sel:[1,0,0] op_sel_hi:[1,1,0]
	v_fma_mix_f32 v104, v88, v19, 0 op_sel:[1,1,0] op_sel_hi:[1,1,0]
	v_add_f32_dpp v99, v99, v99 quad_perm:[2,3,0,1] row_mask:0xf bank_mask:0xf bound_ctrl:1
	v_fma_mix_f32 v84, v84, v8, v101 op_sel:[0,0,0] op_sel_hi:[0,1,0]
	v_fma_mix_f32 v85, v85, v8, v102 op_sel:[0,1,0] op_sel_hi:[0,1,0]
	v_add_f32_dpp v99, v99, v99 row_half_mirror row_mask:0xf bank_mask:0xf bound_ctrl:1
	v_fma_mix_f32 v86, v86, v9, v103 op_sel:[0,0,0] op_sel_hi:[0,1,0]
	v_fma_mix_f32 v87, v87, v9, v104 op_sel:[0,1,0] op_sel_hi:[0,1,0]
	v_add_f32_dpp v99, v99, v99 row_mirror row_mask:0xf bank_mask:0xf bound_ctrl:1
	v_fma_mix_f32 v84, -v99, v16, v84 op_sel:[0,0,0] op_sel_hi:[0,1,0]
	v_fma_mix_f32 v85, -v99, v16, v85 op_sel:[0,1,0] op_sel_hi:[0,1,0]
	v_fma_mix_f32 v86, -v99, v17, v86 op_sel:[0,0,0] op_sel_hi:[0,1,0]
	v_fma_mix_f32 v87, -v99, v17, v87 op_sel:[0,1,0] op_sel_hi:[0,1,0]
	v_fma_mix_f32 v100, v84, v26, 0 op_sel:[0,0,0] op_sel_hi:[0,1,0]
	v_fma_mix_f32 v97, v84, v2, 0 op_sel:[0,0,0] op_sel_hi:[0,1,0]
	v_fma_mix_f32 v100, v85, v26, v100 op_sel:[0,1,0] op_sel_hi:[0,1,0]
	v_fma_mix_f32 v97, v85, v2, v97 op_sel:[0,1,0] op_sel_hi:[0,1,0]
	v_fma_mix_f32 v100, v86, v27, v100 op_sel:[0,0,0] op_sel_hi:[0,1,0]
	v_fma_mix_f32 v97, v86, v3, v97 op_sel:[0,0,0] op_sel_hi:[0,1,0]
	v_fma_mix_f32 v100, v87, v27, v100 op_sel:[0,1,0] op_sel_hi:[0,1,0]
	v_fma_mix_f32 v97, v87, v3, v97 op_sel:[0,1,0] op_sel_hi:[0,1,0]
	v_fma_mix_f32 v102, v89, v34, 0 op_sel:[0,0,0] op_sel_hi:[1,1,0]
	v_fma_mix_f32 v103, v89, v34, 0 op_sel:[0,1,0] op_sel_hi:[1,1,0]
	v_add_f32_dpp v100, v100, v100 quad_perm:[1,0,3,2] row_mask:0xf bank_mask:0xf bound_ctrl:1
	v_fma_mix_f32 v104, v89, v35, 0 op_sel:[0,0,0] op_sel_hi:[1,1,0]
	v_fma_mix_f32 v105, v89, v35, 0 op_sel:[0,1,0] op_sel_hi:[1,1,0]
	v_add_f32_dpp v100, v100, v100 quad_perm:[2,3,0,1] row_mask:0xf bank_mask:0xf bound_ctrl:1
	v_fma_mix_f32 v84, v84, v24, v102 op_sel:[0,0,0] op_sel_hi:[0,1,0]
	v_fma_mix_f32 v85, v85, v24, v103 op_sel:[0,1,0] op_sel_hi:[0,1,0]
	v_add_f32_dpp v100, v100, v100 row_half_mirror row_mask:0xf bank_mask:0xf bound_ctrl:1
	v_fma_mix_f32 v86, v86, v25, v104 op_sel:[0,0,0] op_sel_hi:[0,1,0]
	v_fma_mix_f32 v87, v87, v25, v105 op_sel:[0,1,0] op_sel_hi:[0,1,0]
	v_add_f32_dpp v100, v100, v100 row_mirror row_mask:0xf bank_mask:0xf bound_ctrl:1
	v_fma_mix_f32 v84, -v100, v32, v84 op_sel:[0,0,0] op_sel_hi:[0,1,0]
	v_fma_mix_f32 v85, -v100, v32, v85 op_sel:[0,1,0] op_sel_hi:[0,1,0]
	v_fma_mix_f32 v86, -v100, v33, v86 op_sel:[0,0,0] op_sel_hi:[0,1,0]
	v_fma_mix_f32 v87, -v100, v33, v87 op_sel:[0,1,0] op_sel_hi:[0,1,0]
	v_fma_mix_f32 v101, v84, v30, 0 op_sel:[0,0,0] op_sel_hi:[0,1,0]
	v_fma_mix_f32 v98, v84, v20, 0 op_sel:[0,0,0] op_sel_hi:[0,1,0]
	v_fma_mix_f32 v101, v85, v30, v101 op_sel:[0,1,0] op_sel_hi:[0,1,0]
	v_fma_mix_f32 v98, v85, v20, v98 op_sel:[0,1,0] op_sel_hi:[0,1,0]
	v_fma_mix_f32 v101, v86, v31, v101 op_sel:[0,0,0] op_sel_hi:[0,1,0]
	v_fma_mix_f32 v98, v86, v21, v98 op_sel:[0,0,0] op_sel_hi:[0,1,0]
	v_fma_mix_f32 v101, v87, v31, v101 op_sel:[0,1,0] op_sel_hi:[0,1,0]
	v_fma_mix_f32 v98, v87, v21, v98 op_sel:[0,1,0] op_sel_hi:[0,1,0]
	v_fma_mix_f32 v103, v89, v38, 0 op_sel:[1,0,0] op_sel_hi:[1,1,0]
	v_fma_mix_f32 v104, v89, v38, 0 op_sel:[1,1,0] op_sel_hi:[1,1,0]
	v_add_f32_dpp v101, v101, v101 quad_perm:[1,0,3,2] row_mask:0xf bank_mask:0xf bound_ctrl:1
	v_fma_mix_f32 v105, v89, v39, 0 op_sel:[1,0,0] op_sel_hi:[1,1,0]
	v_fma_mix_f32 v119, v89, v39, 0 op_sel:[1,1,0] op_sel_hi:[1,1,0]
	v_add_f32_dpp v101, v101, v101 quad_perm:[2,3,0,1] row_mask:0xf bank_mask:0xf bound_ctrl:1
	v_fma_mix_f32 v84, v84, v28, v103 op_sel:[0,0,0] op_sel_hi:[0,1,0]
	v_fma_mix_f32 v85, v85, v28, v104 op_sel:[0,1,0] op_sel_hi:[0,1,0]
	v_add_f32_dpp v101, v101, v101 row_half_mirror row_mask:0xf bank_mask:0xf bound_ctrl:1
	v_fma_mix_f32 v86, v86, v29, v105 op_sel:[0,0,0] op_sel_hi:[0,1,0]
	v_fma_mix_f32 v87, v87, v29, v119 op_sel:[0,1,0] op_sel_hi:[0,1,0]
	v_add_f32_dpp v101, v101, v101 row_mirror row_mask:0xf bank_mask:0xf bound_ctrl:1
	v_fma_mix_f32 v84, -v101, v36, v84 op_sel:[0,0,0] op_sel_hi:[0,1,0]
	v_fma_mix_f32 v85, -v101, v36, v85 op_sel:[0,1,0] op_sel_hi:[0,1,0]
	v_fma_mix_f32 v86, -v101, v37, v86 op_sel:[0,0,0] op_sel_hi:[0,1,0]
	v_fma_mix_f32 v87, -v101, v37, v87 op_sel:[0,1,0] op_sel_hi:[0,1,0]
	v_fma_mix_f32 v99, v84, v22, 0 op_sel:[0,0,0] op_sel_hi:[0,1,0]
	v_add_u32_e32 v173, 1, v193
	v_fma_mix_f32 v99, v85, v22, v99 op_sel:[0,1,0] op_sel_hi:[0,1,0]
	ds_write_b32 v172, v173 offset:49216
	v_fma_mix_f32 v99, v86, v23, v99 op_sel:[0,0,0] op_sel_hi:[0,1,0]
	v_cndmask_b32_e64 v187, v97, v96, s[38:39]
	v_fma_mix_f32 v99, v87, v23, v99 op_sel:[0,1,0] op_sel_hi:[0,1,0]
	v_cndmask_b32_e64 v188, v96, v97, s[38:39]
	v_cndmask_b32_e64 v189, v99, v98, s[38:39]
	v_cndmask_b32_e64 v190, v98, v99, s[38:39]
	s_waitcnt lgkmcnt(1)
	v_fma_mix_f32 v98, v84, v74, 0 op_sel:[0,0,0] op_sel_hi:[0,1,0]
	v_fma_mix_f32 v98, v85, v74, v98 op_sel:[0,1,0] op_sel_hi:[0,1,0]
	v_add_f32_dpp v188, v188, v187 quad_perm:[1,0,3,2] row_mask:0xf bank_mask:0xf bound_ctrl:1
	v_add_f32_dpp v189, v190, v189 quad_perm:[1,0,3,2] row_mask:0xf bank_mask:0xf bound_ctrl:1
	v_fma_mix_f32 v98, v86, v75, v98 op_sel:[0,0,0] op_sel_hi:[0,1,0]
	v_fma_mix_f32 v98, v87, v75, v98 op_sel:[0,1,0] op_sel_hi:[0,1,0]
	v_cndmask_b32_e64 v191, v189, v188, s[40:41]
	v_cndmask_b32_e64 v192, v188, v189, s[40:41]
	v_fma_mix_f32 v100, v92, v78, 0 op_sel:[0,0,0] op_sel_hi:[1,1,0]
	v_fma_mix_f32 v101, v92, v78, 0 op_sel:[0,1,0] op_sel_hi:[1,1,0]
	v_add_f32_dpp v192, v192, v191 quad_perm:[2,3,0,1] row_mask:0xf bank_mask:0xf bound_ctrl:1
	v_add_f32_dpp v98, v98, v98 quad_perm:[1,0,3,2] row_mask:0xf bank_mask:0xf bound_ctrl:1
	v_fma_mix_f32 v102, v92, v79, 0 op_sel:[0,0,0] op_sel_hi:[1,1,0]
	v_add_f32_dpp v192, v192, v192 row_ror:4 row_mask:0xf bank_mask:0xf bound_ctrl:1
	v_fma_mix_f32 v103, v92, v79, 0 op_sel:[0,1,0] op_sel_hi:[1,1,0]
	v_add_f32_dpp v98, v98, v98 quad_perm:[2,3,0,1] row_mask:0xf bank_mask:0xf bound_ctrl:1
	v_add_f32_dpp v192, v192, v192 row_ror:8 row_mask:0xf bank_mask:0xf bound_ctrl:1
	v_cvt_f16_f32_e32 v192, v192
	global_store_short v83, v192, s[36:37]
	s_add_u32 s36, s36, s44
	s_addc_u32 s37, s37, s45
	s_cmp_gt_i32 s35, 2
	s_cbranch_scc0 .Lc_poll_A0
.Lc_ret_A0:
	ds_read_b128 v[0:3], v194 offset:8192
	ds_read_b128 v[4:7], v194 offset:6144
	ds_read_b128 v[8:11], v194 offset:6400
	ds_read_b128 v[12:15], v194 offset:7168
	ds_read_b128 v[16:19], v194 offset:7424
	ds_read_b128 v[20:23], v194 offset:8448
	ds_read_b128 v[24:27], v194 offset:6656
	ds_read_b128 v[28:31], v194 offset:6912
	ds_read_b128 v[32:35], v194 offset:7680
	ds_read_b128 v[36:39], v194 offset:7936
	ds_read_b64 v[88:89], v195 offset:8704
	v_fma_mix_f32 v84, v84, v72, v100 op_sel:[0,0,0] op_sel_hi:[0,1,0]
	v_fma_mix_f32 v85, v85, v72, v101 op_sel:[0,1,0] op_sel_hi:[0,1,0]
	v_add_f32_dpp v98, v98, v98 row_half_mirror row_mask:0xf bank_mask:0xf bound_ctrl:1
	v_fma_mix_f32 v86, v86, v73, v102 op_sel:[0,0,0] op_sel_hi:[0,1,0]
	v_fma_mix_f32 v87, v87, v73, v103 op_sel:[0,1,0] op_sel_hi:[0,1,0]
	v_add_f32_dpp v98, v98, v98 row_mirror row_mask:0xf bank_mask:0xf bound_ctrl:1
	v_fma_mix_f32 v84, -v98, v76, v84 op_sel:[0,0,0] op_sel_hi:[0,1,0]
	v_fma_mix_f32 v85, -v98, v76, v85 op_sel:[0,1,0] op_sel_hi:[0,1,0]
	v_fma_mix_f32 v86, -v98, v77, v86 op_sel:[0,0,0] op_sel_hi:[0,1,0]
	v_fma_mix_f32 v87, -v98, v77, v87 op_sel:[0,1,0] op_sel_hi:[0,1,0]
	v_fma_mix_f32 v73, v84, v66, 0 op_sel:[0,0,0] op_sel_hi:[0,1,0]
	v_fma_mix_f32 v97, v84, v56, 0 op_sel:[0,0,0] op_sel_hi:[0,1,0]
	v_fma_mix_f32 v73, v85, v66, v73 op_sel:[0,1,0] op_sel_hi:[0,1,0]
	v_fma_mix_f32 v56, v85, v56, v97 op_sel:[0,1,0] op_sel_hi:[0,1,0]
	v_fma_mix_f32 v73, v86, v67, v73 op_sel:[0,0,0] op_sel_hi:[0,1,0]
	v_fma_mix_f32 v56, v86, v57, v56 op_sel:[0,0,0] op_sel_hi:[0,1,0]
	v_fma_mix_f32 v73, v87, v67, v73 op_sel:[0,1,0] op_sel_hi:[0,1,0]
	v_fma_mix_f32 v56, v87, v57, v56 op_sel:[0,1,0] op_sel_hi:[0,1,0]
	v_fma_mix_f32 v75, v92, v70, 0 op_sel:[1,0,0] op_sel_hi:[1,1,0]
	v_fma_mix_f32 v76, v92, v70, 0 op_sel:[1,1,0] op_sel_hi:[1,1,0]
	v_add_f32_dpp v73, v73, v73 quad_perm:[1,0,3,2] row_mask:0xf bank_mask:0xf bound_ctrl:1
	v_fma_mix_f32 v77, v92, v71, 0 op_sel:[1,0,0] op_sel_hi:[1,1,0]
	v_fma_mix_f32 v78, v92, v71, 0 op_sel:[1,1,0] op_sel_hi:[1,1,0]
	v_add_f32_dpp v73, v73, v73 quad_perm:[2,3,0,1] row_mask:0xf bank_mask:0xf bound_ctrl:1
	v_fma_mix_f32 v84, v84, v64, v75 op_sel:[0,0,0] op_sel_hi:[0,1,0]
	v_fma_mix_f32 v85, v85, v64, v76 op_sel:[0,1,0] op_sel_hi:[0,1,0]
	v_add_f32_dpp v73, v73, v73 row_half_mirror row_mask:0xf bank_mask:0xf bound_ctrl:1
	v_fma_mix_f32 v86, v86, v65, v77 op_sel:[0,0,0] op_sel_hi:[0,1,0]
	v_fma_mix_f32 v87, v87, v65, v78 op_sel:[0,1,0] op_sel_hi:[0,1,0]
	v_add_f32_dpp v73, v73, v73 row_mirror row_mask:0xf bank_mask:0xf bound_ctrl:1
	v_fma_mix_f32 v84, -v73, v68, v84 op_sel:[0,0,0] op_sel_hi:[0,1,0]
	v_fma_mix_f32 v85, -v73, v68, v85 op_sel:[0,1,0] op_sel_hi:[0,1,0]
	v_fma_mix_f32 v86, -v73, v69, v86 op_sel:[0,0,0] op_sel_hi:[0,1,0]
	v_fma_mix_f32 v87, -v73, v69, v87 op_sel:[0,1,0] op_sel_hi:[0,1,0]
	v_fma_mix_f32 v64, v84, v54, 0 op_sel:[0,0,0] op_sel_hi:[0,1,0]
	v_fma_mix_f32 v57, v84, v58, 0 op_sel:[0,0,0] op_sel_hi:[0,1,0]
	v_fma_mix_f32 v64, v85, v54, v64 op_sel:[0,1,0] op_sel_hi:[0,1,0]
	v_fma_mix_f32 v57, v85, v58, v57 op_sel:[0,1,0] op_sel_hi:[0,1,0]
	v_fma_mix_f32 v64, v86, v55, v64 op_sel:[0,0,0] op_sel_hi:[0,1,0]
	v_fma_mix_f32 v57, v86, v59, v57 op_sel:[0,0,0] op_sel_hi:[0,1,0]
	v_fma_mix_f32 v64, v87, v55, v64 op_sel:[0,1,0] op_sel_hi:[0,1,0]
	v_fma_mix_f32 v57, v87, v59, v57 op_sel:[0,1,0] op_sel_hi:[0,1,0]
	v_fma_mix_f32 v66, v93, v62, 0 op_sel:[0,0,0] op_sel_hi:[1,1,0]
	v_fma_mix_f32 v67, v93, v62, 0 op_sel:[0,1,0] op_sel_hi:[1,1,0]
	v_add_f32_dpp v64, v64, v64 quad_perm:[1,0,3,2] row_mask:0xf bank_mask:0xf bound_ctrl:1
	v_fma_mix_f32 v68, v93, v63, 0 op_sel:[0,0,0] op_sel_hi:[1,1,0]
	v_fma_mix_f32 v69, v93, v63, 0 op_sel:[0,1,0] op_sel_hi:[1,1,0]
	v_add_f32_dpp v64, v64, v64 quad_perm:[2,3,0,1] row_mask:0xf bank_mask:0xf bound_ctrl:1
	v_fma_mix_f32 v84, v84, v52, v66 op_sel:[0,0,0] op_sel_hi:[0,1,0]
	v_fma_mix_f32 v85, v85, v52, v67 op_sel:[0,1,0] op_sel_hi:[0,1,0]
	v_add_f32_dpp v64, v64, v64 row_half_mirror row_mask:0xf bank_mask:0xf bound_ctrl:1
	v_fma_mix_f32 v86, v86, v53, v68 op_sel:[0,0,0] op_sel_hi:[0,1,0]
	v_fma_mix_f32 v87, v87, v53, v69 op_sel:[0,1,0] op_sel_hi:[0,1,0]
	v_add_f32_dpp v64, v64, v64 row_mirror row_mask:0xf bank_mask:0xf bound_ctrl:1
	v_fma_mix_f32 v84, -v64, v60, v84 op_sel:[0,0,0] op_sel_hi:[0,1,0]
	v_fma_mix_f32 v85, -v64, v60, v85 op_sel:[0,1,0] op_sel_hi:[0,1,0]
	v_fma_mix_f32 v86, -v64, v61, v86 op_sel:[0,0,0] op_sel_hi:[0,1,0]
	v_fma_mix_f32 v87, -v64, v61, v87 op_sel:[0,1,0] op_sel_hi:[0,1,0]
	v_fma_mix_f32 v53, v84, v46, 0 op_sel:[0,0,0] op_sel_hi:[0,1,0]
	v_fma_mix_f32 v59, v84, v40, 0 op_sel:[0,0,0] op_sel_hi:[0,1,0]
	v_fma_mix_f32 v53, v85, v46, v53 op_sel:[0,1,0] op_sel_hi:[0,1,0]
	v_fma_mix_f32 v40, v85, v40, v59 op_sel:[0,1,0] op_sel_hi:[0,1,0]
	v_fma_mix_f32 v53, v86, v47, v53 op_sel:[0,0,0] op_sel_hi:[0,1,0]
	v_fma_mix_f32 v40, v86, v41, v40 op_sel:[0,0,0] op_sel_hi:[0,1,0]
	v_fma_mix_f32 v53, v87, v47, v53 op_sel:[0,1,0] op_sel_hi:[0,1,0]
	v_fma_mix_f32 v40, v87, v41, v40 op_sel:[0,1,0] op_sel_hi:[0,1,0]
	v_fma_mix_f32 v55, v93, v50, 0 op_sel:[1,0,0] op_sel_hi:[1,1,0]
	v_fma_mix_f32 v58, v93, v50, 0 op_sel:[1,1,0] op_sel_hi:[1,1,0]
	v_add_f32_dpp v53, v53, v53 quad_perm:[1,0,3,2] row_mask:0xf bank_mask:0xf bound_ctrl:1
	v_fma_mix_f32 v59, v93, v51, 0 op_sel:[1,0,0] op_sel_hi:[1,1,0]
	v_fma_mix_f32 v60, v93, v51, 0 op_sel:[1,1,0] op_sel_hi:[1,1,0]
	v_add_f32_dpp v53, v53, v53 quad_perm:[2,3,0,1] row_mask:0xf bank_mask:0xf bound_ctrl:1
	v_fma_mix_f32 v84, v84, v44, v55 op_sel:[0,0,0] op_sel_hi:[0,1,0]
	v_fma_mix_f32 v85, v85, v44, v58 op_sel:[0,1,0] op_sel_hi:[0,1,0]
	v_add_f32_dpp v53, v53, v53 row_half_mirror row_mask:0xf bank_mask:0xf bound_ctrl:1
	v_fma_mix_f32 v86, v86, v45, v59 op_sel:[0,0,0] op_sel_hi:[0,1,0]
	v_fma_mix_f32 v87, v87, v45, v60 op_sel:[0,1,0] op_sel_hi:[0,1,0]
	v_add_f32_dpp v53, v53, v53 row_mirror row_mask:0xf bank_mask:0xf bound_ctrl:1
	v_fma_mix_f32 v84, -v53, v48, v84 op_sel:[0,0,0] op_sel_hi:[0,1,0]
	v_fma_mix_f32 v85, -v53, v48, v85 op_sel:[0,1,0] op_sel_hi:[0,1,0]
	v_fma_mix_f32 v86, -v53, v49, v86 op_sel:[0,0,0] op_sel_hi:[0,1,0]
	v_fma_mix_f32 v87, -v53, v49, v87 op_sel:[0,1,0] op_sel_hi:[0,1,0]
	v_fma_mix_f32 v41, v84, v42, 0 op_sel:[0,0,0] op_sel_hi:[0,1,0]
	v_add_u32_e32 v173, 2, v193
	v_fma_mix_f32 v41, v85, v42, v41 op_sel:[0,1,0] op_sel_hi:[0,1,0]
	ds_write_b32 v172, v173 offset:49216
	v_fma_mix_f32 v41, v86, v43, v41 op_sel:[0,0,0] op_sel_hi:[0,1,0]
	v_cndmask_b32_e64 v187, v57, v56, s[38:39]
	v_fma_mix_f32 v41, v87, v43, v41 op_sel:[0,1,0] op_sel_hi:[0,1,0]
	v_cndmask_b32_e64 v188, v56, v57, s[38:39]
	v_cndmask_b32_e64 v189, v41, v40, s[38:39]
	v_cndmask_b32_e64 v190, v40, v41, s[38:39]
	s_waitcnt lgkmcnt(1)
	v_fma_mix_f32 v98, v84, v6, 0 op_sel:[0,0,0] op_sel_hi:[0,1,0]
	v_fma_mix_f32 v98, v85, v6, v98 op_sel:[0,1,0] op_sel_hi:[0,1,0]
	v_add_f32_dpp v188, v188, v187 quad_perm:[1,0,3,2] row_mask:0xf bank_mask:0xf bound_ctrl:1
	v_add_f32_dpp v189, v190, v189 quad_perm:[1,0,3,2] row_mask:0xf bank_mask:0xf bound_ctrl:1
	v_fma_mix_f32 v98, v86, v7, v98 op_sel:[0,0,0] op_sel_hi:[0,1,0]
	v_fma_mix_f32 v98, v87, v7, v98 op_sel:[0,1,0] op_sel_hi:[0,1,0]
	v_cndmask_b32_e64 v191, v189, v188, s[40:41]
	v_cndmask_b32_e64 v192, v188, v189, s[40:41]
	v_fma_mix_f32 v100, v88, v14, 0 op_sel:[0,0,0] op_sel_hi:[1,1,0]
	v_fma_mix_f32 v101, v88, v14, 0 op_sel:[0,1,0] op_sel_hi:[1,1,0]
	v_add_f32_dpp v192, v192, v191 quad_perm:[2,3,0,1] row_mask:0xf bank_mask:0xf bound_ctrl:1
	v_add_f32_dpp v98, v98, v98 quad_perm:[1,0,3,2] row_mask:0xf bank_mask:0xf bound_ctrl:1
	v_fma_mix_f32 v102, v88, v15, 0 op_sel:[0,0,0] op_sel_hi:[1,1,0]
	v_add_f32_dpp v192, v192, v192 row_ror:4 row_mask:0xf bank_mask:0xf bound_ctrl:1
	v_fma_mix_f32 v103, v88, v15, 0 op_sel:[0,1,0] op_sel_hi:[1,1,0]
	v_add_f32_dpp v98, v98, v98 quad_perm:[2,3,0,1] row_mask:0xf bank_mask:0xf bound_ctrl:1
	v_add_f32_dpp v192, v192, v192 row_ror:8 row_mask:0xf bank_mask:0xf bound_ctrl:1
	v_cvt_f16_f32_e32 v192, v192
	global_store_short v83, v192, s[36:37]
	s_add_u32 s36, s36, s44
	s_addc_u32 s37, s37, s45
	s_cmp_gt_i32 s35, 3
	s_cbranch_scc0 .Lc_poll_B0
.Lc_ret_B0:
	ds_read_b128 v[56:59], v194 offset:11264
	ds_read_b128 v[72:75], v194 offset:9216
	ds_read_b128 v[64:67], v194 offset:9472
	ds_read_b128 v[76:79], v194 offset:10240
	ds_read_b128 v[68:71], v194 offset:10496
	ds_read_b128 v[40:43], v194 offset:11520
	ds_read_b128 v[52:55], v194 offset:9728
	ds_read_b128 v[44:47], v194 offset:9984
	ds_read_b128 v[60:63], v194 offset:10752
	ds_read_b128 v[48:51], v194 offset:11008
	ds_read_b64 v[92:93], v195 offset:11776
	v_fma_mix_f32 v84, v84, v4, v100 op_sel:[0,0,0] op_sel_hi:[0,1,0]
	v_fma_mix_f32 v85, v85, v4, v101 op_sel:[0,1,0] op_sel_hi:[0,1,0]
	v_add_f32_dpp v98, v98, v98 row_half_mirror row_mask:0xf bank_mask:0xf bound_ctrl:1
	v_fma_mix_f32 v86, v86, v5, v102 op_sel:[0,0,0] op_sel_hi:[0,1,0]
	v_fma_mix_f32 v87, v87, v5, v103 op_sel:[0,1,0] op_sel_hi:[0,1,0]
	v_add_f32_dpp v98, v98, v98 row_mirror row_mask:0xf bank_mask:0xf bound_ctrl:1
	v_fma_mix_f32 v84, -v98, v12, v84 op_sel:[0,0,0] op_sel_hi:[0,1,0]
	v_fma_mix_f32 v85, -v98, v12, v85 op_sel:[0,1,0] op_sel_hi:[0,1,0]
	v_fma_mix_f32 v86, -v98, v13, v86 op_sel:[0,0,0] op_sel_hi:[0,1,0]
	v_fma_mix_f32 v87, -v98, v13, v87 op_sel:[0,1,0] op_sel_hi:[0,1,0]
	v_fma_mix_f32 v99, v84, v10, 0 op_sel:[0,0,0] op_sel_hi:[0,1,0]
	v_fma_mix_f32 v96, v84, v0, 0 op_sel:[0,0,0] op_sel_hi:[0,1,0]
	v_fma_mix_f32 v99, v85, v10, v99 op_sel:[0,1,0] op_sel_hi:[0,1,0]
	v_fma_mix_f32 v96, v85, v0, v96 op_sel:[0,1,0] op_sel_hi:[0,1,0]
	v_fma_mix_f32 v99, v86, v11, v99 op_sel:[0,0,0] op_sel_hi:[0,1,0]
	v_fma_mix_f32 v96, v86, v1, v96 op_sel:[0,0,0] op_sel_hi:[0,1,0]
	v_fma_mix_f32 v99, v87, v11, v99 op_sel:[0,1,0] op_sel_hi:[0,1,0]
	v_fma_mix_f32 v96, v87, v1, v96 op_sel:[0,1,0] op_sel_hi:[0,1,0]
	v_fma_mix_f32 v101, v88, v18, 0 op_sel:[1,0,0] op_sel_hi:[1,1,0]
	v_fma_mix_f32 v102, v88, v18, 0 op_sel:[1,1,0] op_sel_hi:[1,1,0]
	v_add_f32_dpp v99, v99, v99 quad_perm:[1,0,3,2] row_mask:0xf bank_mask:0xf bound_ctrl:1
	v_fma_mix_f32 v103, v88, v19, 0 op_sel:[1,0,0] op_sel_hi:[1,1,0]
	v_fma_mix_f32 v104, v88, v19, 0 op_sel:[1,1,0] op_sel_hi:[1,1,0]
	v_add_f32_dpp v99, v99, v99 quad_perm:[2,3,0,1] row_mask:0xf bank_mask:0xf bound_ctrl:1
	v_fma_mix_f32 v84, v84, v8, v101 op_sel:[0,0,0] op_sel_hi:[0,1,0]
	v_fma_mix_f32 v85, v85, v8, v102 op_sel:[0,1,0] op_sel_hi:[0,1,0]
	v_add_f32_dpp v99, v99, v99 row_half_mirror row_mask:0xf bank_mask:0xf bound_ctrl:1
	v_fma_mix_f32 v86, v86, v9, v103 op_sel:[0,0,0] op_sel_hi:[0,1,0]
	v_fma_mix_f32 v87, v87, v9, v104 op_sel:[0,1,0] op_sel_hi:[0,1,0]
	v_add_f32_dpp v99, v99, v99 row_mirror row_mask:0xf bank_mask:0xf bound_ctrl:1
	v_fma_mix_f32 v84, -v99, v16, v84 op_sel:[0,0,0] op_sel_hi:[0,1,0]
	v_fma_mix_f32 v85, -v99, v16, v85 op_sel:[0,1,0] op_sel_hi:[0,1,0]
	v_fma_mix_f32 v86, -v99, v17, v86 op_sel:[0,0,0] op_sel_hi:[0,1,0]
	v_fma_mix_f32 v87, -v99, v17, v87 op_sel:[0,1,0] op_sel_hi:[0,1,0]
	v_fma_mix_f32 v100, v84, v26, 0 op_sel:[0,0,0] op_sel_hi:[0,1,0]
	v_fma_mix_f32 v97, v84, v2, 0 op_sel:[0,0,0] op_sel_hi:[0,1,0]
	v_fma_mix_f32 v100, v85, v26, v100 op_sel:[0,1,0] op_sel_hi:[0,1,0]
	v_fma_mix_f32 v97, v85, v2, v97 op_sel:[0,1,0] op_sel_hi:[0,1,0]
	v_fma_mix_f32 v100, v86, v27, v100 op_sel:[0,0,0] op_sel_hi:[0,1,0]
	v_fma_mix_f32 v97, v86, v3, v97 op_sel:[0,0,0] op_sel_hi:[0,1,0]
	v_fma_mix_f32 v100, v87, v27, v100 op_sel:[0,1,0] op_sel_hi:[0,1,0]
	v_fma_mix_f32 v97, v87, v3, v97 op_sel:[0,1,0] op_sel_hi:[0,1,0]
	v_fma_mix_f32 v102, v89, v34, 0 op_sel:[0,0,0] op_sel_hi:[1,1,0]
	v_fma_mix_f32 v103, v89, v34, 0 op_sel:[0,1,0] op_sel_hi:[1,1,0]
	v_add_f32_dpp v100, v100, v100 quad_perm:[1,0,3,2] row_mask:0xf bank_mask:0xf bound_ctrl:1
	v_fma_mix_f32 v104, v89, v35, 0 op_sel:[0,0,0] op_sel_hi:[1,1,0]
	v_fma_mix_f32 v105, v89, v35, 0 op_sel:[0,1,0] op_sel_hi:[1,1,0]
	v_add_f32_dpp v100, v100, v100 quad_perm:[2,3,0,1] row_mask:0xf bank_mask:0xf bound_ctrl:1
	v_fma_mix_f32 v84, v84, v24, v102 op_sel:[0,0,0] op_sel_hi:[0,1,0]
	v_fma_mix_f32 v85, v85, v24, v103 op_sel:[0,1,0] op_sel_hi:[0,1,0]
	v_add_f32_dpp v100, v100, v100 row_half_mirror row_mask:0xf bank_mask:0xf bound_ctrl:1
	v_fma_mix_f32 v86, v86, v25, v104 op_sel:[0,0,0] op_sel_hi:[0,1,0]
	v_fma_mix_f32 v87, v87, v25, v105 op_sel:[0,1,0] op_sel_hi:[0,1,0]
	v_add_f32_dpp v100, v100, v100 row_mirror row_mask:0xf bank_mask:0xf bound_ctrl:1
	v_fma_mix_f32 v84, -v100, v32, v84 op_sel:[0,0,0] op_sel_hi:[0,1,0]
	v_fma_mix_f32 v85, -v100, v32, v85 op_sel:[0,1,0] op_sel_hi:[0,1,0]
	v_fma_mix_f32 v86, -v100, v33, v86 op_sel:[0,0,0] op_sel_hi:[0,1,0]
	v_fma_mix_f32 v87, -v100, v33, v87 op_sel:[0,1,0] op_sel_hi:[0,1,0]
	v_fma_mix_f32 v101, v84, v30, 0 op_sel:[0,0,0] op_sel_hi:[0,1,0]
	v_fma_mix_f32 v98, v84, v20, 0 op_sel:[0,0,0] op_sel_hi:[0,1,0]
	v_fma_mix_f32 v101, v85, v30, v101 op_sel:[0,1,0] op_sel_hi:[0,1,0]
	v_fma_mix_f32 v98, v85, v20, v98 op_sel:[0,1,0] op_sel_hi:[0,1,0]
	v_fma_mix_f32 v101, v86, v31, v101 op_sel:[0,0,0] op_sel_hi:[0,1,0]
	v_fma_mix_f32 v98, v86, v21, v98 op_sel:[0,0,0] op_sel_hi:[0,1,0]
	v_fma_mix_f32 v101, v87, v31, v101 op_sel:[0,1,0] op_sel_hi:[0,1,0]
	v_fma_mix_f32 v98, v87, v21, v98 op_sel:[0,1,0] op_sel_hi:[0,1,0]
	v_fma_mix_f32 v103, v89, v38, 0 op_sel:[1,0,0] op_sel_hi:[1,1,0]
	v_fma_mix_f32 v104, v89, v38, 0 op_sel:[1,1,0] op_sel_hi:[1,1,0]
	v_add_f32_dpp v101, v101, v101 quad_perm:[1,0,3,2] row_mask:0xf bank_mask:0xf bound_ctrl:1
	v_fma_mix_f32 v105, v89, v39, 0 op_sel:[1,0,0] op_sel_hi:[1,1,0]
	v_fma_mix_f32 v119, v89, v39, 0 op_sel:[1,1,0] op_sel_hi:[1,1,0]
	v_add_f32_dpp v101, v101, v101 quad_perm:[2,3,0,1] row_mask:0xf bank_mask:0xf bound_ctrl:1
	v_fma_mix_f32 v84, v84, v28, v103 op_sel:[0,0,0] op_sel_hi:[0,1,0]
	v_fma_mix_f32 v85, v85, v28, v104 op_sel:[0,1,0] op_sel_hi:[0,1,0]
	v_add_f32_dpp v101, v101, v101 row_half_mirror row_mask:0xf bank_mask:0xf bound_ctrl:1
	v_fma_mix_f32 v86, v86, v29, v105 op_sel:[0,0,0] op_sel_hi:[0,1,0]
	v_fma_mix_f32 v87, v87, v29, v119 op_sel:[0,1,0] op_sel_hi:[0,1,0]
	v_add_f32_dpp v101, v101, v101 row_mirror row_mask:0xf bank_mask:0xf bound_ctrl:1
	v_fma_mix_f32 v84, -v101, v36, v84 op_sel:[0,0,0] op_sel_hi:[0,1,0]
	v_fma_mix_f32 v85, -v101, v36, v85 op_sel:[0,1,0] op_sel_hi:[0,1,0]
	v_fma_mix_f32 v86, -v101, v37, v86 op_sel:[0,0,0] op_sel_hi:[0,1,0]
	v_fma_mix_f32 v87, -v101, v37, v87 op_sel:[0,1,0] op_sel_hi:[0,1,0]
	v_fma_mix_f32 v99, v84, v22, 0 op_sel:[0,0,0] op_sel_hi:[0,1,0]
	v_add_u32_e32 v173, 3, v193
	v_fma_mix_f32 v99, v85, v22, v99 op_sel:[0,1,0] op_sel_hi:[0,1,0]
	ds_write_b32 v172, v173 offset:49216
	v_fma_mix_f32 v99, v86, v23, v99 op_sel:[0,0,0] op_sel_hi:[0,1,0]
	v_cndmask_b32_e64 v187, v97, v96, s[38:39]
	v_fma_mix_f32 v99, v87, v23, v99 op_sel:[0,1,0] op_sel_hi:[0,1,0]
	v_cndmask_b32_e64 v188, v96, v97, s[38:39]
	v_cndmask_b32_e64 v189, v99, v98, s[38:39]
	v_cndmask_b32_e64 v190, v98, v99, s[38:39]
	s_waitcnt lgkmcnt(1)
	v_fma_mix_f32 v98, v84, v74, 0 op_sel:[0,0,0] op_sel_hi:[0,1,0]
	v_fma_mix_f32 v98, v85, v74, v98 op_sel:[0,1,0] op_sel_hi:[0,1,0]
	v_add_f32_dpp v188, v188, v187 quad_perm:[1,0,3,2] row_mask:0xf bank_mask:0xf bound_ctrl:1
	v_add_f32_dpp v189, v190, v189 quad_perm:[1,0,3,2] row_mask:0xf bank_mask:0xf bound_ctrl:1
	v_fma_mix_f32 v98, v86, v75, v98 op_sel:[0,0,0] op_sel_hi:[0,1,0]
	v_fma_mix_f32 v98, v87, v75, v98 op_sel:[0,1,0] op_sel_hi:[0,1,0]
	v_cndmask_b32_e64 v191, v189, v188, s[40:41]
	v_cndmask_b32_e64 v192, v188, v189, s[40:41]
	v_fma_mix_f32 v100, v92, v78, 0 op_sel:[0,0,0] op_sel_hi:[1,1,0]
	v_fma_mix_f32 v101, v92, v78, 0 op_sel:[0,1,0] op_sel_hi:[1,1,0]
	v_add_f32_dpp v192, v192, v191 quad_perm:[2,3,0,1] row_mask:0xf bank_mask:0xf bound_ctrl:1
	v_add_f32_dpp v98, v98, v98 quad_perm:[1,0,3,2] row_mask:0xf bank_mask:0xf bound_ctrl:1
	v_fma_mix_f32 v102, v92, v79, 0 op_sel:[0,0,0] op_sel_hi:[1,1,0]
	v_add_f32_dpp v192, v192, v192 row_ror:4 row_mask:0xf bank_mask:0xf bound_ctrl:1
	v_fma_mix_f32 v103, v92, v79, 0 op_sel:[0,1,0] op_sel_hi:[1,1,0]
	v_add_f32_dpp v98, v98, v98 quad_perm:[2,3,0,1] row_mask:0xf bank_mask:0xf bound_ctrl:1
	v_add_f32_dpp v192, v192, v192 row_ror:8 row_mask:0xf bank_mask:0xf bound_ctrl:1
	v_cvt_f16_f32_e32 v192, v192
	global_store_short v83, v192, s[36:37]
	s_add_u32 s36, s36, s44
	s_addc_u32 s37, s37, s45
	s_cmp_gt_i32 s35, 4
	s_cbranch_scc0 .Lc_poll_A1
.Lc_ret_A1:
	ds_read_b128 v[0:3], v194 offset:14336
	ds_read_b128 v[4:7], v194 offset:12288
	ds_read_b128 v[8:11], v194 offset:12544
	ds_read_b128 v[12:15], v194 offset:13312
	ds_read_b128 v[16:19], v194 offset:13568
	ds_read_b128 v[20:23], v194 offset:14592
	ds_read_b128 v[24:27], v194 offset:12800
	ds_read_b128 v[28:31], v194 offset:13056
	ds_read_b128 v[32:35], v194 offset:13824
	ds_read_b128 v[36:39], v194 offset:14080
	ds_read_b64 v[88:89], v195 offset:14848
	v_fma_mix_f32 v84, v84, v72, v100 op_sel:[0,0,0] op_sel_hi:[0,1,0]
	v_fma_mix_f32 v85, v85, v72, v101 op_sel:[0,1,0] op_sel_hi:[0,1,0]
	v_add_f32_dpp v98, v98, v98 row_half_mirror row_mask:0xf bank_mask:0xf bound_ctrl:1
	v_fma_mix_f32 v86, v86, v73, v102 op_sel:[0,0,0] op_sel_hi:[0,1,0]
	v_fma_mix_f32 v87, v87, v73, v103 op_sel:[0,1,0] op_sel_hi:[0,1,0]
	v_add_f32_dpp v98, v98, v98 row_mirror row_mask:0xf bank_mask:0xf bound_ctrl:1
	v_fma_mix_f32 v84, -v98, v76, v84 op_sel:[0,0,0] op_sel_hi:[0,1,0]
	v_fma_mix_f32 v85, -v98, v76, v85 op_sel:[0,1,0] op_sel_hi:[0,1,0]
	v_fma_mix_f32 v86, -v98, v77, v86 op_sel:[0,0,0] op_sel_hi:[0,1,0]
	v_fma_mix_f32 v87, -v98, v77, v87 op_sel:[0,1,0] op_sel_hi:[0,1,0]
	v_fma_mix_f32 v73, v84, v66, 0 op_sel:[0,0,0] op_sel_hi:[0,1,0]
	v_fma_mix_f32 v97, v84, v56, 0 op_sel:[0,0,0] op_sel_hi:[0,1,0]
	v_fma_mix_f32 v73, v85, v66, v73 op_sel:[0,1,0] op_sel_hi:[0,1,0]
	v_fma_mix_f32 v56, v85, v56, v97 op_sel:[0,1,0] op_sel_hi:[0,1,0]
	v_fma_mix_f32 v73, v86, v67, v73 op_sel:[0,0,0] op_sel_hi:[0,1,0]
	v_fma_mix_f32 v56, v86, v57, v56 op_sel:[0,0,0] op_sel_hi:[0,1,0]
	v_fma_mix_f32 v73, v87, v67, v73 op_sel:[0,1,0] op_sel_hi:[0,1,0]
	v_fma_mix_f32 v56, v87, v57, v56 op_sel:[0,1,0] op_sel_hi:[0,1,0]
	v_fma_mix_f32 v75, v92, v70, 0 op_sel:[1,0,0] op_sel_hi:[1,1,0]
	v_fma_mix_f32 v76, v92, v70, 0 op_sel:[1,1,0] op_sel_hi:[1,1,0]
	v_add_f32_dpp v73, v73, v73 quad_perm:[1,0,3,2] row_mask:0xf bank_mask:0xf bound_ctrl:1
	v_fma_mix_f32 v77, v92, v71, 0 op_sel:[1,0,0] op_sel_hi:[1,1,0]
	v_fma_mix_f32 v78, v92, v71, 0 op_sel:[1,1,0] op_sel_hi:[1,1,0]
	v_add_f32_dpp v73, v73, v73 quad_perm:[2,3,0,1] row_mask:0xf bank_mask:0xf bound_ctrl:1
	v_fma_mix_f32 v84, v84, v64, v75 op_sel:[0,0,0] op_sel_hi:[0,1,0]
	v_fma_mix_f32 v85, v85, v64, v76 op_sel:[0,1,0] op_sel_hi:[0,1,0]
	v_add_f32_dpp v73, v73, v73 row_half_mirror row_mask:0xf bank_mask:0xf bound_ctrl:1
	v_fma_mix_f32 v86, v86, v65, v77 op_sel:[0,0,0] op_sel_hi:[0,1,0]
	v_fma_mix_f32 v87, v87, v65, v78 op_sel:[0,1,0] op_sel_hi:[0,1,0]
	v_add_f32_dpp v73, v73, v73 row_mirror row_mask:0xf bank_mask:0xf bound_ctrl:1
	v_fma_mix_f32 v84, -v73, v68, v84 op_sel:[0,0,0] op_sel_hi:[0,1,0]
	v_fma_mix_f32 v85, -v73, v68, v85 op_sel:[0,1,0] op_sel_hi:[0,1,0]
	v_fma_mix_f32 v86, -v73, v69, v86 op_sel:[0,0,0] op_sel_hi:[0,1,0]
	v_fma_mix_f32 v87, -v73, v69, v87 op_sel:[0,1,0] op_sel_hi:[0,1,0]
	v_fma_mix_f32 v64, v84, v54, 0 op_sel:[0,0,0] op_sel_hi:[0,1,0]
	v_fma_mix_f32 v57, v84, v58, 0 op_sel:[0,0,0] op_sel_hi:[0,1,0]
	v_fma_mix_f32 v64, v85, v54, v64 op_sel:[0,1,0] op_sel_hi:[0,1,0]
	v_fma_mix_f32 v57, v85, v58, v57 op_sel:[0,1,0] op_sel_hi:[0,1,0]
	v_fma_mix_f32 v64, v86, v55, v64 op_sel:[0,0,0] op_sel_hi:[0,1,0]
	v_fma_mix_f32 v57, v86, v59, v57 op_sel:[0,0,0] op_sel_hi:[0,1,0]
	v_fma_mix_f32 v64, v87, v55, v64 op_sel:[0,1,0] op_sel_hi:[0,1,0]
	v_fma_mix_f32 v57, v87, v59, v57 op_sel:[0,1,0] op_sel_hi:[0,1,0]
	v_fma_mix_f32 v66, v93, v62, 0 op_sel:[0,0,0] op_sel_hi:[1,1,0]
	v_fma_mix_f32 v67, v93, v62, 0 op_sel:[0,1,0] op_sel_hi:[1,1,0]
	v_add_f32_dpp v64, v64, v64 quad_perm:[1,0,3,2] row_mask:0xf bank_mask:0xf bound_ctrl:1
	v_fma_mix_f32 v68, v93, v63, 0 op_sel:[0,0,0] op_sel_hi:[1,1,0]
	v_fma_mix_f32 v69, v93, v63, 0 op_sel:[0,1,0] op_sel_hi:[1,1,0]
	v_add_f32_dpp v64, v64, v64 quad_perm:[2,3,0,1] row_mask:0xf bank_mask:0xf bound_ctrl:1
	v_fma_mix_f32 v84, v84, v52, v66 op_sel:[0,0,0] op_sel_hi:[0,1,0]
	v_fma_mix_f32 v85, v85, v52, v67 op_sel:[0,1,0] op_sel_hi:[0,1,0]
	v_add_f32_dpp v64, v64, v64 row_half_mirror row_mask:0xf bank_mask:0xf bound_ctrl:1
	v_fma_mix_f32 v86, v86, v53, v68 op_sel:[0,0,0] op_sel_hi:[0,1,0]
	v_fma_mix_f32 v87, v87, v53, v69 op_sel:[0,1,0] op_sel_hi:[0,1,0]
	v_add_f32_dpp v64, v64, v64 row_mirror row_mask:0xf bank_mask:0xf bound_ctrl:1
	v_fma_mix_f32 v84, -v64, v60, v84 op_sel:[0,0,0] op_sel_hi:[0,1,0]
	v_fma_mix_f32 v85, -v64, v60, v85 op_sel:[0,1,0] op_sel_hi:[0,1,0]
	v_fma_mix_f32 v86, -v64, v61, v86 op_sel:[0,0,0] op_sel_hi:[0,1,0]
	v_fma_mix_f32 v87, -v64, v61, v87 op_sel:[0,1,0] op_sel_hi:[0,1,0]
	v_fma_mix_f32 v53, v84, v46, 0 op_sel:[0,0,0] op_sel_hi:[0,1,0]
	v_fma_mix_f32 v59, v84, v40, 0 op_sel:[0,0,0] op_sel_hi:[0,1,0]
	v_fma_mix_f32 v53, v85, v46, v53 op_sel:[0,1,0] op_sel_hi:[0,1,0]
	v_fma_mix_f32 v40, v85, v40, v59 op_sel:[0,1,0] op_sel_hi:[0,1,0]
	v_fma_mix_f32 v53, v86, v47, v53 op_sel:[0,0,0] op_sel_hi:[0,1,0]
	v_fma_mix_f32 v40, v86, v41, v40 op_sel:[0,0,0] op_sel_hi:[0,1,0]
	v_fma_mix_f32 v53, v87, v47, v53 op_sel:[0,1,0] op_sel_hi:[0,1,0]
	v_fma_mix_f32 v40, v87, v41, v40 op_sel:[0,1,0] op_sel_hi:[0,1,0]
	v_fma_mix_f32 v55, v93, v50, 0 op_sel:[1,0,0] op_sel_hi:[1,1,0]
	v_fma_mix_f32 v58, v93, v50, 0 op_sel:[1,1,0] op_sel_hi:[1,1,0]
	v_add_f32_dpp v53, v53, v53 quad_perm:[1,0,3,2] row_mask:0xf bank_mask:0xf bound_ctrl:1
	v_fma_mix_f32 v59, v93, v51, 0 op_sel:[1,0,0] op_sel_hi:[1,1,0]
	v_fma_mix_f32 v60, v93, v51, 0 op_sel:[1,1,0] op_sel_hi:[1,1,0]
	v_add_f32_dpp v53, v53, v53 quad_perm:[2,3,0,1] row_mask:0xf bank_mask:0xf bound_ctrl:1
	v_fma_mix_f32 v84, v84, v44, v55 op_sel:[0,0,0] op_sel_hi:[0,1,0]
	v_fma_mix_f32 v85, v85, v44, v58 op_sel:[0,1,0] op_sel_hi:[0,1,0]
	v_add_f32_dpp v53, v53, v53 row_half_mirror row_mask:0xf bank_mask:0xf bound_ctrl:1
	v_fma_mix_f32 v86, v86, v45, v59 op_sel:[0,0,0] op_sel_hi:[0,1,0]
	v_fma_mix_f32 v87, v87, v45, v60 op_sel:[0,1,0] op_sel_hi:[0,1,0]
	v_add_f32_dpp v53, v53, v53 row_mirror row_mask:0xf bank_mask:0xf bound_ctrl:1
	v_fma_mix_f32 v84, -v53, v48, v84 op_sel:[0,0,0] op_sel_hi:[0,1,0]
	v_fma_mix_f32 v85, -v53, v48, v85 op_sel:[0,1,0] op_sel_hi:[0,1,0]
	v_fma_mix_f32 v86, -v53, v49, v86 op_sel:[0,0,0] op_sel_hi:[0,1,0]
	v_fma_mix_f32 v87, -v53, v49, v87 op_sel:[0,1,0] op_sel_hi:[0,1,0]
	v_fma_mix_f32 v41, v84, v42, 0 op_sel:[0,0,0] op_sel_hi:[0,1,0]
	v_add_u32_e32 v173, 4, v193
	v_fma_mix_f32 v41, v85, v42, v41 op_sel:[0,1,0] op_sel_hi:[0,1,0]
	ds_write_b32 v172, v173 offset:49216
	v_fma_mix_f32 v41, v86, v43, v41 op_sel:[0,0,0] op_sel_hi:[0,1,0]
	v_cndmask_b32_e64 v187, v57, v56, s[38:39]
	v_fma_mix_f32 v41, v87, v43, v41 op_sel:[0,1,0] op_sel_hi:[0,1,0]
	v_cndmask_b32_e64 v188, v56, v57, s[38:39]
	v_cndmask_b32_e64 v189, v41, v40, s[38:39]
	v_cndmask_b32_e64 v190, v40, v41, s[38:39]
	s_waitcnt lgkmcnt(1)
	v_fma_mix_f32 v98, v84, v6, 0 op_sel:[0,0,0] op_sel_hi:[0,1,0]
	v_fma_mix_f32 v98, v85, v6, v98 op_sel:[0,1,0] op_sel_hi:[0,1,0]
	v_add_f32_dpp v188, v188, v187 quad_perm:[1,0,3,2] row_mask:0xf bank_mask:0xf bound_ctrl:1
	v_add_f32_dpp v189, v190, v189 quad_perm:[1,0,3,2] row_mask:0xf bank_mask:0xf bound_ctrl:1
	v_fma_mix_f32 v98, v86, v7, v98 op_sel:[0,0,0] op_sel_hi:[0,1,0]
	v_fma_mix_f32 v98, v87, v7, v98 op_sel:[0,1,0] op_sel_hi:[0,1,0]
	v_cndmask_b32_e64 v191, v189, v188, s[40:41]
	v_cndmask_b32_e64 v192, v188, v189, s[40:41]
	v_fma_mix_f32 v100, v88, v14, 0 op_sel:[0,0,0] op_sel_hi:[1,1,0]
	v_fma_mix_f32 v101, v88, v14, 0 op_sel:[0,1,0] op_sel_hi:[1,1,0]
	v_add_f32_dpp v192, v192, v191 quad_perm:[2,3,0,1] row_mask:0xf bank_mask:0xf bound_ctrl:1
	v_add_f32_dpp v98, v98, v98 quad_perm:[1,0,3,2] row_mask:0xf bank_mask:0xf bound_ctrl:1
	v_fma_mix_f32 v102, v88, v15, 0 op_sel:[0,0,0] op_sel_hi:[1,1,0]
	v_add_f32_dpp v192, v192, v192 row_ror:4 row_mask:0xf bank_mask:0xf bound_ctrl:1
	v_fma_mix_f32 v103, v88, v15, 0 op_sel:[0,1,0] op_sel_hi:[1,1,0]
	v_add_f32_dpp v98, v98, v98 quad_perm:[2,3,0,1] row_mask:0xf bank_mask:0xf bound_ctrl:1
	v_add_f32_dpp v192, v192, v192 row_ror:8 row_mask:0xf bank_mask:0xf bound_ctrl:1
	v_cvt_f16_f32_e32 v192, v192
	global_store_short v83, v192, s[36:37]
	s_add_u32 s36, s36, s44
	s_addc_u32 s37, s37, s45
	s_cmp_gt_i32 s35, 5
	s_cbranch_scc0 .Lc_poll_B1
.Lc_ret_B1:
	ds_read_b128 v[56:59], v194 offset:17408
	ds_read_b128 v[72:75], v194 offset:15360
	ds_read_b128 v[64:67], v194 offset:15616
	ds_read_b128 v[76:79], v194 offset:16384
	ds_read_b128 v[68:71], v194 offset:16640
	ds_read_b128 v[40:43], v194 offset:17664
	ds_read_b128 v[52:55], v194 offset:15872
	ds_read_b128 v[44:47], v194 offset:16128
	ds_read_b128 v[60:63], v194 offset:16896
	ds_read_b128 v[48:51], v194 offset:17152
	ds_read_b64 v[92:93], v195 offset:17920
	v_fma_mix_f32 v84, v84, v4, v100 op_sel:[0,0,0] op_sel_hi:[0,1,0]
	v_fma_mix_f32 v85, v85, v4, v101 op_sel:[0,1,0] op_sel_hi:[0,1,0]
	v_add_f32_dpp v98, v98, v98 row_half_mirror row_mask:0xf bank_mask:0xf bound_ctrl:1
	v_fma_mix_f32 v86, v86, v5, v102 op_sel:[0,0,0] op_sel_hi:[0,1,0]
	v_fma_mix_f32 v87, v87, v5, v103 op_sel:[0,1,0] op_sel_hi:[0,1,0]
	v_add_f32_dpp v98, v98, v98 row_mirror row_mask:0xf bank_mask:0xf bound_ctrl:1
	v_fma_mix_f32 v84, -v98, v12, v84 op_sel:[0,0,0] op_sel_hi:[0,1,0]
	v_fma_mix_f32 v85, -v98, v12, v85 op_sel:[0,1,0] op_sel_hi:[0,1,0]
	v_fma_mix_f32 v86, -v98, v13, v86 op_sel:[0,0,0] op_sel_hi:[0,1,0]
	v_fma_mix_f32 v87, -v98, v13, v87 op_sel:[0,1,0] op_sel_hi:[0,1,0]
	v_fma_mix_f32 v99, v84, v10, 0 op_sel:[0,0,0] op_sel_hi:[0,1,0]
	v_fma_mix_f32 v96, v84, v0, 0 op_sel:[0,0,0] op_sel_hi:[0,1,0]
	v_fma_mix_f32 v99, v85, v10, v99 op_sel:[0,1,0] op_sel_hi:[0,1,0]
	v_fma_mix_f32 v96, v85, v0, v96 op_sel:[0,1,0] op_sel_hi:[0,1,0]
	v_fma_mix_f32 v99, v86, v11, v99 op_sel:[0,0,0] op_sel_hi:[0,1,0]
	v_fma_mix_f32 v96, v86, v1, v96 op_sel:[0,0,0] op_sel_hi:[0,1,0]
	v_fma_mix_f32 v99, v87, v11, v99 op_sel:[0,1,0] op_sel_hi:[0,1,0]
	v_fma_mix_f32 v96, v87, v1, v96 op_sel:[0,1,0] op_sel_hi:[0,1,0]
	v_fma_mix_f32 v101, v88, v18, 0 op_sel:[1,0,0] op_sel_hi:[1,1,0]
	v_fma_mix_f32 v102, v88, v18, 0 op_sel:[1,1,0] op_sel_hi:[1,1,0]
	v_add_f32_dpp v99, v99, v99 quad_perm:[1,0,3,2] row_mask:0xf bank_mask:0xf bound_ctrl:1
	v_fma_mix_f32 v103, v88, v19, 0 op_sel:[1,0,0] op_sel_hi:[1,1,0]
	v_fma_mix_f32 v104, v88, v19, 0 op_sel:[1,1,0] op_sel_hi:[1,1,0]
	v_add_f32_dpp v99, v99, v99 quad_perm:[2,3,0,1] row_mask:0xf bank_mask:0xf bound_ctrl:1
	v_fma_mix_f32 v84, v84, v8, v101 op_sel:[0,0,0] op_sel_hi:[0,1,0]
	v_fma_mix_f32 v85, v85, v8, v102 op_sel:[0,1,0] op_sel_hi:[0,1,0]
	v_add_f32_dpp v99, v99, v99 row_half_mirror row_mask:0xf bank_mask:0xf bound_ctrl:1
	v_fma_mix_f32 v86, v86, v9, v103 op_sel:[0,0,0] op_sel_hi:[0,1,0]
	v_fma_mix_f32 v87, v87, v9, v104 op_sel:[0,1,0] op_sel_hi:[0,1,0]
	v_add_f32_dpp v99, v99, v99 row_mirror row_mask:0xf bank_mask:0xf bound_ctrl:1
	v_fma_mix_f32 v84, -v99, v16, v84 op_sel:[0,0,0] op_sel_hi:[0,1,0]
	v_fma_mix_f32 v85, -v99, v16, v85 op_sel:[0,1,0] op_sel_hi:[0,1,0]
	v_fma_mix_f32 v86, -v99, v17, v86 op_sel:[0,0,0] op_sel_hi:[0,1,0]
	v_fma_mix_f32 v87, -v99, v17, v87 op_sel:[0,1,0] op_sel_hi:[0,1,0]
	v_fma_mix_f32 v100, v84, v26, 0 op_sel:[0,0,0] op_sel_hi:[0,1,0]
	v_fma_mix_f32 v97, v84, v2, 0 op_sel:[0,0,0] op_sel_hi:[0,1,0]
	v_fma_mix_f32 v100, v85, v26, v100 op_sel:[0,1,0] op_sel_hi:[0,1,0]
	v_fma_mix_f32 v97, v85, v2, v97 op_sel:[0,1,0] op_sel_hi:[0,1,0]
	v_fma_mix_f32 v100, v86, v27, v100 op_sel:[0,0,0] op_sel_hi:[0,1,0]
	v_fma_mix_f32 v97, v86, v3, v97 op_sel:[0,0,0] op_sel_hi:[0,1,0]
	v_fma_mix_f32 v100, v87, v27, v100 op_sel:[0,1,0] op_sel_hi:[0,1,0]
	v_fma_mix_f32 v97, v87, v3, v97 op_sel:[0,1,0] op_sel_hi:[0,1,0]
	v_fma_mix_f32 v102, v89, v34, 0 op_sel:[0,0,0] op_sel_hi:[1,1,0]
	v_fma_mix_f32 v103, v89, v34, 0 op_sel:[0,1,0] op_sel_hi:[1,1,0]
	v_add_f32_dpp v100, v100, v100 quad_perm:[1,0,3,2] row_mask:0xf bank_mask:0xf bound_ctrl:1
	v_fma_mix_f32 v104, v89, v35, 0 op_sel:[0,0,0] op_sel_hi:[1,1,0]
	v_fma_mix_f32 v105, v89, v35, 0 op_sel:[0,1,0] op_sel_hi:[1,1,0]
	v_add_f32_dpp v100, v100, v100 quad_perm:[2,3,0,1] row_mask:0xf bank_mask:0xf bound_ctrl:1
	v_fma_mix_f32 v84, v84, v24, v102 op_sel:[0,0,0] op_sel_hi:[0,1,0]
	v_fma_mix_f32 v85, v85, v24, v103 op_sel:[0,1,0] op_sel_hi:[0,1,0]
	v_add_f32_dpp v100, v100, v100 row_half_mirror row_mask:0xf bank_mask:0xf bound_ctrl:1
	v_fma_mix_f32 v86, v86, v25, v104 op_sel:[0,0,0] op_sel_hi:[0,1,0]
	v_fma_mix_f32 v87, v87, v25, v105 op_sel:[0,1,0] op_sel_hi:[0,1,0]
	v_add_f32_dpp v100, v100, v100 row_mirror row_mask:0xf bank_mask:0xf bound_ctrl:1
	v_fma_mix_f32 v84, -v100, v32, v84 op_sel:[0,0,0] op_sel_hi:[0,1,0]
	v_fma_mix_f32 v85, -v100, v32, v85 op_sel:[0,1,0] op_sel_hi:[0,1,0]
	v_fma_mix_f32 v86, -v100, v33, v86 op_sel:[0,0,0] op_sel_hi:[0,1,0]
	v_fma_mix_f32 v87, -v100, v33, v87 op_sel:[0,1,0] op_sel_hi:[0,1,0]
	v_fma_mix_f32 v101, v84, v30, 0 op_sel:[0,0,0] op_sel_hi:[0,1,0]
	v_fma_mix_f32 v98, v84, v20, 0 op_sel:[0,0,0] op_sel_hi:[0,1,0]
	v_fma_mix_f32 v101, v85, v30, v101 op_sel:[0,1,0] op_sel_hi:[0,1,0]
	v_fma_mix_f32 v98, v85, v20, v98 op_sel:[0,1,0] op_sel_hi:[0,1,0]
	v_fma_mix_f32 v101, v86, v31, v101 op_sel:[0,0,0] op_sel_hi:[0,1,0]
	v_fma_mix_f32 v98, v86, v21, v98 op_sel:[0,0,0] op_sel_hi:[0,1,0]
	v_fma_mix_f32 v101, v87, v31, v101 op_sel:[0,1,0] op_sel_hi:[0,1,0]
	v_fma_mix_f32 v98, v87, v21, v98 op_sel:[0,1,0] op_sel_hi:[0,1,0]
	v_fma_mix_f32 v103, v89, v38, 0 op_sel:[1,0,0] op_sel_hi:[1,1,0]
	v_fma_mix_f32 v104, v89, v38, 0 op_sel:[1,1,0] op_sel_hi:[1,1,0]
	v_add_f32_dpp v101, v101, v101 quad_perm:[1,0,3,2] row_mask:0xf bank_mask:0xf bound_ctrl:1
	v_fma_mix_f32 v105, v89, v39, 0 op_sel:[1,0,0] op_sel_hi:[1,1,0]
	v_fma_mix_f32 v119, v89, v39, 0 op_sel:[1,1,0] op_sel_hi:[1,1,0]
	v_add_f32_dpp v101, v101, v101 quad_perm:[2,3,0,1] row_mask:0xf bank_mask:0xf bound_ctrl:1
	v_fma_mix_f32 v84, v84, v28, v103 op_sel:[0,0,0] op_sel_hi:[0,1,0]
	v_fma_mix_f32 v85, v85, v28, v104 op_sel:[0,1,0] op_sel_hi:[0,1,0]
	v_add_f32_dpp v101, v101, v101 row_half_mirror row_mask:0xf bank_mask:0xf bound_ctrl:1
	v_fma_mix_f32 v86, v86, v29, v105 op_sel:[0,0,0] op_sel_hi:[0,1,0]
	v_fma_mix_f32 v87, v87, v29, v119 op_sel:[0,1,0] op_sel_hi:[0,1,0]
	v_add_f32_dpp v101, v101, v101 row_mirror row_mask:0xf bank_mask:0xf bound_ctrl:1
	v_fma_mix_f32 v84, -v101, v36, v84 op_sel:[0,0,0] op_sel_hi:[0,1,0]
	v_fma_mix_f32 v85, -v101, v36, v85 op_sel:[0,1,0] op_sel_hi:[0,1,0]
	v_fma_mix_f32 v86, -v101, v37, v86 op_sel:[0,0,0] op_sel_hi:[0,1,0]
	v_fma_mix_f32 v87, -v101, v37, v87 op_sel:[0,1,0] op_sel_hi:[0,1,0]
	v_fma_mix_f32 v99, v84, v22, 0 op_sel:[0,0,0] op_sel_hi:[0,1,0]
	v_add_u32_e32 v173, 5, v193
	v_fma_mix_f32 v99, v85, v22, v99 op_sel:[0,1,0] op_sel_hi:[0,1,0]
	ds_write_b32 v172, v173 offset:49216
	v_fma_mix_f32 v99, v86, v23, v99 op_sel:[0,0,0] op_sel_hi:[0,1,0]
	v_cndmask_b32_e64 v187, v97, v96, s[38:39]
	v_fma_mix_f32 v99, v87, v23, v99 op_sel:[0,1,0] op_sel_hi:[0,1,0]
	v_cndmask_b32_e64 v188, v96, v97, s[38:39]
	v_cndmask_b32_e64 v189, v99, v98, s[38:39]
	v_cndmask_b32_e64 v190, v98, v99, s[38:39]
	s_waitcnt lgkmcnt(1)
	v_fma_mix_f32 v98, v84, v74, 0 op_sel:[0,0,0] op_sel_hi:[0,1,0]
	v_fma_mix_f32 v98, v85, v74, v98 op_sel:[0,1,0] op_sel_hi:[0,1,0]
	v_add_f32_dpp v188, v188, v187 quad_perm:[1,0,3,2] row_mask:0xf bank_mask:0xf bound_ctrl:1
	v_add_f32_dpp v189, v190, v189 quad_perm:[1,0,3,2] row_mask:0xf bank_mask:0xf bound_ctrl:1
	v_fma_mix_f32 v98, v86, v75, v98 op_sel:[0,0,0] op_sel_hi:[0,1,0]
	v_fma_mix_f32 v98, v87, v75, v98 op_sel:[0,1,0] op_sel_hi:[0,1,0]
	v_cndmask_b32_e64 v191, v189, v188, s[40:41]
	v_cndmask_b32_e64 v192, v188, v189, s[40:41]
	v_fma_mix_f32 v100, v92, v78, 0 op_sel:[0,0,0] op_sel_hi:[1,1,0]
	v_fma_mix_f32 v101, v92, v78, 0 op_sel:[0,1,0] op_sel_hi:[1,1,0]
	v_add_f32_dpp v192, v192, v191 quad_perm:[2,3,0,1] row_mask:0xf bank_mask:0xf bound_ctrl:1
	v_add_f32_dpp v98, v98, v98 quad_perm:[1,0,3,2] row_mask:0xf bank_mask:0xf bound_ctrl:1
	v_fma_mix_f32 v102, v92, v79, 0 op_sel:[0,0,0] op_sel_hi:[1,1,0]
	v_add_f32_dpp v192, v192, v192 row_ror:4 row_mask:0xf bank_mask:0xf bound_ctrl:1
	v_fma_mix_f32 v103, v92, v79, 0 op_sel:[0,1,0] op_sel_hi:[1,1,0]
	v_add_f32_dpp v98, v98, v98 quad_perm:[2,3,0,1] row_mask:0xf bank_mask:0xf bound_ctrl:1
	v_add_f32_dpp v192, v192, v192 row_ror:8 row_mask:0xf bank_mask:0xf bound_ctrl:1
	v_cvt_f16_f32_e32 v192, v192
	global_store_short v83, v192, s[36:37]
	s_add_u32 s36, s36, s44
	s_addc_u32 s37, s37, s45
	s_cmp_gt_i32 s35, 6
	s_cbranch_scc0 .Lc_poll_A2
.Lc_ret_A2:
	ds_read_b128 v[0:3], v194 offset:20480
	ds_read_b128 v[4:7], v194 offset:18432
	ds_read_b128 v[8:11], v194 offset:18688
	ds_read_b128 v[12:15], v194 offset:19456
	ds_read_b128 v[16:19], v194 offset:19712
	ds_read_b128 v[20:23], v194 offset:20736
	ds_read_b128 v[24:27], v194 offset:18944
	ds_read_b128 v[28:31], v194 offset:19200
	ds_read_b128 v[32:35], v194 offset:19968
	ds_read_b128 v[36:39], v194 offset:20224
	ds_read_b64 v[88:89], v195 offset:20992
	v_fma_mix_f32 v84, v84, v72, v100 op_sel:[0,0,0] op_sel_hi:[0,1,0]
	v_fma_mix_f32 v85, v85, v72, v101 op_sel:[0,1,0] op_sel_hi:[0,1,0]
	v_add_f32_dpp v98, v98, v98 row_half_mirror row_mask:0xf bank_mask:0xf bound_ctrl:1
	v_fma_mix_f32 v86, v86, v73, v102 op_sel:[0,0,0] op_sel_hi:[0,1,0]
	v_fma_mix_f32 v87, v87, v73, v103 op_sel:[0,1,0] op_sel_hi:[0,1,0]
	v_add_f32_dpp v98, v98, v98 row_mirror row_mask:0xf bank_mask:0xf bound_ctrl:1
	v_fma_mix_f32 v84, -v98, v76, v84 op_sel:[0,0,0] op_sel_hi:[0,1,0]
	v_fma_mix_f32 v85, -v98, v76, v85 op_sel:[0,1,0] op_sel_hi:[0,1,0]
	v_fma_mix_f32 v86, -v98, v77, v86 op_sel:[0,0,0] op_sel_hi:[0,1,0]
	v_fma_mix_f32 v87, -v98, v77, v87 op_sel:[0,1,0] op_sel_hi:[0,1,0]
	v_fma_mix_f32 v73, v84, v66, 0 op_sel:[0,0,0] op_sel_hi:[0,1,0]
	v_fma_mix_f32 v97, v84, v56, 0 op_sel:[0,0,0] op_sel_hi:[0,1,0]
	v_fma_mix_f32 v73, v85, v66, v73 op_sel:[0,1,0] op_sel_hi:[0,1,0]
	v_fma_mix_f32 v56, v85, v56, v97 op_sel:[0,1,0] op_sel_hi:[0,1,0]
	v_fma_mix_f32 v73, v86, v67, v73 op_sel:[0,0,0] op_sel_hi:[0,1,0]
	v_fma_mix_f32 v56, v86, v57, v56 op_sel:[0,0,0] op_sel_hi:[0,1,0]
	v_fma_mix_f32 v73, v87, v67, v73 op_sel:[0,1,0] op_sel_hi:[0,1,0]
	v_fma_mix_f32 v56, v87, v57, v56 op_sel:[0,1,0] op_sel_hi:[0,1,0]
	v_fma_mix_f32 v75, v92, v70, 0 op_sel:[1,0,0] op_sel_hi:[1,1,0]
	v_fma_mix_f32 v76, v92, v70, 0 op_sel:[1,1,0] op_sel_hi:[1,1,0]
	v_add_f32_dpp v73, v73, v73 quad_perm:[1,0,3,2] row_mask:0xf bank_mask:0xf bound_ctrl:1
	v_fma_mix_f32 v77, v92, v71, 0 op_sel:[1,0,0] op_sel_hi:[1,1,0]
	v_fma_mix_f32 v78, v92, v71, 0 op_sel:[1,1,0] op_sel_hi:[1,1,0]
	v_add_f32_dpp v73, v73, v73 quad_perm:[2,3,0,1] row_mask:0xf bank_mask:0xf bound_ctrl:1
	v_fma_mix_f32 v84, v84, v64, v75 op_sel:[0,0,0] op_sel_hi:[0,1,0]
	v_fma_mix_f32 v85, v85, v64, v76 op_sel:[0,1,0] op_sel_hi:[0,1,0]
	v_add_f32_dpp v73, v73, v73 row_half_mirror row_mask:0xf bank_mask:0xf bound_ctrl:1
	v_fma_mix_f32 v86, v86, v65, v77 op_sel:[0,0,0] op_sel_hi:[0,1,0]
	v_fma_mix_f32 v87, v87, v65, v78 op_sel:[0,1,0] op_sel_hi:[0,1,0]
	v_add_f32_dpp v73, v73, v73 row_mirror row_mask:0xf bank_mask:0xf bound_ctrl:1
	v_fma_mix_f32 v84, -v73, v68, v84 op_sel:[0,0,0] op_sel_hi:[0,1,0]
	v_fma_mix_f32 v85, -v73, v68, v85 op_sel:[0,1,0] op_sel_hi:[0,1,0]
	v_fma_mix_f32 v86, -v73, v69, v86 op_sel:[0,0,0] op_sel_hi:[0,1,0]
	v_fma_mix_f32 v87, -v73, v69, v87 op_sel:[0,1,0] op_sel_hi:[0,1,0]
	v_fma_mix_f32 v64, v84, v54, 0 op_sel:[0,0,0] op_sel_hi:[0,1,0]
	v_fma_mix_f32 v57, v84, v58, 0 op_sel:[0,0,0] op_sel_hi:[0,1,0]
	v_fma_mix_f32 v64, v85, v54, v64 op_sel:[0,1,0] op_sel_hi:[0,1,0]
	v_fma_mix_f32 v57, v85, v58, v57 op_sel:[0,1,0] op_sel_hi:[0,1,0]
	v_fma_mix_f32 v64, v86, v55, v64 op_sel:[0,0,0] op_sel_hi:[0,1,0]
	v_fma_mix_f32 v57, v86, v59, v57 op_sel:[0,0,0] op_sel_hi:[0,1,0]
	v_fma_mix_f32 v64, v87, v55, v64 op_sel:[0,1,0] op_sel_hi:[0,1,0]
	v_fma_mix_f32 v57, v87, v59, v57 op_sel:[0,1,0] op_sel_hi:[0,1,0]
	v_fma_mix_f32 v66, v93, v62, 0 op_sel:[0,0,0] op_sel_hi:[1,1,0]
	v_fma_mix_f32 v67, v93, v62, 0 op_sel:[0,1,0] op_sel_hi:[1,1,0]
	v_add_f32_dpp v64, v64, v64 quad_perm:[1,0,3,2] row_mask:0xf bank_mask:0xf bound_ctrl:1
	v_fma_mix_f32 v68, v93, v63, 0 op_sel:[0,0,0] op_sel_hi:[1,1,0]
	v_fma_mix_f32 v69, v93, v63, 0 op_sel:[0,1,0] op_sel_hi:[1,1,0]
	v_add_f32_dpp v64, v64, v64 quad_perm:[2,3,0,1] row_mask:0xf bank_mask:0xf bound_ctrl:1
	v_fma_mix_f32 v84, v84, v52, v66 op_sel:[0,0,0] op_sel_hi:[0,1,0]
	v_fma_mix_f32 v85, v85, v52, v67 op_sel:[0,1,0] op_sel_hi:[0,1,0]
	v_add_f32_dpp v64, v64, v64 row_half_mirror row_mask:0xf bank_mask:0xf bound_ctrl:1
	v_fma_mix_f32 v86, v86, v53, v68 op_sel:[0,0,0] op_sel_hi:[0,1,0]
	v_fma_mix_f32 v87, v87, v53, v69 op_sel:[0,1,0] op_sel_hi:[0,1,0]
	v_add_f32_dpp v64, v64, v64 row_mirror row_mask:0xf bank_mask:0xf bound_ctrl:1
	v_fma_mix_f32 v84, -v64, v60, v84 op_sel:[0,0,0] op_sel_hi:[0,1,0]
	v_fma_mix_f32 v85, -v64, v60, v85 op_sel:[0,1,0] op_sel_hi:[0,1,0]
	v_fma_mix_f32 v86, -v64, v61, v86 op_sel:[0,0,0] op_sel_hi:[0,1,0]
	v_fma_mix_f32 v87, -v64, v61, v87 op_sel:[0,1,0] op_sel_hi:[0,1,0]
	v_fma_mix_f32 v53, v84, v46, 0 op_sel:[0,0,0] op_sel_hi:[0,1,0]
	v_fma_mix_f32 v59, v84, v40, 0 op_sel:[0,0,0] op_sel_hi:[0,1,0]
	v_fma_mix_f32 v53, v85, v46, v53 op_sel:[0,1,0] op_sel_hi:[0,1,0]
	v_fma_mix_f32 v40, v85, v40, v59 op_sel:[0,1,0] op_sel_hi:[0,1,0]
	v_fma_mix_f32 v53, v86, v47, v53 op_sel:[0,0,0] op_sel_hi:[0,1,0]
	v_fma_mix_f32 v40, v86, v41, v40 op_sel:[0,0,0] op_sel_hi:[0,1,0]
	v_fma_mix_f32 v53, v87, v47, v53 op_sel:[0,1,0] op_sel_hi:[0,1,0]
	v_fma_mix_f32 v40, v87, v41, v40 op_sel:[0,1,0] op_sel_hi:[0,1,0]
	v_fma_mix_f32 v55, v93, v50, 0 op_sel:[1,0,0] op_sel_hi:[1,1,0]
	v_fma_mix_f32 v58, v93, v50, 0 op_sel:[1,1,0] op_sel_hi:[1,1,0]
	v_add_f32_dpp v53, v53, v53 quad_perm:[1,0,3,2] row_mask:0xf bank_mask:0xf bound_ctrl:1
	v_fma_mix_f32 v59, v93, v51, 0 op_sel:[1,0,0] op_sel_hi:[1,1,0]
	v_fma_mix_f32 v60, v93, v51, 0 op_sel:[1,1,0] op_sel_hi:[1,1,0]
	v_add_f32_dpp v53, v53, v53 quad_perm:[2,3,0,1] row_mask:0xf bank_mask:0xf bound_ctrl:1
	v_fma_mix_f32 v84, v84, v44, v55 op_sel:[0,0,0] op_sel_hi:[0,1,0]
	v_fma_mix_f32 v85, v85, v44, v58 op_sel:[0,1,0] op_sel_hi:[0,1,0]
	v_add_f32_dpp v53, v53, v53 row_half_mirror row_mask:0xf bank_mask:0xf bound_ctrl:1
	v_fma_mix_f32 v86, v86, v45, v59 op_sel:[0,0,0] op_sel_hi:[0,1,0]
	v_fma_mix_f32 v87, v87, v45, v60 op_sel:[0,1,0] op_sel_hi:[0,1,0]
	v_add_f32_dpp v53, v53, v53 row_mirror row_mask:0xf bank_mask:0xf bound_ctrl:1
	v_fma_mix_f32 v84, -v53, v48, v84 op_sel:[0,0,0] op_sel_hi:[0,1,0]
	v_fma_mix_f32 v85, -v53, v48, v85 op_sel:[0,1,0] op_sel_hi:[0,1,0]
	v_fma_mix_f32 v86, -v53, v49, v86 op_sel:[0,0,0] op_sel_hi:[0,1,0]
	v_fma_mix_f32 v87, -v53, v49, v87 op_sel:[0,1,0] op_sel_hi:[0,1,0]
	v_fma_mix_f32 v41, v84, v42, 0 op_sel:[0,0,0] op_sel_hi:[0,1,0]
	v_add_u32_e32 v173, 6, v193
	v_fma_mix_f32 v41, v85, v42, v41 op_sel:[0,1,0] op_sel_hi:[0,1,0]
	ds_write_b32 v172, v173 offset:49216
	v_fma_mix_f32 v41, v86, v43, v41 op_sel:[0,0,0] op_sel_hi:[0,1,0]
	v_cndmask_b32_e64 v187, v57, v56, s[38:39]
	v_fma_mix_f32 v41, v87, v43, v41 op_sel:[0,1,0] op_sel_hi:[0,1,0]
	v_cndmask_b32_e64 v188, v56, v57, s[38:39]
	v_cndmask_b32_e64 v189, v41, v40, s[38:39]
	v_cndmask_b32_e64 v190, v40, v41, s[38:39]
	s_waitcnt lgkmcnt(1)
	v_fma_mix_f32 v98, v84, v6, 0 op_sel:[0,0,0] op_sel_hi:[0,1,0]
	v_fma_mix_f32 v98, v85, v6, v98 op_sel:[0,1,0] op_sel_hi:[0,1,0]
	v_add_f32_dpp v188, v188, v187 quad_perm:[1,0,3,2] row_mask:0xf bank_mask:0xf bound_ctrl:1
	v_add_f32_dpp v189, v190, v189 quad_perm:[1,0,3,2] row_mask:0xf bank_mask:0xf bound_ctrl:1
	v_fma_mix_f32 v98, v86, v7, v98 op_sel:[0,0,0] op_sel_hi:[0,1,0]
	v_fma_mix_f32 v98, v87, v7, v98 op_sel:[0,1,0] op_sel_hi:[0,1,0]
	v_cndmask_b32_e64 v191, v189, v188, s[40:41]
	v_cndmask_b32_e64 v192, v188, v189, s[40:41]
	v_fma_mix_f32 v100, v88, v14, 0 op_sel:[0,0,0] op_sel_hi:[1,1,0]
	v_fma_mix_f32 v101, v88, v14, 0 op_sel:[0,1,0] op_sel_hi:[1,1,0]
	v_add_f32_dpp v192, v192, v191 quad_perm:[2,3,0,1] row_mask:0xf bank_mask:0xf bound_ctrl:1
	v_add_f32_dpp v98, v98, v98 quad_perm:[1,0,3,2] row_mask:0xf bank_mask:0xf bound_ctrl:1
	v_fma_mix_f32 v102, v88, v15, 0 op_sel:[0,0,0] op_sel_hi:[1,1,0]
	v_add_f32_dpp v192, v192, v192 row_ror:4 row_mask:0xf bank_mask:0xf bound_ctrl:1
	v_fma_mix_f32 v103, v88, v15, 0 op_sel:[0,1,0] op_sel_hi:[1,1,0]
	v_add_f32_dpp v98, v98, v98 quad_perm:[2,3,0,1] row_mask:0xf bank_mask:0xf bound_ctrl:1
	v_add_f32_dpp v192, v192, v192 row_ror:8 row_mask:0xf bank_mask:0xf bound_ctrl:1
	v_cvt_f16_f32_e32 v192, v192
	global_store_short v83, v192, s[36:37]
	s_add_u32 s36, s36, s44
	s_addc_u32 s37, s37, s45
	s_cmp_gt_i32 s35, 7
	s_cbranch_scc0 .Lc_poll_B2
.Lc_ret_B2:
	ds_read_b128 v[56:59], v194 offset:23552
	ds_read_b128 v[72:75], v194 offset:21504
	ds_read_b128 v[64:67], v194 offset:21760
	ds_read_b128 v[76:79], v194 offset:22528
	ds_read_b128 v[68:71], v194 offset:22784
	ds_read_b128 v[40:43], v194 offset:23808
	ds_read_b128 v[52:55], v194 offset:22016
	ds_read_b128 v[44:47], v194 offset:22272
	ds_read_b128 v[60:63], v194 offset:23040
	ds_read_b128 v[48:51], v194 offset:23296
	ds_read_b64 v[92:93], v195 offset:24064
	v_fma_mix_f32 v84, v84, v4, v100 op_sel:[0,0,0] op_sel_hi:[0,1,0]
	v_fma_mix_f32 v85, v85, v4, v101 op_sel:[0,1,0] op_sel_hi:[0,1,0]
	v_add_f32_dpp v98, v98, v98 row_half_mirror row_mask:0xf bank_mask:0xf bound_ctrl:1
	v_fma_mix_f32 v86, v86, v5, v102 op_sel:[0,0,0] op_sel_hi:[0,1,0]
	v_fma_mix_f32 v87, v87, v5, v103 op_sel:[0,1,0] op_sel_hi:[0,1,0]
	v_add_f32_dpp v98, v98, v98 row_mirror row_mask:0xf bank_mask:0xf bound_ctrl:1
	v_fma_mix_f32 v84, -v98, v12, v84 op_sel:[0,0,0] op_sel_hi:[0,1,0]
	v_fma_mix_f32 v85, -v98, v12, v85 op_sel:[0,1,0] op_sel_hi:[0,1,0]
	v_fma_mix_f32 v86, -v98, v13, v86 op_sel:[0,0,0] op_sel_hi:[0,1,0]
	v_fma_mix_f32 v87, -v98, v13, v87 op_sel:[0,1,0] op_sel_hi:[0,1,0]
	v_fma_mix_f32 v99, v84, v10, 0 op_sel:[0,0,0] op_sel_hi:[0,1,0]
	v_fma_mix_f32 v96, v84, v0, 0 op_sel:[0,0,0] op_sel_hi:[0,1,0]
	v_fma_mix_f32 v99, v85, v10, v99 op_sel:[0,1,0] op_sel_hi:[0,1,0]
	v_fma_mix_f32 v96, v85, v0, v96 op_sel:[0,1,0] op_sel_hi:[0,1,0]
	v_fma_mix_f32 v99, v86, v11, v99 op_sel:[0,0,0] op_sel_hi:[0,1,0]
	v_fma_mix_f32 v96, v86, v1, v96 op_sel:[0,0,0] op_sel_hi:[0,1,0]
	v_fma_mix_f32 v99, v87, v11, v99 op_sel:[0,1,0] op_sel_hi:[0,1,0]
	v_fma_mix_f32 v96, v87, v1, v96 op_sel:[0,1,0] op_sel_hi:[0,1,0]
	v_fma_mix_f32 v101, v88, v18, 0 op_sel:[1,0,0] op_sel_hi:[1,1,0]
	v_fma_mix_f32 v102, v88, v18, 0 op_sel:[1,1,0] op_sel_hi:[1,1,0]
	v_add_f32_dpp v99, v99, v99 quad_perm:[1,0,3,2] row_mask:0xf bank_mask:0xf bound_ctrl:1
	v_fma_mix_f32 v103, v88, v19, 0 op_sel:[1,0,0] op_sel_hi:[1,1,0]
	v_fma_mix_f32 v104, v88, v19, 0 op_sel:[1,1,0] op_sel_hi:[1,1,0]
	v_add_f32_dpp v99, v99, v99 quad_perm:[2,3,0,1] row_mask:0xf bank_mask:0xf bound_ctrl:1
	v_fma_mix_f32 v84, v84, v8, v101 op_sel:[0,0,0] op_sel_hi:[0,1,0]
	v_fma_mix_f32 v85, v85, v8, v102 op_sel:[0,1,0] op_sel_hi:[0,1,0]
	v_add_f32_dpp v99, v99, v99 row_half_mirror row_mask:0xf bank_mask:0xf bound_ctrl:1
	v_fma_mix_f32 v86, v86, v9, v103 op_sel:[0,0,0] op_sel_hi:[0,1,0]
	v_fma_mix_f32 v87, v87, v9, v104 op_sel:[0,1,0] op_sel_hi:[0,1,0]
	v_add_f32_dpp v99, v99, v99 row_mirror row_mask:0xf bank_mask:0xf bound_ctrl:1
	v_fma_mix_f32 v84, -v99, v16, v84 op_sel:[0,0,0] op_sel_hi:[0,1,0]
	v_fma_mix_f32 v85, -v99, v16, v85 op_sel:[0,1,0] op_sel_hi:[0,1,0]
	v_fma_mix_f32 v86, -v99, v17, v86 op_sel:[0,0,0] op_sel_hi:[0,1,0]
	v_fma_mix_f32 v87, -v99, v17, v87 op_sel:[0,1,0] op_sel_hi:[0,1,0]
	v_fma_mix_f32 v100, v84, v26, 0 op_sel:[0,0,0] op_sel_hi:[0,1,0]
	v_fma_mix_f32 v97, v84, v2, 0 op_sel:[0,0,0] op_sel_hi:[0,1,0]
	v_fma_mix_f32 v100, v85, v26, v100 op_sel:[0,1,0] op_sel_hi:[0,1,0]
	v_fma_mix_f32 v97, v85, v2, v97 op_sel:[0,1,0] op_sel_hi:[0,1,0]
	v_fma_mix_f32 v100, v86, v27, v100 op_sel:[0,0,0] op_sel_hi:[0,1,0]
	v_fma_mix_f32 v97, v86, v3, v97 op_sel:[0,0,0] op_sel_hi:[0,1,0]
	v_fma_mix_f32 v100, v87, v27, v100 op_sel:[0,1,0] op_sel_hi:[0,1,0]
	v_fma_mix_f32 v97, v87, v3, v97 op_sel:[0,1,0] op_sel_hi:[0,1,0]
	v_fma_mix_f32 v102, v89, v34, 0 op_sel:[0,0,0] op_sel_hi:[1,1,0]
	v_fma_mix_f32 v103, v89, v34, 0 op_sel:[0,1,0] op_sel_hi:[1,1,0]
	v_add_f32_dpp v100, v100, v100 quad_perm:[1,0,3,2] row_mask:0xf bank_mask:0xf bound_ctrl:1
	v_fma_mix_f32 v104, v89, v35, 0 op_sel:[0,0,0] op_sel_hi:[1,1,0]
	v_fma_mix_f32 v105, v89, v35, 0 op_sel:[0,1,0] op_sel_hi:[1,1,0]
	v_add_f32_dpp v100, v100, v100 quad_perm:[2,3,0,1] row_mask:0xf bank_mask:0xf bound_ctrl:1
	v_fma_mix_f32 v84, v84, v24, v102 op_sel:[0,0,0] op_sel_hi:[0,1,0]
	v_fma_mix_f32 v85, v85, v24, v103 op_sel:[0,1,0] op_sel_hi:[0,1,0]
	v_add_f32_dpp v100, v100, v100 row_half_mirror row_mask:0xf bank_mask:0xf bound_ctrl:1
	v_fma_mix_f32 v86, v86, v25, v104 op_sel:[0,0,0] op_sel_hi:[0,1,0]
	v_fma_mix_f32 v87, v87, v25, v105 op_sel:[0,1,0] op_sel_hi:[0,1,0]
	v_add_f32_dpp v100, v100, v100 row_mirror row_mask:0xf bank_mask:0xf bound_ctrl:1
	v_fma_mix_f32 v84, -v100, v32, v84 op_sel:[0,0,0] op_sel_hi:[0,1,0]
	v_fma_mix_f32 v85, -v100, v32, v85 op_sel:[0,1,0] op_sel_hi:[0,1,0]
	v_fma_mix_f32 v86, -v100, v33, v86 op_sel:[0,0,0] op_sel_hi:[0,1,0]
	v_fma_mix_f32 v87, -v100, v33, v87 op_sel:[0,1,0] op_sel_hi:[0,1,0]
	v_fma_mix_f32 v101, v84, v30, 0 op_sel:[0,0,0] op_sel_hi:[0,1,0]
	v_fma_mix_f32 v98, v84, v20, 0 op_sel:[0,0,0] op_sel_hi:[0,1,0]
	v_fma_mix_f32 v101, v85, v30, v101 op_sel:[0,1,0] op_sel_hi:[0,1,0]
	v_fma_mix_f32 v98, v85, v20, v98 op_sel:[0,1,0] op_sel_hi:[0,1,0]
	v_fma_mix_f32 v101, v86, v31, v101 op_sel:[0,0,0] op_sel_hi:[0,1,0]
	v_fma_mix_f32 v98, v86, v21, v98 op_sel:[0,0,0] op_sel_hi:[0,1,0]
	v_fma_mix_f32 v101, v87, v31, v101 op_sel:[0,1,0] op_sel_hi:[0,1,0]
	v_fma_mix_f32 v98, v87, v21, v98 op_sel:[0,1,0] op_sel_hi:[0,1,0]
	v_fma_mix_f32 v103, v89, v38, 0 op_sel:[1,0,0] op_sel_hi:[1,1,0]
	v_fma_mix_f32 v104, v89, v38, 0 op_sel:[1,1,0] op_sel_hi:[1,1,0]
	v_add_f32_dpp v101, v101, v101 quad_perm:[1,0,3,2] row_mask:0xf bank_mask:0xf bound_ctrl:1
	v_fma_mix_f32 v105, v89, v39, 0 op_sel:[1,0,0] op_sel_hi:[1,1,0]
	v_fma_mix_f32 v119, v89, v39, 0 op_sel:[1,1,0] op_sel_hi:[1,1,0]
	v_add_f32_dpp v101, v101, v101 quad_perm:[2,3,0,1] row_mask:0xf bank_mask:0xf bound_ctrl:1
	v_fma_mix_f32 v84, v84, v28, v103 op_sel:[0,0,0] op_sel_hi:[0,1,0]
	v_fma_mix_f32 v85, v85, v28, v104 op_sel:[0,1,0] op_sel_hi:[0,1,0]
	v_add_f32_dpp v101, v101, v101 row_half_mirror row_mask:0xf bank_mask:0xf bound_ctrl:1
	v_fma_mix_f32 v86, v86, v29, v105 op_sel:[0,0,0] op_sel_hi:[0,1,0]
	v_fma_mix_f32 v87, v87, v29, v119 op_sel:[0,1,0] op_sel_hi:[0,1,0]
	v_add_f32_dpp v101, v101, v101 row_mirror row_mask:0xf bank_mask:0xf bound_ctrl:1
	v_fma_mix_f32 v84, -v101, v36, v84 op_sel:[0,0,0] op_sel_hi:[0,1,0]
	v_fma_mix_f32 v85, -v101, v36, v85 op_sel:[0,1,0] op_sel_hi:[0,1,0]
	v_fma_mix_f32 v86, -v101, v37, v86 op_sel:[0,0,0] op_sel_hi:[0,1,0]
	v_fma_mix_f32 v87, -v101, v37, v87 op_sel:[0,1,0] op_sel_hi:[0,1,0]
	v_fma_mix_f32 v99, v84, v22, 0 op_sel:[0,0,0] op_sel_hi:[0,1,0]
	v_add_u32_e32 v173, 7, v193
	v_fma_mix_f32 v99, v85, v22, v99 op_sel:[0,1,0] op_sel_hi:[0,1,0]
	ds_write_b32 v172, v173 offset:49216
	v_fma_mix_f32 v99, v86, v23, v99 op_sel:[0,0,0] op_sel_hi:[0,1,0]
	v_cndmask_b32_e64 v187, v97, v96, s[38:39]
	v_fma_mix_f32 v99, v87, v23, v99 op_sel:[0,1,0] op_sel_hi:[0,1,0]
	v_cndmask_b32_e64 v188, v96, v97, s[38:39]
	v_cndmask_b32_e64 v189, v99, v98, s[38:39]
	v_cndmask_b32_e64 v190, v98, v99, s[38:39]
	s_waitcnt lgkmcnt(1)
	v_fma_mix_f32 v98, v84, v74, 0 op_sel:[0,0,0] op_sel_hi:[0,1,0]
	v_fma_mix_f32 v98, v85, v74, v98 op_sel:[0,1,0] op_sel_hi:[0,1,0]
	v_add_f32_dpp v188, v188, v187 quad_perm:[1,0,3,2] row_mask:0xf bank_mask:0xf bound_ctrl:1
	v_add_f32_dpp v189, v190, v189 quad_perm:[1,0,3,2] row_mask:0xf bank_mask:0xf bound_ctrl:1
	v_fma_mix_f32 v98, v86, v75, v98 op_sel:[0,0,0] op_sel_hi:[0,1,0]
	v_fma_mix_f32 v98, v87, v75, v98 op_sel:[0,1,0] op_sel_hi:[0,1,0]
	v_cndmask_b32_e64 v191, v189, v188, s[40:41]
	v_cndmask_b32_e64 v192, v188, v189, s[40:41]
	v_fma_mix_f32 v100, v92, v78, 0 op_sel:[0,0,0] op_sel_hi:[1,1,0]
	v_fma_mix_f32 v101, v92, v78, 0 op_sel:[0,1,0] op_sel_hi:[1,1,0]
	v_add_f32_dpp v192, v192, v191 quad_perm:[2,3,0,1] row_mask:0xf bank_mask:0xf bound_ctrl:1
	v_add_f32_dpp v98, v98, v98 quad_perm:[1,0,3,2] row_mask:0xf bank_mask:0xf bound_ctrl:1
	v_fma_mix_f32 v102, v92, v79, 0 op_sel:[0,0,0] op_sel_hi:[1,1,0]
	v_add_f32_dpp v192, v192, v192 row_ror:4 row_mask:0xf bank_mask:0xf bound_ctrl:1
	v_fma_mix_f32 v103, v92, v79, 0 op_sel:[0,1,0] op_sel_hi:[1,1,0]
	v_add_f32_dpp v98, v98, v98 quad_perm:[2,3,0,1] row_mask:0xf bank_mask:0xf bound_ctrl:1
	v_add_f32_dpp v192, v192, v192 row_ror:8 row_mask:0xf bank_mask:0xf bound_ctrl:1
	v_cvt_f16_f32_e32 v192, v192
	global_store_short v83, v192, s[36:37]
	s_add_u32 s36, s36, s44
	s_addc_u32 s37, s37, s45
	s_cmp_gt_i32 s35, 8
	s_cbranch_scc0 .Lc_poll_A3
.Lc_ret_A3:
	ds_read_b128 v[0:3], v194 offset:26624
	ds_read_b128 v[4:7], v194 offset:24576
	ds_read_b128 v[8:11], v194 offset:24832
	ds_read_b128 v[12:15], v194 offset:25600
	ds_read_b128 v[16:19], v194 offset:25856
	ds_read_b128 v[20:23], v194 offset:26880
	ds_read_b128 v[24:27], v194 offset:25088
	ds_read_b128 v[28:31], v194 offset:25344
	ds_read_b128 v[32:35], v194 offset:26112
	ds_read_b128 v[36:39], v194 offset:26368
	ds_read_b64 v[88:89], v195 offset:27136
	v_fma_mix_f32 v84, v84, v72, v100 op_sel:[0,0,0] op_sel_hi:[0,1,0]
	v_fma_mix_f32 v85, v85, v72, v101 op_sel:[0,1,0] op_sel_hi:[0,1,0]
	v_add_f32_dpp v98, v98, v98 row_half_mirror row_mask:0xf bank_mask:0xf bound_ctrl:1
	v_fma_mix_f32 v86, v86, v73, v102 op_sel:[0,0,0] op_sel_hi:[0,1,0]
	v_fma_mix_f32 v87, v87, v73, v103 op_sel:[0,1,0] op_sel_hi:[0,1,0]
	v_add_f32_dpp v98, v98, v98 row_mirror row_mask:0xf bank_mask:0xf bound_ctrl:1
	v_fma_mix_f32 v84, -v98, v76, v84 op_sel:[0,0,0] op_sel_hi:[0,1,0]
	v_fma_mix_f32 v85, -v98, v76, v85 op_sel:[0,1,0] op_sel_hi:[0,1,0]
	v_fma_mix_f32 v86, -v98, v77, v86 op_sel:[0,0,0] op_sel_hi:[0,1,0]
	v_fma_mix_f32 v87, -v98, v77, v87 op_sel:[0,1,0] op_sel_hi:[0,1,0]
	v_fma_mix_f32 v73, v84, v66, 0 op_sel:[0,0,0] op_sel_hi:[0,1,0]
	v_fma_mix_f32 v97, v84, v56, 0 op_sel:[0,0,0] op_sel_hi:[0,1,0]
	v_fma_mix_f32 v73, v85, v66, v73 op_sel:[0,1,0] op_sel_hi:[0,1,0]
	v_fma_mix_f32 v56, v85, v56, v97 op_sel:[0,1,0] op_sel_hi:[0,1,0]
	v_fma_mix_f32 v73, v86, v67, v73 op_sel:[0,0,0] op_sel_hi:[0,1,0]
	v_fma_mix_f32 v56, v86, v57, v56 op_sel:[0,0,0] op_sel_hi:[0,1,0]
	v_fma_mix_f32 v73, v87, v67, v73 op_sel:[0,1,0] op_sel_hi:[0,1,0]
	v_fma_mix_f32 v56, v87, v57, v56 op_sel:[0,1,0] op_sel_hi:[0,1,0]
	v_fma_mix_f32 v75, v92, v70, 0 op_sel:[1,0,0] op_sel_hi:[1,1,0]
	v_fma_mix_f32 v76, v92, v70, 0 op_sel:[1,1,0] op_sel_hi:[1,1,0]
	v_add_f32_dpp v73, v73, v73 quad_perm:[1,0,3,2] row_mask:0xf bank_mask:0xf bound_ctrl:1
	v_fma_mix_f32 v77, v92, v71, 0 op_sel:[1,0,0] op_sel_hi:[1,1,0]
	v_fma_mix_f32 v78, v92, v71, 0 op_sel:[1,1,0] op_sel_hi:[1,1,0]
	v_add_f32_dpp v73, v73, v73 quad_perm:[2,3,0,1] row_mask:0xf bank_mask:0xf bound_ctrl:1
	v_fma_mix_f32 v84, v84, v64, v75 op_sel:[0,0,0] op_sel_hi:[0,1,0]
	v_fma_mix_f32 v85, v85, v64, v76 op_sel:[0,1,0] op_sel_hi:[0,1,0]
	v_add_f32_dpp v73, v73, v73 row_half_mirror row_mask:0xf bank_mask:0xf bound_ctrl:1
	v_fma_mix_f32 v86, v86, v65, v77 op_sel:[0,0,0] op_sel_hi:[0,1,0]
	v_fma_mix_f32 v87, v87, v65, v78 op_sel:[0,1,0] op_sel_hi:[0,1,0]
	v_add_f32_dpp v73, v73, v73 row_mirror row_mask:0xf bank_mask:0xf bound_ctrl:1
	v_fma_mix_f32 v84, -v73, v68, v84 op_sel:[0,0,0] op_sel_hi:[0,1,0]
	v_fma_mix_f32 v85, -v73, v68, v85 op_sel:[0,1,0] op_sel_hi:[0,1,0]
	v_fma_mix_f32 v86, -v73, v69, v86 op_sel:[0,0,0] op_sel_hi:[0,1,0]
	v_fma_mix_f32 v87, -v73, v69, v87 op_sel:[0,1,0] op_sel_hi:[0,1,0]
	v_fma_mix_f32 v64, v84, v54, 0 op_sel:[0,0,0] op_sel_hi:[0,1,0]
	v_fma_mix_f32 v57, v84, v58, 0 op_sel:[0,0,0] op_sel_hi:[0,1,0]
	v_fma_mix_f32 v64, v85, v54, v64 op_sel:[0,1,0] op_sel_hi:[0,1,0]
	v_fma_mix_f32 v57, v85, v58, v57 op_sel:[0,1,0] op_sel_hi:[0,1,0]
	v_fma_mix_f32 v64, v86, v55, v64 op_sel:[0,0,0] op_sel_hi:[0,1,0]
	v_fma_mix_f32 v57, v86, v59, v57 op_sel:[0,0,0] op_sel_hi:[0,1,0]
	v_fma_mix_f32 v64, v87, v55, v64 op_sel:[0,1,0] op_sel_hi:[0,1,0]
	v_fma_mix_f32 v57, v87, v59, v57 op_sel:[0,1,0] op_sel_hi:[0,1,0]
	v_fma_mix_f32 v66, v93, v62, 0 op_sel:[0,0,0] op_sel_hi:[1,1,0]
	v_fma_mix_f32 v67, v93, v62, 0 op_sel:[0,1,0] op_sel_hi:[1,1,0]
	v_add_f32_dpp v64, v64, v64 quad_perm:[1,0,3,2] row_mask:0xf bank_mask:0xf bound_ctrl:1
	v_fma_mix_f32 v68, v93, v63, 0 op_sel:[0,0,0] op_sel_hi:[1,1,0]
	v_fma_mix_f32 v69, v93, v63, 0 op_sel:[0,1,0] op_sel_hi:[1,1,0]
	v_add_f32_dpp v64, v64, v64 quad_perm:[2,3,0,1] row_mask:0xf bank_mask:0xf bound_ctrl:1
	v_fma_mix_f32 v84, v84, v52, v66 op_sel:[0,0,0] op_sel_hi:[0,1,0]
	v_fma_mix_f32 v85, v85, v52, v67 op_sel:[0,1,0] op_sel_hi:[0,1,0]
	v_add_f32_dpp v64, v64, v64 row_half_mirror row_mask:0xf bank_mask:0xf bound_ctrl:1
	v_fma_mix_f32 v86, v86, v53, v68 op_sel:[0,0,0] op_sel_hi:[0,1,0]
	v_fma_mix_f32 v87, v87, v53, v69 op_sel:[0,1,0] op_sel_hi:[0,1,0]
	v_add_f32_dpp v64, v64, v64 row_mirror row_mask:0xf bank_mask:0xf bound_ctrl:1
	v_fma_mix_f32 v84, -v64, v60, v84 op_sel:[0,0,0] op_sel_hi:[0,1,0]
	v_fma_mix_f32 v85, -v64, v60, v85 op_sel:[0,1,0] op_sel_hi:[0,1,0]
	v_fma_mix_f32 v86, -v64, v61, v86 op_sel:[0,0,0] op_sel_hi:[0,1,0]
	v_fma_mix_f32 v87, -v64, v61, v87 op_sel:[0,1,0] op_sel_hi:[0,1,0]
	v_fma_mix_f32 v53, v84, v46, 0 op_sel:[0,0,0] op_sel_hi:[0,1,0]
	v_fma_mix_f32 v59, v84, v40, 0 op_sel:[0,0,0] op_sel_hi:[0,1,0]
	v_fma_mix_f32 v53, v85, v46, v53 op_sel:[0,1,0] op_sel_hi:[0,1,0]
	v_fma_mix_f32 v40, v85, v40, v59 op_sel:[0,1,0] op_sel_hi:[0,1,0]
	v_fma_mix_f32 v53, v86, v47, v53 op_sel:[0,0,0] op_sel_hi:[0,1,0]
	v_fma_mix_f32 v40, v86, v41, v40 op_sel:[0,0,0] op_sel_hi:[0,1,0]
	v_fma_mix_f32 v53, v87, v47, v53 op_sel:[0,1,0] op_sel_hi:[0,1,0]
	v_fma_mix_f32 v40, v87, v41, v40 op_sel:[0,1,0] op_sel_hi:[0,1,0]
	v_fma_mix_f32 v55, v93, v50, 0 op_sel:[1,0,0] op_sel_hi:[1,1,0]
	v_fma_mix_f32 v58, v93, v50, 0 op_sel:[1,1,0] op_sel_hi:[1,1,0]
	v_add_f32_dpp v53, v53, v53 quad_perm:[1,0,3,2] row_mask:0xf bank_mask:0xf bound_ctrl:1
	v_fma_mix_f32 v59, v93, v51, 0 op_sel:[1,0,0] op_sel_hi:[1,1,0]
	v_fma_mix_f32 v60, v93, v51, 0 op_sel:[1,1,0] op_sel_hi:[1,1,0]
	v_add_f32_dpp v53, v53, v53 quad_perm:[2,3,0,1] row_mask:0xf bank_mask:0xf bound_ctrl:1
	v_fma_mix_f32 v84, v84, v44, v55 op_sel:[0,0,0] op_sel_hi:[0,1,0]
	v_fma_mix_f32 v85, v85, v44, v58 op_sel:[0,1,0] op_sel_hi:[0,1,0]
	v_add_f32_dpp v53, v53, v53 row_half_mirror row_mask:0xf bank_mask:0xf bound_ctrl:1
	v_fma_mix_f32 v86, v86, v45, v59 op_sel:[0,0,0] op_sel_hi:[0,1,0]
	v_fma_mix_f32 v87, v87, v45, v60 op_sel:[0,1,0] op_sel_hi:[0,1,0]
	v_add_f32_dpp v53, v53, v53 row_mirror row_mask:0xf bank_mask:0xf bound_ctrl:1
	v_fma_mix_f32 v84, -v53, v48, v84 op_sel:[0,0,0] op_sel_hi:[0,1,0]
	v_fma_mix_f32 v85, -v53, v48, v85 op_sel:[0,1,0] op_sel_hi:[0,1,0]
	v_fma_mix_f32 v86, -v53, v49, v86 op_sel:[0,0,0] op_sel_hi:[0,1,0]
	v_fma_mix_f32 v87, -v53, v49, v87 op_sel:[0,1,0] op_sel_hi:[0,1,0]
	v_fma_mix_f32 v41, v84, v42, 0 op_sel:[0,0,0] op_sel_hi:[0,1,0]
	v_add_u32_e32 v173, 8, v193
	v_fma_mix_f32 v41, v85, v42, v41 op_sel:[0,1,0] op_sel_hi:[0,1,0]
	ds_write_b32 v172, v173 offset:49216
	v_fma_mix_f32 v41, v86, v43, v41 op_sel:[0,0,0] op_sel_hi:[0,1,0]
	v_cndmask_b32_e64 v187, v57, v56, s[38:39]
	v_fma_mix_f32 v41, v87, v43, v41 op_sel:[0,1,0] op_sel_hi:[0,1,0]
	v_cndmask_b32_e64 v188, v56, v57, s[38:39]
	v_cndmask_b32_e64 v189, v41, v40, s[38:39]
	v_cndmask_b32_e64 v190, v40, v41, s[38:39]
	s_waitcnt lgkmcnt(1)
	v_fma_mix_f32 v98, v84, v6, 0 op_sel:[0,0,0] op_sel_hi:[0,1,0]
	v_fma_mix_f32 v98, v85, v6, v98 op_sel:[0,1,0] op_sel_hi:[0,1,0]
	v_add_f32_dpp v188, v188, v187 quad_perm:[1,0,3,2] row_mask:0xf bank_mask:0xf bound_ctrl:1
	v_add_f32_dpp v189, v190, v189 quad_perm:[1,0,3,2] row_mask:0xf bank_mask:0xf bound_ctrl:1
	v_fma_mix_f32 v98, v86, v7, v98 op_sel:[0,0,0] op_sel_hi:[0,1,0]
	v_fma_mix_f32 v98, v87, v7, v98 op_sel:[0,1,0] op_sel_hi:[0,1,0]
	v_cndmask_b32_e64 v191, v189, v188, s[40:41]
	v_cndmask_b32_e64 v192, v188, v189, s[40:41]
	v_fma_mix_f32 v100, v88, v14, 0 op_sel:[0,0,0] op_sel_hi:[1,1,0]
	v_fma_mix_f32 v101, v88, v14, 0 op_sel:[0,1,0] op_sel_hi:[1,1,0]
	v_add_f32_dpp v192, v192, v191 quad_perm:[2,3,0,1] row_mask:0xf bank_mask:0xf bound_ctrl:1
	v_add_f32_dpp v98, v98, v98 quad_perm:[1,0,3,2] row_mask:0xf bank_mask:0xf bound_ctrl:1
	v_fma_mix_f32 v102, v88, v15, 0 op_sel:[0,0,0] op_sel_hi:[1,1,0]
	v_add_f32_dpp v192, v192, v192 row_ror:4 row_mask:0xf bank_mask:0xf bound_ctrl:1
	v_fma_mix_f32 v103, v88, v15, 0 op_sel:[0,1,0] op_sel_hi:[1,1,0]
	v_add_f32_dpp v98, v98, v98 quad_perm:[2,3,0,1] row_mask:0xf bank_mask:0xf bound_ctrl:1
	v_add_f32_dpp v192, v192, v192 row_ror:8 row_mask:0xf bank_mask:0xf bound_ctrl:1
	v_cvt_f16_f32_e32 v192, v192
	global_store_short v83, v192, s[36:37]
	s_add_u32 s36, s36, s44
	s_addc_u32 s37, s37, s45
	s_cmp_gt_i32 s35, 9
	s_cbranch_scc0 .Lc_poll_B3
.Lc_ret_B3:
	ds_read_b128 v[56:59], v194 offset:29696
	ds_read_b128 v[72:75], v194 offset:27648
	ds_read_b128 v[64:67], v194 offset:27904
	ds_read_b128 v[76:79], v194 offset:28672
	ds_read_b128 v[68:71], v194 offset:28928
	ds_read_b128 v[40:43], v194 offset:29952
	ds_read_b128 v[52:55], v194 offset:28160
	ds_read_b128 v[44:47], v194 offset:28416
	ds_read_b128 v[60:63], v194 offset:29184
	ds_read_b128 v[48:51], v194 offset:29440
	ds_read_b64 v[92:93], v195 offset:30208
	v_fma_mix_f32 v84, v84, v4, v100 op_sel:[0,0,0] op_sel_hi:[0,1,0]
	v_fma_mix_f32 v85, v85, v4, v101 op_sel:[0,1,0] op_sel_hi:[0,1,0]
	v_add_f32_dpp v98, v98, v98 row_half_mirror row_mask:0xf bank_mask:0xf bound_ctrl:1
	v_fma_mix_f32 v86, v86, v5, v102 op_sel:[0,0,0] op_sel_hi:[0,1,0]
	v_fma_mix_f32 v87, v87, v5, v103 op_sel:[0,1,0] op_sel_hi:[0,1,0]
	v_add_f32_dpp v98, v98, v98 row_mirror row_mask:0xf bank_mask:0xf bound_ctrl:1
	v_fma_mix_f32 v84, -v98, v12, v84 op_sel:[0,0,0] op_sel_hi:[0,1,0]
	v_fma_mix_f32 v85, -v98, v12, v85 op_sel:[0,1,0] op_sel_hi:[0,1,0]
	v_fma_mix_f32 v86, -v98, v13, v86 op_sel:[0,0,0] op_sel_hi:[0,1,0]
	v_fma_mix_f32 v87, -v98, v13, v87 op_sel:[0,1,0] op_sel_hi:[0,1,0]
	v_fma_mix_f32 v99, v84, v10, 0 op_sel:[0,0,0] op_sel_hi:[0,1,0]
	v_fma_mix_f32 v96, v84, v0, 0 op_sel:[0,0,0] op_sel_hi:[0,1,0]
	v_fma_mix_f32 v99, v85, v10, v99 op_sel:[0,1,0] op_sel_hi:[0,1,0]
	v_fma_mix_f32 v96, v85, v0, v96 op_sel:[0,1,0] op_sel_hi:[0,1,0]
	v_fma_mix_f32 v99, v86, v11, v99 op_sel:[0,0,0] op_sel_hi:[0,1,0]
	v_fma_mix_f32 v96, v86, v1, v96 op_sel:[0,0,0] op_sel_hi:[0,1,0]
	v_fma_mix_f32 v99, v87, v11, v99 op_sel:[0,1,0] op_sel_hi:[0,1,0]
	v_fma_mix_f32 v96, v87, v1, v96 op_sel:[0,1,0] op_sel_hi:[0,1,0]
	v_fma_mix_f32 v101, v88, v18, 0 op_sel:[1,0,0] op_sel_hi:[1,1,0]
	v_fma_mix_f32 v102, v88, v18, 0 op_sel:[1,1,0] op_sel_hi:[1,1,0]
	v_add_f32_dpp v99, v99, v99 quad_perm:[1,0,3,2] row_mask:0xf bank_mask:0xf bound_ctrl:1
	v_fma_mix_f32 v103, v88, v19, 0 op_sel:[1,0,0] op_sel_hi:[1,1,0]
	v_fma_mix_f32 v104, v88, v19, 0 op_sel:[1,1,0] op_sel_hi:[1,1,0]
	v_add_f32_dpp v99, v99, v99 quad_perm:[2,3,0,1] row_mask:0xf bank_mask:0xf bound_ctrl:1
	v_fma_mix_f32 v84, v84, v8, v101 op_sel:[0,0,0] op_sel_hi:[0,1,0]
	v_fma_mix_f32 v85, v85, v8, v102 op_sel:[0,1,0] op_sel_hi:[0,1,0]
	v_add_f32_dpp v99, v99, v99 row_half_mirror row_mask:0xf bank_mask:0xf bound_ctrl:1
	v_fma_mix_f32 v86, v86, v9, v103 op_sel:[0,0,0] op_sel_hi:[0,1,0]
	v_fma_mix_f32 v87, v87, v9, v104 op_sel:[0,1,0] op_sel_hi:[0,1,0]
	v_add_f32_dpp v99, v99, v99 row_mirror row_mask:0xf bank_mask:0xf bound_ctrl:1
	v_fma_mix_f32 v84, -v99, v16, v84 op_sel:[0,0,0] op_sel_hi:[0,1,0]
	v_fma_mix_f32 v85, -v99, v16, v85 op_sel:[0,1,0] op_sel_hi:[0,1,0]
	v_fma_mix_f32 v86, -v99, v17, v86 op_sel:[0,0,0] op_sel_hi:[0,1,0]
	v_fma_mix_f32 v87, -v99, v17, v87 op_sel:[0,1,0] op_sel_hi:[0,1,0]
	v_fma_mix_f32 v100, v84, v26, 0 op_sel:[0,0,0] op_sel_hi:[0,1,0]
	v_fma_mix_f32 v97, v84, v2, 0 op_sel:[0,0,0] op_sel_hi:[0,1,0]
	v_fma_mix_f32 v100, v85, v26, v100 op_sel:[0,1,0] op_sel_hi:[0,1,0]
	v_fma_mix_f32 v97, v85, v2, v97 op_sel:[0,1,0] op_sel_hi:[0,1,0]
	v_fma_mix_f32 v100, v86, v27, v100 op_sel:[0,0,0] op_sel_hi:[0,1,0]
	v_fma_mix_f32 v97, v86, v3, v97 op_sel:[0,0,0] op_sel_hi:[0,1,0]
	v_fma_mix_f32 v100, v87, v27, v100 op_sel:[0,1,0] op_sel_hi:[0,1,0]
	v_fma_mix_f32 v97, v87, v3, v97 op_sel:[0,1,0] op_sel_hi:[0,1,0]
	v_fma_mix_f32 v102, v89, v34, 0 op_sel:[0,0,0] op_sel_hi:[1,1,0]
	v_fma_mix_f32 v103, v89, v34, 0 op_sel:[0,1,0] op_sel_hi:[1,1,0]
	v_add_f32_dpp v100, v100, v100 quad_perm:[1,0,3,2] row_mask:0xf bank_mask:0xf bound_ctrl:1
	v_fma_mix_f32 v104, v89, v35, 0 op_sel:[0,0,0] op_sel_hi:[1,1,0]
	v_fma_mix_f32 v105, v89, v35, 0 op_sel:[0,1,0] op_sel_hi:[1,1,0]
	v_add_f32_dpp v100, v100, v100 quad_perm:[2,3,0,1] row_mask:0xf bank_mask:0xf bound_ctrl:1
	v_fma_mix_f32 v84, v84, v24, v102 op_sel:[0,0,0] op_sel_hi:[0,1,0]
	v_fma_mix_f32 v85, v85, v24, v103 op_sel:[0,1,0] op_sel_hi:[0,1,0]
	v_add_f32_dpp v100, v100, v100 row_half_mirror row_mask:0xf bank_mask:0xf bound_ctrl:1
	v_fma_mix_f32 v86, v86, v25, v104 op_sel:[0,0,0] op_sel_hi:[0,1,0]
	v_fma_mix_f32 v87, v87, v25, v105 op_sel:[0,1,0] op_sel_hi:[0,1,0]
	v_add_f32_dpp v100, v100, v100 row_mirror row_mask:0xf bank_mask:0xf bound_ctrl:1
	v_fma_mix_f32 v84, -v100, v32, v84 op_sel:[0,0,0] op_sel_hi:[0,1,0]
	v_fma_mix_f32 v85, -v100, v32, v85 op_sel:[0,1,0] op_sel_hi:[0,1,0]
	v_fma_mix_f32 v86, -v100, v33, v86 op_sel:[0,0,0] op_sel_hi:[0,1,0]
	v_fma_mix_f32 v87, -v100, v33, v87 op_sel:[0,1,0] op_sel_hi:[0,1,0]
	v_fma_mix_f32 v101, v84, v30, 0 op_sel:[0,0,0] op_sel_hi:[0,1,0]
	v_fma_mix_f32 v98, v84, v20, 0 op_sel:[0,0,0] op_sel_hi:[0,1,0]
	v_fma_mix_f32 v101, v85, v30, v101 op_sel:[0,1,0] op_sel_hi:[0,1,0]
	v_fma_mix_f32 v98, v85, v20, v98 op_sel:[0,1,0] op_sel_hi:[0,1,0]
	v_fma_mix_f32 v101, v86, v31, v101 op_sel:[0,0,0] op_sel_hi:[0,1,0]
	v_fma_mix_f32 v98, v86, v21, v98 op_sel:[0,0,0] op_sel_hi:[0,1,0]
	v_fma_mix_f32 v101, v87, v31, v101 op_sel:[0,1,0] op_sel_hi:[0,1,0]
	v_fma_mix_f32 v98, v87, v21, v98 op_sel:[0,1,0] op_sel_hi:[0,1,0]
	v_fma_mix_f32 v103, v89, v38, 0 op_sel:[1,0,0] op_sel_hi:[1,1,0]
	v_fma_mix_f32 v104, v89, v38, 0 op_sel:[1,1,0] op_sel_hi:[1,1,0]
	v_add_f32_dpp v101, v101, v101 quad_perm:[1,0,3,2] row_mask:0xf bank_mask:0xf bound_ctrl:1
	v_fma_mix_f32 v105, v89, v39, 0 op_sel:[1,0,0] op_sel_hi:[1,1,0]
	v_fma_mix_f32 v119, v89, v39, 0 op_sel:[1,1,0] op_sel_hi:[1,1,0]
	v_add_f32_dpp v101, v101, v101 quad_perm:[2,3,0,1] row_mask:0xf bank_mask:0xf bound_ctrl:1
	v_fma_mix_f32 v84, v84, v28, v103 op_sel:[0,0,0] op_sel_hi:[0,1,0]
	v_fma_mix_f32 v85, v85, v28, v104 op_sel:[0,1,0] op_sel_hi:[0,1,0]
	v_add_f32_dpp v101, v101, v101 row_half_mirror row_mask:0xf bank_mask:0xf bound_ctrl:1
	v_fma_mix_f32 v86, v86, v29, v105 op_sel:[0,0,0] op_sel_hi:[0,1,0]
	v_fma_mix_f32 v87, v87, v29, v119 op_sel:[0,1,0] op_sel_hi:[0,1,0]
	v_add_f32_dpp v101, v101, v101 row_mirror row_mask:0xf bank_mask:0xf bound_ctrl:1
	v_fma_mix_f32 v84, -v101, v36, v84 op_sel:[0,0,0] op_sel_hi:[0,1,0]
	v_fma_mix_f32 v85, -v101, v36, v85 op_sel:[0,1,0] op_sel_hi:[0,1,0]
	v_fma_mix_f32 v86, -v101, v37, v86 op_sel:[0,0,0] op_sel_hi:[0,1,0]
	v_fma_mix_f32 v87, -v101, v37, v87 op_sel:[0,1,0] op_sel_hi:[0,1,0]
	v_fma_mix_f32 v99, v84, v22, 0 op_sel:[0,0,0] op_sel_hi:[0,1,0]
	v_add_u32_e32 v173, 9, v193
	v_fma_mix_f32 v99, v85, v22, v99 op_sel:[0,1,0] op_sel_hi:[0,1,0]
	ds_write_b32 v172, v173 offset:49216
	v_fma_mix_f32 v99, v86, v23, v99 op_sel:[0,0,0] op_sel_hi:[0,1,0]
	v_cndmask_b32_e64 v187, v97, v96, s[38:39]
	v_fma_mix_f32 v99, v87, v23, v99 op_sel:[0,1,0] op_sel_hi:[0,1,0]
	v_cndmask_b32_e64 v188, v96, v97, s[38:39]
	v_cndmask_b32_e64 v189, v99, v98, s[38:39]
	v_cndmask_b32_e64 v190, v98, v99, s[38:39]
	s_waitcnt lgkmcnt(1)
	v_fma_mix_f32 v98, v84, v74, 0 op_sel:[0,0,0] op_sel_hi:[0,1,0]
	v_fma_mix_f32 v98, v85, v74, v98 op_sel:[0,1,0] op_sel_hi:[0,1,0]
	v_add_f32_dpp v188, v188, v187 quad_perm:[1,0,3,2] row_mask:0xf bank_mask:0xf bound_ctrl:1
	v_add_f32_dpp v189, v190, v189 quad_perm:[1,0,3,2] row_mask:0xf bank_mask:0xf bound_ctrl:1
	v_fma_mix_f32 v98, v86, v75, v98 op_sel:[0,0,0] op_sel_hi:[0,1,0]
	v_fma_mix_f32 v98, v87, v75, v98 op_sel:[0,1,0] op_sel_hi:[0,1,0]
	v_cndmask_b32_e64 v191, v189, v188, s[40:41]
	v_cndmask_b32_e64 v192, v188, v189, s[40:41]
	v_fma_mix_f32 v100, v92, v78, 0 op_sel:[0,0,0] op_sel_hi:[1,1,0]
	v_fma_mix_f32 v101, v92, v78, 0 op_sel:[0,1,0] op_sel_hi:[1,1,0]
	v_add_f32_dpp v192, v192, v191 quad_perm:[2,3,0,1] row_mask:0xf bank_mask:0xf bound_ctrl:1
	v_add_f32_dpp v98, v98, v98 quad_perm:[1,0,3,2] row_mask:0xf bank_mask:0xf bound_ctrl:1
	v_fma_mix_f32 v102, v92, v79, 0 op_sel:[0,0,0] op_sel_hi:[1,1,0]
	v_add_f32_dpp v192, v192, v192 row_ror:4 row_mask:0xf bank_mask:0xf bound_ctrl:1
	v_fma_mix_f32 v103, v92, v79, 0 op_sel:[0,1,0] op_sel_hi:[1,1,0]
	v_add_f32_dpp v98, v98, v98 quad_perm:[2,3,0,1] row_mask:0xf bank_mask:0xf bound_ctrl:1
	v_add_f32_dpp v192, v192, v192 row_ror:8 row_mask:0xf bank_mask:0xf bound_ctrl:1
	v_cvt_f16_f32_e32 v192, v192
	global_store_short v83, v192, s[36:37]
	s_add_u32 s36, s36, s44
	s_addc_u32 s37, s37, s45
	s_cmp_gt_i32 s35, 10
	s_cbranch_scc0 .Lc_poll_A4
.Lc_ret_A4:
	ds_read_b128 v[0:3], v194 offset:32768
	ds_read_b128 v[4:7], v194 offset:30720
	ds_read_b128 v[8:11], v194 offset:30976
	ds_read_b128 v[12:15], v194 offset:31744
	ds_read_b128 v[16:19], v194 offset:32000
	ds_read_b128 v[20:23], v194 offset:33024
	ds_read_b128 v[24:27], v194 offset:31232
	ds_read_b128 v[28:31], v194 offset:31488
	ds_read_b128 v[32:35], v194 offset:32256
	ds_read_b128 v[36:39], v194 offset:32512
	ds_read_b64 v[88:89], v195 offset:33280
	v_fma_mix_f32 v84, v84, v72, v100 op_sel:[0,0,0] op_sel_hi:[0,1,0]
	v_fma_mix_f32 v85, v85, v72, v101 op_sel:[0,1,0] op_sel_hi:[0,1,0]
	v_add_f32_dpp v98, v98, v98 row_half_mirror row_mask:0xf bank_mask:0xf bound_ctrl:1
	v_fma_mix_f32 v86, v86, v73, v102 op_sel:[0,0,0] op_sel_hi:[0,1,0]
	v_fma_mix_f32 v87, v87, v73, v103 op_sel:[0,1,0] op_sel_hi:[0,1,0]
	v_add_f32_dpp v98, v98, v98 row_mirror row_mask:0xf bank_mask:0xf bound_ctrl:1
	v_fma_mix_f32 v84, -v98, v76, v84 op_sel:[0,0,0] op_sel_hi:[0,1,0]
	v_fma_mix_f32 v85, -v98, v76, v85 op_sel:[0,1,0] op_sel_hi:[0,1,0]
	v_fma_mix_f32 v86, -v98, v77, v86 op_sel:[0,0,0] op_sel_hi:[0,1,0]
	v_fma_mix_f32 v87, -v98, v77, v87 op_sel:[0,1,0] op_sel_hi:[0,1,0]
	v_fma_mix_f32 v73, v84, v66, 0 op_sel:[0,0,0] op_sel_hi:[0,1,0]
	v_fma_mix_f32 v97, v84, v56, 0 op_sel:[0,0,0] op_sel_hi:[0,1,0]
	v_fma_mix_f32 v73, v85, v66, v73 op_sel:[0,1,0] op_sel_hi:[0,1,0]
	v_fma_mix_f32 v56, v85, v56, v97 op_sel:[0,1,0] op_sel_hi:[0,1,0]
	v_fma_mix_f32 v73, v86, v67, v73 op_sel:[0,0,0] op_sel_hi:[0,1,0]
	v_fma_mix_f32 v56, v86, v57, v56 op_sel:[0,0,0] op_sel_hi:[0,1,0]
	v_fma_mix_f32 v73, v87, v67, v73 op_sel:[0,1,0] op_sel_hi:[0,1,0]
	v_fma_mix_f32 v56, v87, v57, v56 op_sel:[0,1,0] op_sel_hi:[0,1,0]
	v_fma_mix_f32 v75, v92, v70, 0 op_sel:[1,0,0] op_sel_hi:[1,1,0]
	v_fma_mix_f32 v76, v92, v70, 0 op_sel:[1,1,0] op_sel_hi:[1,1,0]
	v_add_f32_dpp v73, v73, v73 quad_perm:[1,0,3,2] row_mask:0xf bank_mask:0xf bound_ctrl:1
	v_fma_mix_f32 v77, v92, v71, 0 op_sel:[1,0,0] op_sel_hi:[1,1,0]
	v_fma_mix_f32 v78, v92, v71, 0 op_sel:[1,1,0] op_sel_hi:[1,1,0]
	v_add_f32_dpp v73, v73, v73 quad_perm:[2,3,0,1] row_mask:0xf bank_mask:0xf bound_ctrl:1
	v_fma_mix_f32 v84, v84, v64, v75 op_sel:[0,0,0] op_sel_hi:[0,1,0]
	v_fma_mix_f32 v85, v85, v64, v76 op_sel:[0,1,0] op_sel_hi:[0,1,0]
	v_add_f32_dpp v73, v73, v73 row_half_mirror row_mask:0xf bank_mask:0xf bound_ctrl:1
	v_fma_mix_f32 v86, v86, v65, v77 op_sel:[0,0,0] op_sel_hi:[0,1,0]
	v_fma_mix_f32 v87, v87, v65, v78 op_sel:[0,1,0] op_sel_hi:[0,1,0]
	v_add_f32_dpp v73, v73, v73 row_mirror row_mask:0xf bank_mask:0xf bound_ctrl:1
	v_fma_mix_f32 v84, -v73, v68, v84 op_sel:[0,0,0] op_sel_hi:[0,1,0]
	v_fma_mix_f32 v85, -v73, v68, v85 op_sel:[0,1,0] op_sel_hi:[0,1,0]
	v_fma_mix_f32 v86, -v73, v69, v86 op_sel:[0,0,0] op_sel_hi:[0,1,0]
	v_fma_mix_f32 v87, -v73, v69, v87 op_sel:[0,1,0] op_sel_hi:[0,1,0]
	v_fma_mix_f32 v64, v84, v54, 0 op_sel:[0,0,0] op_sel_hi:[0,1,0]
	v_fma_mix_f32 v57, v84, v58, 0 op_sel:[0,0,0] op_sel_hi:[0,1,0]
	v_fma_mix_f32 v64, v85, v54, v64 op_sel:[0,1,0] op_sel_hi:[0,1,0]
	v_fma_mix_f32 v57, v85, v58, v57 op_sel:[0,1,0] op_sel_hi:[0,1,0]
	v_fma_mix_f32 v64, v86, v55, v64 op_sel:[0,0,0] op_sel_hi:[0,1,0]
	v_fma_mix_f32 v57, v86, v59, v57 op_sel:[0,0,0] op_sel_hi:[0,1,0]
	v_fma_mix_f32 v64, v87, v55, v64 op_sel:[0,1,0] op_sel_hi:[0,1,0]
	v_fma_mix_f32 v57, v87, v59, v57 op_sel:[0,1,0] op_sel_hi:[0,1,0]
	v_fma_mix_f32 v66, v93, v62, 0 op_sel:[0,0,0] op_sel_hi:[1,1,0]
	v_fma_mix_f32 v67, v93, v62, 0 op_sel:[0,1,0] op_sel_hi:[1,1,0]
	v_add_f32_dpp v64, v64, v64 quad_perm:[1,0,3,2] row_mask:0xf bank_mask:0xf bound_ctrl:1
	v_fma_mix_f32 v68, v93, v63, 0 op_sel:[0,0,0] op_sel_hi:[1,1,0]
	v_fma_mix_f32 v69, v93, v63, 0 op_sel:[0,1,0] op_sel_hi:[1,1,0]
	v_add_f32_dpp v64, v64, v64 quad_perm:[2,3,0,1] row_mask:0xf bank_mask:0xf bound_ctrl:1
	v_fma_mix_f32 v84, v84, v52, v66 op_sel:[0,0,0] op_sel_hi:[0,1,0]
	v_fma_mix_f32 v85, v85, v52, v67 op_sel:[0,1,0] op_sel_hi:[0,1,0]
	v_add_f32_dpp v64, v64, v64 row_half_mirror row_mask:0xf bank_mask:0xf bound_ctrl:1
	v_fma_mix_f32 v86, v86, v53, v68 op_sel:[0,0,0] op_sel_hi:[0,1,0]
	v_fma_mix_f32 v87, v87, v53, v69 op_sel:[0,1,0] op_sel_hi:[0,1,0]
	v_add_f32_dpp v64, v64, v64 row_mirror row_mask:0xf bank_mask:0xf bound_ctrl:1
	v_fma_mix_f32 v84, -v64, v60, v84 op_sel:[0,0,0] op_sel_hi:[0,1,0]
	v_fma_mix_f32 v85, -v64, v60, v85 op_sel:[0,1,0] op_sel_hi:[0,1,0]
	v_fma_mix_f32 v86, -v64, v61, v86 op_sel:[0,0,0] op_sel_hi:[0,1,0]
	v_fma_mix_f32 v87, -v64, v61, v87 op_sel:[0,1,0] op_sel_hi:[0,1,0]
	v_fma_mix_f32 v53, v84, v46, 0 op_sel:[0,0,0] op_sel_hi:[0,1,0]
	v_fma_mix_f32 v59, v84, v40, 0 op_sel:[0,0,0] op_sel_hi:[0,1,0]
	v_fma_mix_f32 v53, v85, v46, v53 op_sel:[0,1,0] op_sel_hi:[0,1,0]
	v_fma_mix_f32 v40, v85, v40, v59 op_sel:[0,1,0] op_sel_hi:[0,1,0]
	v_fma_mix_f32 v53, v86, v47, v53 op_sel:[0,0,0] op_sel_hi:[0,1,0]
	v_fma_mix_f32 v40, v86, v41, v40 op_sel:[0,0,0] op_sel_hi:[0,1,0]
	v_fma_mix_f32 v53, v87, v47, v53 op_sel:[0,1,0] op_sel_hi:[0,1,0]
	v_fma_mix_f32 v40, v87, v41, v40 op_sel:[0,1,0] op_sel_hi:[0,1,0]
	v_fma_mix_f32 v55, v93, v50, 0 op_sel:[1,0,0] op_sel_hi:[1,1,0]
	v_fma_mix_f32 v58, v93, v50, 0 op_sel:[1,1,0] op_sel_hi:[1,1,0]
	v_add_f32_dpp v53, v53, v53 quad_perm:[1,0,3,2] row_mask:0xf bank_mask:0xf bound_ctrl:1
	v_fma_mix_f32 v59, v93, v51, 0 op_sel:[1,0,0] op_sel_hi:[1,1,0]
	v_fma_mix_f32 v60, v93, v51, 0 op_sel:[1,1,0] op_sel_hi:[1,1,0]
	v_add_f32_dpp v53, v53, v53 quad_perm:[2,3,0,1] row_mask:0xf bank_mask:0xf bound_ctrl:1
	v_fma_mix_f32 v84, v84, v44, v55 op_sel:[0,0,0] op_sel_hi:[0,1,0]
	v_fma_mix_f32 v85, v85, v44, v58 op_sel:[0,1,0] op_sel_hi:[0,1,0]
	v_add_f32_dpp v53, v53, v53 row_half_mirror row_mask:0xf bank_mask:0xf bound_ctrl:1
	v_fma_mix_f32 v86, v86, v45, v59 op_sel:[0,0,0] op_sel_hi:[0,1,0]
	v_fma_mix_f32 v87, v87, v45, v60 op_sel:[0,1,0] op_sel_hi:[0,1,0]
	v_add_f32_dpp v53, v53, v53 row_mirror row_mask:0xf bank_mask:0xf bound_ctrl:1
	v_fma_mix_f32 v84, -v53, v48, v84 op_sel:[0,0,0] op_sel_hi:[0,1,0]
	v_fma_mix_f32 v85, -v53, v48, v85 op_sel:[0,1,0] op_sel_hi:[0,1,0]
	v_fma_mix_f32 v86, -v53, v49, v86 op_sel:[0,0,0] op_sel_hi:[0,1,0]
	v_fma_mix_f32 v87, -v53, v49, v87 op_sel:[0,1,0] op_sel_hi:[0,1,0]
	v_fma_mix_f32 v41, v84, v42, 0 op_sel:[0,0,0] op_sel_hi:[0,1,0]
	v_add_u32_e32 v173, 10, v193
	v_fma_mix_f32 v41, v85, v42, v41 op_sel:[0,1,0] op_sel_hi:[0,1,0]
	ds_write_b32 v172, v173 offset:49216
	v_fma_mix_f32 v41, v86, v43, v41 op_sel:[0,0,0] op_sel_hi:[0,1,0]
	v_cndmask_b32_e64 v187, v57, v56, s[38:39]
	v_fma_mix_f32 v41, v87, v43, v41 op_sel:[0,1,0] op_sel_hi:[0,1,0]
	v_cndmask_b32_e64 v188, v56, v57, s[38:39]
	v_cndmask_b32_e64 v189, v41, v40, s[38:39]
	v_cndmask_b32_e64 v190, v40, v41, s[38:39]
	s_waitcnt lgkmcnt(1)
	v_fma_mix_f32 v98, v84, v6, 0 op_sel:[0,0,0] op_sel_hi:[0,1,0]
	v_fma_mix_f32 v98, v85, v6, v98 op_sel:[0,1,0] op_sel_hi:[0,1,0]
	v_add_f32_dpp v188, v188, v187 quad_perm:[1,0,3,2] row_mask:0xf bank_mask:0xf bound_ctrl:1
	v_add_f32_dpp v189, v190, v189 quad_perm:[1,0,3,2] row_mask:0xf bank_mask:0xf bound_ctrl:1
	v_fma_mix_f32 v98, v86, v7, v98 op_sel:[0,0,0] op_sel_hi:[0,1,0]
	v_fma_mix_f32 v98, v87, v7, v98 op_sel:[0,1,0] op_sel_hi:[0,1,0]
	v_cndmask_b32_e64 v191, v189, v188, s[40:41]
	v_cndmask_b32_e64 v192, v188, v189, s[40:41]
	v_fma_mix_f32 v100, v88, v14, 0 op_sel:[0,0,0] op_sel_hi:[1,1,0]
	v_fma_mix_f32 v101, v88, v14, 0 op_sel:[0,1,0] op_sel_hi:[1,1,0]
	v_add_f32_dpp v192, v192, v191 quad_perm:[2,3,0,1] row_mask:0xf bank_mask:0xf bound_ctrl:1
	v_add_f32_dpp v98, v98, v98 quad_perm:[1,0,3,2] row_mask:0xf bank_mask:0xf bound_ctrl:1
	v_fma_mix_f32 v102, v88, v15, 0 op_sel:[0,0,0] op_sel_hi:[1,1,0]
	v_add_f32_dpp v192, v192, v192 row_ror:4 row_mask:0xf bank_mask:0xf bound_ctrl:1
	v_fma_mix_f32 v103, v88, v15, 0 op_sel:[0,1,0] op_sel_hi:[1,1,0]
	v_add_f32_dpp v98, v98, v98 quad_perm:[2,3,0,1] row_mask:0xf bank_mask:0xf bound_ctrl:1
	v_add_f32_dpp v192, v192, v192 row_ror:8 row_mask:0xf bank_mask:0xf bound_ctrl:1
	v_cvt_f16_f32_e32 v192, v192
	global_store_short v83, v192, s[36:37]
	s_add_u32 s36, s36, s44
	s_addc_u32 s37, s37, s45
	s_cmp_gt_i32 s35, 11
	s_cbranch_scc0 .Lc_poll_B4
.Lc_ret_B4:
	ds_read_b128 v[56:59], v194 offset:35840
	ds_read_b128 v[72:75], v194 offset:33792
	ds_read_b128 v[64:67], v194 offset:34048
	ds_read_b128 v[76:79], v194 offset:34816
	ds_read_b128 v[68:71], v194 offset:35072
	ds_read_b128 v[40:43], v194 offset:36096
	ds_read_b128 v[52:55], v194 offset:34304
	ds_read_b128 v[44:47], v194 offset:34560
	ds_read_b128 v[60:63], v194 offset:35328
	ds_read_b128 v[48:51], v194 offset:35584
	ds_read_b64 v[92:93], v195 offset:36352
	v_fma_mix_f32 v84, v84, v4, v100 op_sel:[0,0,0] op_sel_hi:[0,1,0]
	v_fma_mix_f32 v85, v85, v4, v101 op_sel:[0,1,0] op_sel_hi:[0,1,0]
	v_add_f32_dpp v98, v98, v98 row_half_mirror row_mask:0xf bank_mask:0xf bound_ctrl:1
	v_fma_mix_f32 v86, v86, v5, v102 op_sel:[0,0,0] op_sel_hi:[0,1,0]
	v_fma_mix_f32 v87, v87, v5, v103 op_sel:[0,1,0] op_sel_hi:[0,1,0]
	v_add_f32_dpp v98, v98, v98 row_mirror row_mask:0xf bank_mask:0xf bound_ctrl:1
	v_fma_mix_f32 v84, -v98, v12, v84 op_sel:[0,0,0] op_sel_hi:[0,1,0]
	v_fma_mix_f32 v85, -v98, v12, v85 op_sel:[0,1,0] op_sel_hi:[0,1,0]
	v_fma_mix_f32 v86, -v98, v13, v86 op_sel:[0,0,0] op_sel_hi:[0,1,0]
	v_fma_mix_f32 v87, -v98, v13, v87 op_sel:[0,1,0] op_sel_hi:[0,1,0]
	v_fma_mix_f32 v99, v84, v10, 0 op_sel:[0,0,0] op_sel_hi:[0,1,0]
	v_fma_mix_f32 v96, v84, v0, 0 op_sel:[0,0,0] op_sel_hi:[0,1,0]
	v_fma_mix_f32 v99, v85, v10, v99 op_sel:[0,1,0] op_sel_hi:[0,1,0]
	v_fma_mix_f32 v96, v85, v0, v96 op_sel:[0,1,0] op_sel_hi:[0,1,0]
	v_fma_mix_f32 v99, v86, v11, v99 op_sel:[0,0,0] op_sel_hi:[0,1,0]
	v_fma_mix_f32 v96, v86, v1, v96 op_sel:[0,0,0] op_sel_hi:[0,1,0]
	v_fma_mix_f32 v99, v87, v11, v99 op_sel:[0,1,0] op_sel_hi:[0,1,0]
	v_fma_mix_f32 v96, v87, v1, v96 op_sel:[0,1,0] op_sel_hi:[0,1,0]
	v_fma_mix_f32 v101, v88, v18, 0 op_sel:[1,0,0] op_sel_hi:[1,1,0]
	v_fma_mix_f32 v102, v88, v18, 0 op_sel:[1,1,0] op_sel_hi:[1,1,0]
	v_add_f32_dpp v99, v99, v99 quad_perm:[1,0,3,2] row_mask:0xf bank_mask:0xf bound_ctrl:1
	v_fma_mix_f32 v103, v88, v19, 0 op_sel:[1,0,0] op_sel_hi:[1,1,0]
	v_fma_mix_f32 v104, v88, v19, 0 op_sel:[1,1,0] op_sel_hi:[1,1,0]
	v_add_f32_dpp v99, v99, v99 quad_perm:[2,3,0,1] row_mask:0xf bank_mask:0xf bound_ctrl:1
	v_fma_mix_f32 v84, v84, v8, v101 op_sel:[0,0,0] op_sel_hi:[0,1,0]
	v_fma_mix_f32 v85, v85, v8, v102 op_sel:[0,1,0] op_sel_hi:[0,1,0]
	v_add_f32_dpp v99, v99, v99 row_half_mirror row_mask:0xf bank_mask:0xf bound_ctrl:1
	v_fma_mix_f32 v86, v86, v9, v103 op_sel:[0,0,0] op_sel_hi:[0,1,0]
	v_fma_mix_f32 v87, v87, v9, v104 op_sel:[0,1,0] op_sel_hi:[0,1,0]
	v_add_f32_dpp v99, v99, v99 row_mirror row_mask:0xf bank_mask:0xf bound_ctrl:1
	v_fma_mix_f32 v84, -v99, v16, v84 op_sel:[0,0,0] op_sel_hi:[0,1,0]
	v_fma_mix_f32 v85, -v99, v16, v85 op_sel:[0,1,0] op_sel_hi:[0,1,0]
	v_fma_mix_f32 v86, -v99, v17, v86 op_sel:[0,0,0] op_sel_hi:[0,1,0]
	v_fma_mix_f32 v87, -v99, v17, v87 op_sel:[0,1,0] op_sel_hi:[0,1,0]
	v_fma_mix_f32 v100, v84, v26, 0 op_sel:[0,0,0] op_sel_hi:[0,1,0]
	v_fma_mix_f32 v97, v84, v2, 0 op_sel:[0,0,0] op_sel_hi:[0,1,0]
	v_fma_mix_f32 v100, v85, v26, v100 op_sel:[0,1,0] op_sel_hi:[0,1,0]
	v_fma_mix_f32 v97, v85, v2, v97 op_sel:[0,1,0] op_sel_hi:[0,1,0]
	v_fma_mix_f32 v100, v86, v27, v100 op_sel:[0,0,0] op_sel_hi:[0,1,0]
	v_fma_mix_f32 v97, v86, v3, v97 op_sel:[0,0,0] op_sel_hi:[0,1,0]
	v_fma_mix_f32 v100, v87, v27, v100 op_sel:[0,1,0] op_sel_hi:[0,1,0]
	v_fma_mix_f32 v97, v87, v3, v97 op_sel:[0,1,0] op_sel_hi:[0,1,0]
	v_fma_mix_f32 v102, v89, v34, 0 op_sel:[0,0,0] op_sel_hi:[1,1,0]
	v_fma_mix_f32 v103, v89, v34, 0 op_sel:[0,1,0] op_sel_hi:[1,1,0]
	v_add_f32_dpp v100, v100, v100 quad_perm:[1,0,3,2] row_mask:0xf bank_mask:0xf bound_ctrl:1
	v_fma_mix_f32 v104, v89, v35, 0 op_sel:[0,0,0] op_sel_hi:[1,1,0]
	v_fma_mix_f32 v105, v89, v35, 0 op_sel:[0,1,0] op_sel_hi:[1,1,0]
	v_add_f32_dpp v100, v100, v100 quad_perm:[2,3,0,1] row_mask:0xf bank_mask:0xf bound_ctrl:1
	v_fma_mix_f32 v84, v84, v24, v102 op_sel:[0,0,0] op_sel_hi:[0,1,0]
	v_fma_mix_f32 v85, v85, v24, v103 op_sel:[0,1,0] op_sel_hi:[0,1,0]
	v_add_f32_dpp v100, v100, v100 row_half_mirror row_mask:0xf bank_mask:0xf bound_ctrl:1
	v_fma_mix_f32 v86, v86, v25, v104 op_sel:[0,0,0] op_sel_hi:[0,1,0]
	v_fma_mix_f32 v87, v87, v25, v105 op_sel:[0,1,0] op_sel_hi:[0,1,0]
	v_add_f32_dpp v100, v100, v100 row_mirror row_mask:0xf bank_mask:0xf bound_ctrl:1
	v_fma_mix_f32 v84, -v100, v32, v84 op_sel:[0,0,0] op_sel_hi:[0,1,0]
	v_fma_mix_f32 v85, -v100, v32, v85 op_sel:[0,1,0] op_sel_hi:[0,1,0]
	v_fma_mix_f32 v86, -v100, v33, v86 op_sel:[0,0,0] op_sel_hi:[0,1,0]
	v_fma_mix_f32 v87, -v100, v33, v87 op_sel:[0,1,0] op_sel_hi:[0,1,0]
	v_fma_mix_f32 v101, v84, v30, 0 op_sel:[0,0,0] op_sel_hi:[0,1,0]
	v_fma_mix_f32 v98, v84, v20, 0 op_sel:[0,0,0] op_sel_hi:[0,1,0]
	v_fma_mix_f32 v101, v85, v30, v101 op_sel:[0,1,0] op_sel_hi:[0,1,0]
	v_fma_mix_f32 v98, v85, v20, v98 op_sel:[0,1,0] op_sel_hi:[0,1,0]
	v_fma_mix_f32 v101, v86, v31, v101 op_sel:[0,0,0] op_sel_hi:[0,1,0]
	v_fma_mix_f32 v98, v86, v21, v98 op_sel:[0,0,0] op_sel_hi:[0,1,0]
	v_fma_mix_f32 v101, v87, v31, v101 op_sel:[0,1,0] op_sel_hi:[0,1,0]
	v_fma_mix_f32 v98, v87, v21, v98 op_sel:[0,1,0] op_sel_hi:[0,1,0]
	v_fma_mix_f32 v103, v89, v38, 0 op_sel:[1,0,0] op_sel_hi:[1,1,0]
	v_fma_mix_f32 v104, v89, v38, 0 op_sel:[1,1,0] op_sel_hi:[1,1,0]
	v_add_f32_dpp v101, v101, v101 quad_perm:[1,0,3,2] row_mask:0xf bank_mask:0xf bound_ctrl:1
	v_fma_mix_f32 v105, v89, v39, 0 op_sel:[1,0,0] op_sel_hi:[1,1,0]
	v_fma_mix_f32 v119, v89, v39, 0 op_sel:[1,1,0] op_sel_hi:[1,1,0]
	v_add_f32_dpp v101, v101, v101 quad_perm:[2,3,0,1] row_mask:0xf bank_mask:0xf bound_ctrl:1
	v_fma_mix_f32 v84, v84, v28, v103 op_sel:[0,0,0] op_sel_hi:[0,1,0]
	v_fma_mix_f32 v85, v85, v28, v104 op_sel:[0,1,0] op_sel_hi:[0,1,0]
	v_add_f32_dpp v101, v101, v101 row_half_mirror row_mask:0xf bank_mask:0xf bound_ctrl:1
	v_fma_mix_f32 v86, v86, v29, v105 op_sel:[0,0,0] op_sel_hi:[0,1,0]
	v_fma_mix_f32 v87, v87, v29, v119 op_sel:[0,1,0] op_sel_hi:[0,1,0]
	v_add_f32_dpp v101, v101, v101 row_mirror row_mask:0xf bank_mask:0xf bound_ctrl:1
	v_fma_mix_f32 v84, -v101, v36, v84 op_sel:[0,0,0] op_sel_hi:[0,1,0]
	v_fma_mix_f32 v85, -v101, v36, v85 op_sel:[0,1,0] op_sel_hi:[0,1,0]
	v_fma_mix_f32 v86, -v101, v37, v86 op_sel:[0,0,0] op_sel_hi:[0,1,0]
	v_fma_mix_f32 v87, -v101, v37, v87 op_sel:[0,1,0] op_sel_hi:[0,1,0]
	v_fma_mix_f32 v99, v84, v22, 0 op_sel:[0,0,0] op_sel_hi:[0,1,0]
	v_add_u32_e32 v173, 11, v193
	v_fma_mix_f32 v99, v85, v22, v99 op_sel:[0,1,0] op_sel_hi:[0,1,0]
	ds_write_b32 v172, v173 offset:49216
	v_fma_mix_f32 v99, v86, v23, v99 op_sel:[0,0,0] op_sel_hi:[0,1,0]
	v_cndmask_b32_e64 v187, v97, v96, s[38:39]
	v_fma_mix_f32 v99, v87, v23, v99 op_sel:[0,1,0] op_sel_hi:[0,1,0]
	v_cndmask_b32_e64 v188, v96, v97, s[38:39]
	v_cndmask_b32_e64 v189, v99, v98, s[38:39]
	v_cndmask_b32_e64 v190, v98, v99, s[38:39]
	s_waitcnt lgkmcnt(1)
	v_fma_mix_f32 v98, v84, v74, 0 op_sel:[0,0,0] op_sel_hi:[0,1,0]
	v_fma_mix_f32 v98, v85, v74, v98 op_sel:[0,1,0] op_sel_hi:[0,1,0]
	v_add_f32_dpp v188, v188, v187 quad_perm:[1,0,3,2] row_mask:0xf bank_mask:0xf bound_ctrl:1
	v_add_f32_dpp v189, v190, v189 quad_perm:[1,0,3,2] row_mask:0xf bank_mask:0xf bound_ctrl:1
	v_fma_mix_f32 v98, v86, v75, v98 op_sel:[0,0,0] op_sel_hi:[0,1,0]
	v_fma_mix_f32 v98, v87, v75, v98 op_sel:[0,1,0] op_sel_hi:[0,1,0]
	v_cndmask_b32_e64 v191, v189, v188, s[40:41]
	v_cndmask_b32_e64 v192, v188, v189, s[40:41]
	v_fma_mix_f32 v100, v92, v78, 0 op_sel:[0,0,0] op_sel_hi:[1,1,0]
	v_fma_mix_f32 v101, v92, v78, 0 op_sel:[0,1,0] op_sel_hi:[1,1,0]
	v_add_f32_dpp v192, v192, v191 quad_perm:[2,3,0,1] row_mask:0xf bank_mask:0xf bound_ctrl:1
	v_add_f32_dpp v98, v98, v98 quad_perm:[1,0,3,2] row_mask:0xf bank_mask:0xf bound_ctrl:1
	v_fma_mix_f32 v102, v92, v79, 0 op_sel:[0,0,0] op_sel_hi:[1,1,0]
	v_add_f32_dpp v192, v192, v192 row_ror:4 row_mask:0xf bank_mask:0xf bound_ctrl:1
	v_fma_mix_f32 v103, v92, v79, 0 op_sel:[0,1,0] op_sel_hi:[1,1,0]
	v_add_f32_dpp v98, v98, v98 quad_perm:[2,3,0,1] row_mask:0xf bank_mask:0xf bound_ctrl:1
	v_add_f32_dpp v192, v192, v192 row_ror:8 row_mask:0xf bank_mask:0xf bound_ctrl:1
	v_cvt_f16_f32_e32 v192, v192
	global_store_short v83, v192, s[36:37]
	s_add_u32 s36, s36, s44
	s_addc_u32 s37, s37, s45
	s_cmp_gt_i32 s35, 12
	s_cbranch_scc0 .Lc_poll_A5
.Lc_ret_A5:
	ds_read_b128 v[0:3], v194 offset:38912
	ds_read_b128 v[4:7], v194 offset:36864
	ds_read_b128 v[8:11], v194 offset:37120
	ds_read_b128 v[12:15], v194 offset:37888
	ds_read_b128 v[16:19], v194 offset:38144
	ds_read_b128 v[20:23], v194 offset:39168
	ds_read_b128 v[24:27], v194 offset:37376
	ds_read_b128 v[28:31], v194 offset:37632
	ds_read_b128 v[32:35], v194 offset:38400
	ds_read_b128 v[36:39], v194 offset:38656
	ds_read_b64 v[88:89], v195 offset:39424
	v_fma_mix_f32 v84, v84, v72, v100 op_sel:[0,0,0] op_sel_hi:[0,1,0]
	v_fma_mix_f32 v85, v85, v72, v101 op_sel:[0,1,0] op_sel_hi:[0,1,0]
	v_add_f32_dpp v98, v98, v98 row_half_mirror row_mask:0xf bank_mask:0xf bound_ctrl:1
	v_fma_mix_f32 v86, v86, v73, v102 op_sel:[0,0,0] op_sel_hi:[0,1,0]
	v_fma_mix_f32 v87, v87, v73, v103 op_sel:[0,1,0] op_sel_hi:[0,1,0]
	v_add_f32_dpp v98, v98, v98 row_mirror row_mask:0xf bank_mask:0xf bound_ctrl:1
	v_fma_mix_f32 v84, -v98, v76, v84 op_sel:[0,0,0] op_sel_hi:[0,1,0]
	v_fma_mix_f32 v85, -v98, v76, v85 op_sel:[0,1,0] op_sel_hi:[0,1,0]
	v_fma_mix_f32 v86, -v98, v77, v86 op_sel:[0,0,0] op_sel_hi:[0,1,0]
	v_fma_mix_f32 v87, -v98, v77, v87 op_sel:[0,1,0] op_sel_hi:[0,1,0]
	v_fma_mix_f32 v73, v84, v66, 0 op_sel:[0,0,0] op_sel_hi:[0,1,0]
	v_fma_mix_f32 v97, v84, v56, 0 op_sel:[0,0,0] op_sel_hi:[0,1,0]
	v_fma_mix_f32 v73, v85, v66, v73 op_sel:[0,1,0] op_sel_hi:[0,1,0]
	v_fma_mix_f32 v56, v85, v56, v97 op_sel:[0,1,0] op_sel_hi:[0,1,0]
	v_fma_mix_f32 v73, v86, v67, v73 op_sel:[0,0,0] op_sel_hi:[0,1,0]
	v_fma_mix_f32 v56, v86, v57, v56 op_sel:[0,0,0] op_sel_hi:[0,1,0]
	v_fma_mix_f32 v73, v87, v67, v73 op_sel:[0,1,0] op_sel_hi:[0,1,0]
	v_fma_mix_f32 v56, v87, v57, v56 op_sel:[0,1,0] op_sel_hi:[0,1,0]
	v_fma_mix_f32 v75, v92, v70, 0 op_sel:[1,0,0] op_sel_hi:[1,1,0]
	v_fma_mix_f32 v76, v92, v70, 0 op_sel:[1,1,0] op_sel_hi:[1,1,0]
	v_add_f32_dpp v73, v73, v73 quad_perm:[1,0,3,2] row_mask:0xf bank_mask:0xf bound_ctrl:1
	v_fma_mix_f32 v77, v92, v71, 0 op_sel:[1,0,0] op_sel_hi:[1,1,0]
	v_fma_mix_f32 v78, v92, v71, 0 op_sel:[1,1,0] op_sel_hi:[1,1,0]
	v_add_f32_dpp v73, v73, v73 quad_perm:[2,3,0,1] row_mask:0xf bank_mask:0xf bound_ctrl:1
	v_fma_mix_f32 v84, v84, v64, v75 op_sel:[0,0,0] op_sel_hi:[0,1,0]
	v_fma_mix_f32 v85, v85, v64, v76 op_sel:[0,1,0] op_sel_hi:[0,1,0]
	v_add_f32_dpp v73, v73, v73 row_half_mirror row_mask:0xf bank_mask:0xf bound_ctrl:1
	v_fma_mix_f32 v86, v86, v65, v77 op_sel:[0,0,0] op_sel_hi:[0,1,0]
	v_fma_mix_f32 v87, v87, v65, v78 op_sel:[0,1,0] op_sel_hi:[0,1,0]
	v_add_f32_dpp v73, v73, v73 row_mirror row_mask:0xf bank_mask:0xf bound_ctrl:1
	v_fma_mix_f32 v84, -v73, v68, v84 op_sel:[0,0,0] op_sel_hi:[0,1,0]
	v_fma_mix_f32 v85, -v73, v68, v85 op_sel:[0,1,0] op_sel_hi:[0,1,0]
	v_fma_mix_f32 v86, -v73, v69, v86 op_sel:[0,0,0] op_sel_hi:[0,1,0]
	v_fma_mix_f32 v87, -v73, v69, v87 op_sel:[0,1,0] op_sel_hi:[0,1,0]
	v_fma_mix_f32 v64, v84, v54, 0 op_sel:[0,0,0] op_sel_hi:[0,1,0]
	v_fma_mix_f32 v57, v84, v58, 0 op_sel:[0,0,0] op_sel_hi:[0,1,0]
	v_fma_mix_f32 v64, v85, v54, v64 op_sel:[0,1,0] op_sel_hi:[0,1,0]
	v_fma_mix_f32 v57, v85, v58, v57 op_sel:[0,1,0] op_sel_hi:[0,1,0]
	v_fma_mix_f32 v64, v86, v55, v64 op_sel:[0,0,0] op_sel_hi:[0,1,0]
	v_fma_mix_f32 v57, v86, v59, v57 op_sel:[0,0,0] op_sel_hi:[0,1,0]
	v_fma_mix_f32 v64, v87, v55, v64 op_sel:[0,1,0] op_sel_hi:[0,1,0]
	v_fma_mix_f32 v57, v87, v59, v57 op_sel:[0,1,0] op_sel_hi:[0,1,0]
	v_fma_mix_f32 v66, v93, v62, 0 op_sel:[0,0,0] op_sel_hi:[1,1,0]
	v_fma_mix_f32 v67, v93, v62, 0 op_sel:[0,1,0] op_sel_hi:[1,1,0]
	v_add_f32_dpp v64, v64, v64 quad_perm:[1,0,3,2] row_mask:0xf bank_mask:0xf bound_ctrl:1
	v_fma_mix_f32 v68, v93, v63, 0 op_sel:[0,0,0] op_sel_hi:[1,1,0]
	v_fma_mix_f32 v69, v93, v63, 0 op_sel:[0,1,0] op_sel_hi:[1,1,0]
	v_add_f32_dpp v64, v64, v64 quad_perm:[2,3,0,1] row_mask:0xf bank_mask:0xf bound_ctrl:1
	v_fma_mix_f32 v84, v84, v52, v66 op_sel:[0,0,0] op_sel_hi:[0,1,0]
	v_fma_mix_f32 v85, v85, v52, v67 op_sel:[0,1,0] op_sel_hi:[0,1,0]
	v_add_f32_dpp v64, v64, v64 row_half_mirror row_mask:0xf bank_mask:0xf bound_ctrl:1
	v_fma_mix_f32 v86, v86, v53, v68 op_sel:[0,0,0] op_sel_hi:[0,1,0]
	v_fma_mix_f32 v87, v87, v53, v69 op_sel:[0,1,0] op_sel_hi:[0,1,0]
	v_add_f32_dpp v64, v64, v64 row_mirror row_mask:0xf bank_mask:0xf bound_ctrl:1
	v_fma_mix_f32 v84, -v64, v60, v84 op_sel:[0,0,0] op_sel_hi:[0,1,0]
	v_fma_mix_f32 v85, -v64, v60, v85 op_sel:[0,1,0] op_sel_hi:[0,1,0]
	v_fma_mix_f32 v86, -v64, v61, v86 op_sel:[0,0,0] op_sel_hi:[0,1,0]
	v_fma_mix_f32 v87, -v64, v61, v87 op_sel:[0,1,0] op_sel_hi:[0,1,0]
	v_fma_mix_f32 v53, v84, v46, 0 op_sel:[0,0,0] op_sel_hi:[0,1,0]
	v_fma_mix_f32 v59, v84, v40, 0 op_sel:[0,0,0] op_sel_hi:[0,1,0]
	v_fma_mix_f32 v53, v85, v46, v53 op_sel:[0,1,0] op_sel_hi:[0,1,0]
	v_fma_mix_f32 v40, v85, v40, v59 op_sel:[0,1,0] op_sel_hi:[0,1,0]
	v_fma_mix_f32 v53, v86, v47, v53 op_sel:[0,0,0] op_sel_hi:[0,1,0]
	v_fma_mix_f32 v40, v86, v41, v40 op_sel:[0,0,0] op_sel_hi:[0,1,0]
	v_fma_mix_f32 v53, v87, v47, v53 op_sel:[0,1,0] op_sel_hi:[0,1,0]
	v_fma_mix_f32 v40, v87, v41, v40 op_sel:[0,1,0] op_sel_hi:[0,1,0]
	v_fma_mix_f32 v55, v93, v50, 0 op_sel:[1,0,0] op_sel_hi:[1,1,0]
	v_fma_mix_f32 v58, v93, v50, 0 op_sel:[1,1,0] op_sel_hi:[1,1,0]
	v_add_f32_dpp v53, v53, v53 quad_perm:[1,0,3,2] row_mask:0xf bank_mask:0xf bound_ctrl:1
	v_fma_mix_f32 v59, v93, v51, 0 op_sel:[1,0,0] op_sel_hi:[1,1,0]
	v_fma_mix_f32 v60, v93, v51, 0 op_sel:[1,1,0] op_sel_hi:[1,1,0]
	v_add_f32_dpp v53, v53, v53 quad_perm:[2,3,0,1] row_mask:0xf bank_mask:0xf bound_ctrl:1
	v_fma_mix_f32 v84, v84, v44, v55 op_sel:[0,0,0] op_sel_hi:[0,1,0]
	v_fma_mix_f32 v85, v85, v44, v58 op_sel:[0,1,0] op_sel_hi:[0,1,0]
	v_add_f32_dpp v53, v53, v53 row_half_mirror row_mask:0xf bank_mask:0xf bound_ctrl:1
	v_fma_mix_f32 v86, v86, v45, v59 op_sel:[0,0,0] op_sel_hi:[0,1,0]
	v_fma_mix_f32 v87, v87, v45, v60 op_sel:[0,1,0] op_sel_hi:[0,1,0]
	v_add_f32_dpp v53, v53, v53 row_mirror row_mask:0xf bank_mask:0xf bound_ctrl:1
	v_fma_mix_f32 v84, -v53, v48, v84 op_sel:[0,0,0] op_sel_hi:[0,1,0]
	v_fma_mix_f32 v85, -v53, v48, v85 op_sel:[0,1,0] op_sel_hi:[0,1,0]
	v_fma_mix_f32 v86, -v53, v49, v86 op_sel:[0,0,0] op_sel_hi:[0,1,0]
	v_fma_mix_f32 v87, -v53, v49, v87 op_sel:[0,1,0] op_sel_hi:[0,1,0]
	v_fma_mix_f32 v41, v84, v42, 0 op_sel:[0,0,0] op_sel_hi:[0,1,0]
	v_add_u32_e32 v173, 12, v193
	v_fma_mix_f32 v41, v85, v42, v41 op_sel:[0,1,0] op_sel_hi:[0,1,0]
	ds_write_b32 v172, v173 offset:49216
	v_fma_mix_f32 v41, v86, v43, v41 op_sel:[0,0,0] op_sel_hi:[0,1,0]
	v_cndmask_b32_e64 v187, v57, v56, s[38:39]
	v_fma_mix_f32 v41, v87, v43, v41 op_sel:[0,1,0] op_sel_hi:[0,1,0]
	v_cndmask_b32_e64 v188, v56, v57, s[38:39]
	v_cndmask_b32_e64 v189, v41, v40, s[38:39]
	v_cndmask_b32_e64 v190, v40, v41, s[38:39]
	s_waitcnt lgkmcnt(1)
	v_fma_mix_f32 v98, v84, v6, 0 op_sel:[0,0,0] op_sel_hi:[0,1,0]
	v_fma_mix_f32 v98, v85, v6, v98 op_sel:[0,1,0] op_sel_hi:[0,1,0]
	v_add_f32_dpp v188, v188, v187 quad_perm:[1,0,3,2] row_mask:0xf bank_mask:0xf bound_ctrl:1
	v_add_f32_dpp v189, v190, v189 quad_perm:[1,0,3,2] row_mask:0xf bank_mask:0xf bound_ctrl:1
	v_fma_mix_f32 v98, v86, v7, v98 op_sel:[0,0,0] op_sel_hi:[0,1,0]
	v_fma_mix_f32 v98, v87, v7, v98 op_sel:[0,1,0] op_sel_hi:[0,1,0]
	v_cndmask_b32_e64 v191, v189, v188, s[40:41]
	v_cndmask_b32_e64 v192, v188, v189, s[40:41]
	v_fma_mix_f32 v100, v88, v14, 0 op_sel:[0,0,0] op_sel_hi:[1,1,0]
	v_fma_mix_f32 v101, v88, v14, 0 op_sel:[0,1,0] op_sel_hi:[1,1,0]
	v_add_f32_dpp v192, v192, v191 quad_perm:[2,3,0,1] row_mask:0xf bank_mask:0xf bound_ctrl:1
	v_add_f32_dpp v98, v98, v98 quad_perm:[1,0,3,2] row_mask:0xf bank_mask:0xf bound_ctrl:1
	v_fma_mix_f32 v102, v88, v15, 0 op_sel:[0,0,0] op_sel_hi:[1,1,0]
	v_add_f32_dpp v192, v192, v192 row_ror:4 row_mask:0xf bank_mask:0xf bound_ctrl:1
	v_fma_mix_f32 v103, v88, v15, 0 op_sel:[0,1,0] op_sel_hi:[1,1,0]
	v_add_f32_dpp v98, v98, v98 quad_perm:[2,3,0,1] row_mask:0xf bank_mask:0xf bound_ctrl:1
	v_add_f32_dpp v192, v192, v192 row_ror:8 row_mask:0xf bank_mask:0xf bound_ctrl:1
	v_cvt_f16_f32_e32 v192, v192
	global_store_short v83, v192, s[36:37]
	s_add_u32 s36, s36, s44
	s_addc_u32 s37, s37, s45
	s_cmp_gt_i32 s35, 13
	s_cbranch_scc0 .Lc_poll_B5
.Lc_ret_B5:
	ds_read_b128 v[56:59], v194 offset:41984
	ds_read_b128 v[72:75], v194 offset:39936
	ds_read_b128 v[64:67], v194 offset:40192
	ds_read_b128 v[76:79], v194 offset:40960
	ds_read_b128 v[68:71], v194 offset:41216
	ds_read_b128 v[40:43], v194 offset:42240
	ds_read_b128 v[52:55], v194 offset:40448
	ds_read_b128 v[44:47], v194 offset:40704
	ds_read_b128 v[60:63], v194 offset:41472
	ds_read_b128 v[48:51], v194 offset:41728
	ds_read_b64 v[92:93], v195 offset:42496
	v_fma_mix_f32 v84, v84, v4, v100 op_sel:[0,0,0] op_sel_hi:[0,1,0]
	v_fma_mix_f32 v85, v85, v4, v101 op_sel:[0,1,0] op_sel_hi:[0,1,0]
	v_add_f32_dpp v98, v98, v98 row_half_mirror row_mask:0xf bank_mask:0xf bound_ctrl:1
	v_fma_mix_f32 v86, v86, v5, v102 op_sel:[0,0,0] op_sel_hi:[0,1,0]
	v_fma_mix_f32 v87, v87, v5, v103 op_sel:[0,1,0] op_sel_hi:[0,1,0]
	v_add_f32_dpp v98, v98, v98 row_mirror row_mask:0xf bank_mask:0xf bound_ctrl:1
	v_fma_mix_f32 v84, -v98, v12, v84 op_sel:[0,0,0] op_sel_hi:[0,1,0]
	v_fma_mix_f32 v85, -v98, v12, v85 op_sel:[0,1,0] op_sel_hi:[0,1,0]
	v_fma_mix_f32 v86, -v98, v13, v86 op_sel:[0,0,0] op_sel_hi:[0,1,0]
	v_fma_mix_f32 v87, -v98, v13, v87 op_sel:[0,1,0] op_sel_hi:[0,1,0]
	v_fma_mix_f32 v99, v84, v10, 0 op_sel:[0,0,0] op_sel_hi:[0,1,0]
	v_fma_mix_f32 v96, v84, v0, 0 op_sel:[0,0,0] op_sel_hi:[0,1,0]
	v_fma_mix_f32 v99, v85, v10, v99 op_sel:[0,1,0] op_sel_hi:[0,1,0]
	v_fma_mix_f32 v96, v85, v0, v96 op_sel:[0,1,0] op_sel_hi:[0,1,0]
	v_fma_mix_f32 v99, v86, v11, v99 op_sel:[0,0,0] op_sel_hi:[0,1,0]
	v_fma_mix_f32 v96, v86, v1, v96 op_sel:[0,0,0] op_sel_hi:[0,1,0]
	v_fma_mix_f32 v99, v87, v11, v99 op_sel:[0,1,0] op_sel_hi:[0,1,0]
	v_fma_mix_f32 v96, v87, v1, v96 op_sel:[0,1,0] op_sel_hi:[0,1,0]
	v_fma_mix_f32 v101, v88, v18, 0 op_sel:[1,0,0] op_sel_hi:[1,1,0]
	v_fma_mix_f32 v102, v88, v18, 0 op_sel:[1,1,0] op_sel_hi:[1,1,0]
	v_add_f32_dpp v99, v99, v99 quad_perm:[1,0,3,2] row_mask:0xf bank_mask:0xf bound_ctrl:1
	v_fma_mix_f32 v103, v88, v19, 0 op_sel:[1,0,0] op_sel_hi:[1,1,0]
	v_fma_mix_f32 v104, v88, v19, 0 op_sel:[1,1,0] op_sel_hi:[1,1,0]
	v_add_f32_dpp v99, v99, v99 quad_perm:[2,3,0,1] row_mask:0xf bank_mask:0xf bound_ctrl:1
	v_fma_mix_f32 v84, v84, v8, v101 op_sel:[0,0,0] op_sel_hi:[0,1,0]
	v_fma_mix_f32 v85, v85, v8, v102 op_sel:[0,1,0] op_sel_hi:[0,1,0]
	v_add_f32_dpp v99, v99, v99 row_half_mirror row_mask:0xf bank_mask:0xf bound_ctrl:1
	v_fma_mix_f32 v86, v86, v9, v103 op_sel:[0,0,0] op_sel_hi:[0,1,0]
	v_fma_mix_f32 v87, v87, v9, v104 op_sel:[0,1,0] op_sel_hi:[0,1,0]
	v_add_f32_dpp v99, v99, v99 row_mirror row_mask:0xf bank_mask:0xf bound_ctrl:1
	v_fma_mix_f32 v84, -v99, v16, v84 op_sel:[0,0,0] op_sel_hi:[0,1,0]
	v_fma_mix_f32 v85, -v99, v16, v85 op_sel:[0,1,0] op_sel_hi:[0,1,0]
	v_fma_mix_f32 v86, -v99, v17, v86 op_sel:[0,0,0] op_sel_hi:[0,1,0]
	v_fma_mix_f32 v87, -v99, v17, v87 op_sel:[0,1,0] op_sel_hi:[0,1,0]
	v_fma_mix_f32 v100, v84, v26, 0 op_sel:[0,0,0] op_sel_hi:[0,1,0]
	v_fma_mix_f32 v97, v84, v2, 0 op_sel:[0,0,0] op_sel_hi:[0,1,0]
	v_fma_mix_f32 v100, v85, v26, v100 op_sel:[0,1,0] op_sel_hi:[0,1,0]
	v_fma_mix_f32 v97, v85, v2, v97 op_sel:[0,1,0] op_sel_hi:[0,1,0]
	v_fma_mix_f32 v100, v86, v27, v100 op_sel:[0,0,0] op_sel_hi:[0,1,0]
	v_fma_mix_f32 v97, v86, v3, v97 op_sel:[0,0,0] op_sel_hi:[0,1,0]
	v_fma_mix_f32 v100, v87, v27, v100 op_sel:[0,1,0] op_sel_hi:[0,1,0]
	v_fma_mix_f32 v97, v87, v3, v97 op_sel:[0,1,0] op_sel_hi:[0,1,0]
	v_fma_mix_f32 v102, v89, v34, 0 op_sel:[0,0,0] op_sel_hi:[1,1,0]
	v_fma_mix_f32 v103, v89, v34, 0 op_sel:[0,1,0] op_sel_hi:[1,1,0]
	v_add_f32_dpp v100, v100, v100 quad_perm:[1,0,3,2] row_mask:0xf bank_mask:0xf bound_ctrl:1
	v_fma_mix_f32 v104, v89, v35, 0 op_sel:[0,0,0] op_sel_hi:[1,1,0]
	v_fma_mix_f32 v105, v89, v35, 0 op_sel:[0,1,0] op_sel_hi:[1,1,0]
	v_add_f32_dpp v100, v100, v100 quad_perm:[2,3,0,1] row_mask:0xf bank_mask:0xf bound_ctrl:1
	v_fma_mix_f32 v84, v84, v24, v102 op_sel:[0,0,0] op_sel_hi:[0,1,0]
	v_fma_mix_f32 v85, v85, v24, v103 op_sel:[0,1,0] op_sel_hi:[0,1,0]
	v_add_f32_dpp v100, v100, v100 row_half_mirror row_mask:0xf bank_mask:0xf bound_ctrl:1
	v_fma_mix_f32 v86, v86, v25, v104 op_sel:[0,0,0] op_sel_hi:[0,1,0]
	v_fma_mix_f32 v87, v87, v25, v105 op_sel:[0,1,0] op_sel_hi:[0,1,0]
	v_add_f32_dpp v100, v100, v100 row_mirror row_mask:0xf bank_mask:0xf bound_ctrl:1
	v_fma_mix_f32 v84, -v100, v32, v84 op_sel:[0,0,0] op_sel_hi:[0,1,0]
	v_fma_mix_f32 v85, -v100, v32, v85 op_sel:[0,1,0] op_sel_hi:[0,1,0]
	v_fma_mix_f32 v86, -v100, v33, v86 op_sel:[0,0,0] op_sel_hi:[0,1,0]
	v_fma_mix_f32 v87, -v100, v33, v87 op_sel:[0,1,0] op_sel_hi:[0,1,0]
	v_fma_mix_f32 v101, v84, v30, 0 op_sel:[0,0,0] op_sel_hi:[0,1,0]
	v_fma_mix_f32 v98, v84, v20, 0 op_sel:[0,0,0] op_sel_hi:[0,1,0]
	v_fma_mix_f32 v101, v85, v30, v101 op_sel:[0,1,0] op_sel_hi:[0,1,0]
	v_fma_mix_f32 v98, v85, v20, v98 op_sel:[0,1,0] op_sel_hi:[0,1,0]
	v_fma_mix_f32 v101, v86, v31, v101 op_sel:[0,0,0] op_sel_hi:[0,1,0]
	v_fma_mix_f32 v98, v86, v21, v98 op_sel:[0,0,0] op_sel_hi:[0,1,0]
	v_fma_mix_f32 v101, v87, v31, v101 op_sel:[0,1,0] op_sel_hi:[0,1,0]
	v_fma_mix_f32 v98, v87, v21, v98 op_sel:[0,1,0] op_sel_hi:[0,1,0]
	v_fma_mix_f32 v103, v89, v38, 0 op_sel:[1,0,0] op_sel_hi:[1,1,0]
	v_fma_mix_f32 v104, v89, v38, 0 op_sel:[1,1,0] op_sel_hi:[1,1,0]
	v_add_f32_dpp v101, v101, v101 quad_perm:[1,0,3,2] row_mask:0xf bank_mask:0xf bound_ctrl:1
	v_fma_mix_f32 v105, v89, v39, 0 op_sel:[1,0,0] op_sel_hi:[1,1,0]
	v_fma_mix_f32 v119, v89, v39, 0 op_sel:[1,1,0] op_sel_hi:[1,1,0]
	v_add_f32_dpp v101, v101, v101 quad_perm:[2,3,0,1] row_mask:0xf bank_mask:0xf bound_ctrl:1
	v_fma_mix_f32 v84, v84, v28, v103 op_sel:[0,0,0] op_sel_hi:[0,1,0]
	v_fma_mix_f32 v85, v85, v28, v104 op_sel:[0,1,0] op_sel_hi:[0,1,0]
	v_add_f32_dpp v101, v101, v101 row_half_mirror row_mask:0xf bank_mask:0xf bound_ctrl:1
	v_fma_mix_f32 v86, v86, v29, v105 op_sel:[0,0,0] op_sel_hi:[0,1,0]
	v_fma_mix_f32 v87, v87, v29, v119 op_sel:[0,1,0] op_sel_hi:[0,1,0]
	v_add_f32_dpp v101, v101, v101 row_mirror row_mask:0xf bank_mask:0xf bound_ctrl:1
	v_fma_mix_f32 v84, -v101, v36, v84 op_sel:[0,0,0] op_sel_hi:[0,1,0]
	v_fma_mix_f32 v85, -v101, v36, v85 op_sel:[0,1,0] op_sel_hi:[0,1,0]
	v_fma_mix_f32 v86, -v101, v37, v86 op_sel:[0,0,0] op_sel_hi:[0,1,0]
	v_fma_mix_f32 v87, -v101, v37, v87 op_sel:[0,1,0] op_sel_hi:[0,1,0]
	v_fma_mix_f32 v99, v84, v22, 0 op_sel:[0,0,0] op_sel_hi:[0,1,0]
	v_add_u32_e32 v173, 13, v193
	v_fma_mix_f32 v99, v85, v22, v99 op_sel:[0,1,0] op_sel_hi:[0,1,0]
	ds_write_b32 v172, v173 offset:49216
	v_fma_mix_f32 v99, v86, v23, v99 op_sel:[0,0,0] op_sel_hi:[0,1,0]
	v_cndmask_b32_e64 v187, v97, v96, s[38:39]
	v_fma_mix_f32 v99, v87, v23, v99 op_sel:[0,1,0] op_sel_hi:[0,1,0]
	v_cndmask_b32_e64 v188, v96, v97, s[38:39]
	v_cndmask_b32_e64 v189, v99, v98, s[38:39]
	v_cndmask_b32_e64 v190, v98, v99, s[38:39]
	s_waitcnt lgkmcnt(1)
	v_fma_mix_f32 v98, v84, v74, 0 op_sel:[0,0,0] op_sel_hi:[0,1,0]
	v_fma_mix_f32 v98, v85, v74, v98 op_sel:[0,1,0] op_sel_hi:[0,1,0]
	v_add_f32_dpp v188, v188, v187 quad_perm:[1,0,3,2] row_mask:0xf bank_mask:0xf bound_ctrl:1
	v_add_f32_dpp v189, v190, v189 quad_perm:[1,0,3,2] row_mask:0xf bank_mask:0xf bound_ctrl:1
	v_fma_mix_f32 v98, v86, v75, v98 op_sel:[0,0,0] op_sel_hi:[0,1,0]
	v_fma_mix_f32 v98, v87, v75, v98 op_sel:[0,1,0] op_sel_hi:[0,1,0]
	v_cndmask_b32_e64 v191, v189, v188, s[40:41]
	v_cndmask_b32_e64 v192, v188, v189, s[40:41]
	v_fma_mix_f32 v100, v92, v78, 0 op_sel:[0,0,0] op_sel_hi:[1,1,0]
	v_fma_mix_f32 v101, v92, v78, 0 op_sel:[0,1,0] op_sel_hi:[1,1,0]
	v_add_f32_dpp v192, v192, v191 quad_perm:[2,3,0,1] row_mask:0xf bank_mask:0xf bound_ctrl:1
	v_add_f32_dpp v98, v98, v98 quad_perm:[1,0,3,2] row_mask:0xf bank_mask:0xf bound_ctrl:1
	v_fma_mix_f32 v102, v92, v79, 0 op_sel:[0,0,0] op_sel_hi:[1,1,0]
	v_add_f32_dpp v192, v192, v192 row_ror:4 row_mask:0xf bank_mask:0xf bound_ctrl:1
	v_fma_mix_f32 v103, v92, v79, 0 op_sel:[0,1,0] op_sel_hi:[1,1,0]
	v_add_f32_dpp v98, v98, v98 quad_perm:[2,3,0,1] row_mask:0xf bank_mask:0xf bound_ctrl:1
	v_add_f32_dpp v192, v192, v192 row_ror:8 row_mask:0xf bank_mask:0xf bound_ctrl:1
	v_cvt_f16_f32_e32 v192, v192
	global_store_short v83, v192, s[36:37]
	s_add_u32 s36, s36, s44
	s_addc_u32 s37, s37, s45
	s_cmp_gt_i32 s35, 14
	s_cbranch_scc0 .Lc_poll_A6
.Lc_ret_A6:
	ds_read_b128 v[0:3], v194 offset:45056
	ds_read_b128 v[4:7], v194 offset:43008
	ds_read_b128 v[8:11], v194 offset:43264
	ds_read_b128 v[12:15], v194 offset:44032
	ds_read_b128 v[16:19], v194 offset:44288
	ds_read_b128 v[20:23], v194 offset:45312
	ds_read_b128 v[24:27], v194 offset:43520
	ds_read_b128 v[28:31], v194 offset:43776
	ds_read_b128 v[32:35], v194 offset:44544
	ds_read_b128 v[36:39], v194 offset:44800
	ds_read_b64 v[88:89], v195 offset:45568
	v_fma_mix_f32 v84, v84, v72, v100 op_sel:[0,0,0] op_sel_hi:[0,1,0]
	v_fma_mix_f32 v85, v85, v72, v101 op_sel:[0,1,0] op_sel_hi:[0,1,0]
	v_add_f32_dpp v98, v98, v98 row_half_mirror row_mask:0xf bank_mask:0xf bound_ctrl:1
	v_fma_mix_f32 v86, v86, v73, v102 op_sel:[0,0,0] op_sel_hi:[0,1,0]
	v_fma_mix_f32 v87, v87, v73, v103 op_sel:[0,1,0] op_sel_hi:[0,1,0]
	v_add_f32_dpp v98, v98, v98 row_mirror row_mask:0xf bank_mask:0xf bound_ctrl:1
	v_fma_mix_f32 v84, -v98, v76, v84 op_sel:[0,0,0] op_sel_hi:[0,1,0]
	v_fma_mix_f32 v85, -v98, v76, v85 op_sel:[0,1,0] op_sel_hi:[0,1,0]
	v_fma_mix_f32 v86, -v98, v77, v86 op_sel:[0,0,0] op_sel_hi:[0,1,0]
	v_fma_mix_f32 v87, -v98, v77, v87 op_sel:[0,1,0] op_sel_hi:[0,1,0]
	v_fma_mix_f32 v73, v84, v66, 0 op_sel:[0,0,0] op_sel_hi:[0,1,0]
	v_fma_mix_f32 v97, v84, v56, 0 op_sel:[0,0,0] op_sel_hi:[0,1,0]
	v_fma_mix_f32 v73, v85, v66, v73 op_sel:[0,1,0] op_sel_hi:[0,1,0]
	v_fma_mix_f32 v56, v85, v56, v97 op_sel:[0,1,0] op_sel_hi:[0,1,0]
	v_fma_mix_f32 v73, v86, v67, v73 op_sel:[0,0,0] op_sel_hi:[0,1,0]
	v_fma_mix_f32 v56, v86, v57, v56 op_sel:[0,0,0] op_sel_hi:[0,1,0]
	v_fma_mix_f32 v73, v87, v67, v73 op_sel:[0,1,0] op_sel_hi:[0,1,0]
	v_fma_mix_f32 v56, v87, v57, v56 op_sel:[0,1,0] op_sel_hi:[0,1,0]
	v_fma_mix_f32 v75, v92, v70, 0 op_sel:[1,0,0] op_sel_hi:[1,1,0]
	v_fma_mix_f32 v76, v92, v70, 0 op_sel:[1,1,0] op_sel_hi:[1,1,0]
	v_add_f32_dpp v73, v73, v73 quad_perm:[1,0,3,2] row_mask:0xf bank_mask:0xf bound_ctrl:1
	v_fma_mix_f32 v77, v92, v71, 0 op_sel:[1,0,0] op_sel_hi:[1,1,0]
	v_fma_mix_f32 v78, v92, v71, 0 op_sel:[1,1,0] op_sel_hi:[1,1,0]
	v_add_f32_dpp v73, v73, v73 quad_perm:[2,3,0,1] row_mask:0xf bank_mask:0xf bound_ctrl:1
	v_fma_mix_f32 v84, v84, v64, v75 op_sel:[0,0,0] op_sel_hi:[0,1,0]
	v_fma_mix_f32 v85, v85, v64, v76 op_sel:[0,1,0] op_sel_hi:[0,1,0]
	v_add_f32_dpp v73, v73, v73 row_half_mirror row_mask:0xf bank_mask:0xf bound_ctrl:1
	v_fma_mix_f32 v86, v86, v65, v77 op_sel:[0,0,0] op_sel_hi:[0,1,0]
	v_fma_mix_f32 v87, v87, v65, v78 op_sel:[0,1,0] op_sel_hi:[0,1,0]
	v_add_f32_dpp v73, v73, v73 row_mirror row_mask:0xf bank_mask:0xf bound_ctrl:1
	v_fma_mix_f32 v84, -v73, v68, v84 op_sel:[0,0,0] op_sel_hi:[0,1,0]
	v_fma_mix_f32 v85, -v73, v68, v85 op_sel:[0,1,0] op_sel_hi:[0,1,0]
	v_fma_mix_f32 v86, -v73, v69, v86 op_sel:[0,0,0] op_sel_hi:[0,1,0]
	v_fma_mix_f32 v87, -v73, v69, v87 op_sel:[0,1,0] op_sel_hi:[0,1,0]
	v_fma_mix_f32 v64, v84, v54, 0 op_sel:[0,0,0] op_sel_hi:[0,1,0]
	v_fma_mix_f32 v57, v84, v58, 0 op_sel:[0,0,0] op_sel_hi:[0,1,0]
	v_fma_mix_f32 v64, v85, v54, v64 op_sel:[0,1,0] op_sel_hi:[0,1,0]
	v_fma_mix_f32 v57, v85, v58, v57 op_sel:[0,1,0] op_sel_hi:[0,1,0]
	v_fma_mix_f32 v64, v86, v55, v64 op_sel:[0,0,0] op_sel_hi:[0,1,0]
	v_fma_mix_f32 v57, v86, v59, v57 op_sel:[0,0,0] op_sel_hi:[0,1,0]
	v_fma_mix_f32 v64, v87, v55, v64 op_sel:[0,1,0] op_sel_hi:[0,1,0]
	v_fma_mix_f32 v57, v87, v59, v57 op_sel:[0,1,0] op_sel_hi:[0,1,0]
	v_fma_mix_f32 v66, v93, v62, 0 op_sel:[0,0,0] op_sel_hi:[1,1,0]
	v_fma_mix_f32 v67, v93, v62, 0 op_sel:[0,1,0] op_sel_hi:[1,1,0]
	v_add_f32_dpp v64, v64, v64 quad_perm:[1,0,3,2] row_mask:0xf bank_mask:0xf bound_ctrl:1
	v_fma_mix_f32 v68, v93, v63, 0 op_sel:[0,0,0] op_sel_hi:[1,1,0]
	v_fma_mix_f32 v69, v93, v63, 0 op_sel:[0,1,0] op_sel_hi:[1,1,0]
	v_add_f32_dpp v64, v64, v64 quad_perm:[2,3,0,1] row_mask:0xf bank_mask:0xf bound_ctrl:1
	v_fma_mix_f32 v84, v84, v52, v66 op_sel:[0,0,0] op_sel_hi:[0,1,0]
	v_fma_mix_f32 v85, v85, v52, v67 op_sel:[0,1,0] op_sel_hi:[0,1,0]
	v_add_f32_dpp v64, v64, v64 row_half_mirror row_mask:0xf bank_mask:0xf bound_ctrl:1
	v_fma_mix_f32 v86, v86, v53, v68 op_sel:[0,0,0] op_sel_hi:[0,1,0]
	v_fma_mix_f32 v87, v87, v53, v69 op_sel:[0,1,0] op_sel_hi:[0,1,0]
	v_add_f32_dpp v64, v64, v64 row_mirror row_mask:0xf bank_mask:0xf bound_ctrl:1
	v_fma_mix_f32 v84, -v64, v60, v84 op_sel:[0,0,0] op_sel_hi:[0,1,0]
	v_fma_mix_f32 v85, -v64, v60, v85 op_sel:[0,1,0] op_sel_hi:[0,1,0]
	v_fma_mix_f32 v86, -v64, v61, v86 op_sel:[0,0,0] op_sel_hi:[0,1,0]
	v_fma_mix_f32 v87, -v64, v61, v87 op_sel:[0,1,0] op_sel_hi:[0,1,0]
	v_fma_mix_f32 v53, v84, v46, 0 op_sel:[0,0,0] op_sel_hi:[0,1,0]
	v_fma_mix_f32 v59, v84, v40, 0 op_sel:[0,0,0] op_sel_hi:[0,1,0]
	v_fma_mix_f32 v53, v85, v46, v53 op_sel:[0,1,0] op_sel_hi:[0,1,0]
	v_fma_mix_f32 v40, v85, v40, v59 op_sel:[0,1,0] op_sel_hi:[0,1,0]
	v_fma_mix_f32 v53, v86, v47, v53 op_sel:[0,0,0] op_sel_hi:[0,1,0]
	v_fma_mix_f32 v40, v86, v41, v40 op_sel:[0,0,0] op_sel_hi:[0,1,0]
	v_fma_mix_f32 v53, v87, v47, v53 op_sel:[0,1,0] op_sel_hi:[0,1,0]
	v_fma_mix_f32 v40, v87, v41, v40 op_sel:[0,1,0] op_sel_hi:[0,1,0]
	v_fma_mix_f32 v55, v93, v50, 0 op_sel:[1,0,0] op_sel_hi:[1,1,0]
	v_fma_mix_f32 v58, v93, v50, 0 op_sel:[1,1,0] op_sel_hi:[1,1,0]
	v_add_f32_dpp v53, v53, v53 quad_perm:[1,0,3,2] row_mask:0xf bank_mask:0xf bound_ctrl:1
	v_fma_mix_f32 v59, v93, v51, 0 op_sel:[1,0,0] op_sel_hi:[1,1,0]
	v_fma_mix_f32 v60, v93, v51, 0 op_sel:[1,1,0] op_sel_hi:[1,1,0]
	v_add_f32_dpp v53, v53, v53 quad_perm:[2,3,0,1] row_mask:0xf bank_mask:0xf bound_ctrl:1
	v_fma_mix_f32 v84, v84, v44, v55 op_sel:[0,0,0] op_sel_hi:[0,1,0]
	v_fma_mix_f32 v85, v85, v44, v58 op_sel:[0,1,0] op_sel_hi:[0,1,0]
	v_add_f32_dpp v53, v53, v53 row_half_mirror row_mask:0xf bank_mask:0xf bound_ctrl:1
	v_fma_mix_f32 v86, v86, v45, v59 op_sel:[0,0,0] op_sel_hi:[0,1,0]
	v_fma_mix_f32 v87, v87, v45, v60 op_sel:[0,1,0] op_sel_hi:[0,1,0]
	v_add_f32_dpp v53, v53, v53 row_mirror row_mask:0xf bank_mask:0xf bound_ctrl:1
	v_fma_mix_f32 v84, -v53, v48, v84 op_sel:[0,0,0] op_sel_hi:[0,1,0]
	v_fma_mix_f32 v85, -v53, v48, v85 op_sel:[0,1,0] op_sel_hi:[0,1,0]
	v_fma_mix_f32 v86, -v53, v49, v86 op_sel:[0,0,0] op_sel_hi:[0,1,0]
	v_fma_mix_f32 v87, -v53, v49, v87 op_sel:[0,1,0] op_sel_hi:[0,1,0]
	v_fma_mix_f32 v41, v84, v42, 0 op_sel:[0,0,0] op_sel_hi:[0,1,0]
	v_add_u32_e32 v173, 14, v193
	v_fma_mix_f32 v41, v85, v42, v41 op_sel:[0,1,0] op_sel_hi:[0,1,0]
	ds_write_b32 v172, v173 offset:49216
	v_fma_mix_f32 v41, v86, v43, v41 op_sel:[0,0,0] op_sel_hi:[0,1,0]
	v_cndmask_b32_e64 v187, v57, v56, s[38:39]
	v_fma_mix_f32 v41, v87, v43, v41 op_sel:[0,1,0] op_sel_hi:[0,1,0]
	v_cndmask_b32_e64 v188, v56, v57, s[38:39]
	v_cndmask_b32_e64 v189, v41, v40, s[38:39]
	v_cndmask_b32_e64 v190, v40, v41, s[38:39]
	s_waitcnt lgkmcnt(1)
	v_fma_mix_f32 v98, v84, v6, 0 op_sel:[0,0,0] op_sel_hi:[0,1,0]
	v_fma_mix_f32 v98, v85, v6, v98 op_sel:[0,1,0] op_sel_hi:[0,1,0]
	v_add_f32_dpp v188, v188, v187 quad_perm:[1,0,3,2] row_mask:0xf bank_mask:0xf bound_ctrl:1
	v_add_f32_dpp v189, v190, v189 quad_perm:[1,0,3,2] row_mask:0xf bank_mask:0xf bound_ctrl:1
	v_fma_mix_f32 v98, v86, v7, v98 op_sel:[0,0,0] op_sel_hi:[0,1,0]
	v_fma_mix_f32 v98, v87, v7, v98 op_sel:[0,1,0] op_sel_hi:[0,1,0]
	v_cndmask_b32_e64 v191, v189, v188, s[40:41]
	v_cndmask_b32_e64 v192, v188, v189, s[40:41]
	v_fma_mix_f32 v100, v88, v14, 0 op_sel:[0,0,0] op_sel_hi:[1,1,0]
	v_fma_mix_f32 v101, v88, v14, 0 op_sel:[0,1,0] op_sel_hi:[1,1,0]
	v_add_f32_dpp v192, v192, v191 quad_perm:[2,3,0,1] row_mask:0xf bank_mask:0xf bound_ctrl:1
	v_add_f32_dpp v98, v98, v98 quad_perm:[1,0,3,2] row_mask:0xf bank_mask:0xf bound_ctrl:1
	v_fma_mix_f32 v102, v88, v15, 0 op_sel:[0,0,0] op_sel_hi:[1,1,0]
	v_add_f32_dpp v192, v192, v192 row_ror:4 row_mask:0xf bank_mask:0xf bound_ctrl:1
	v_fma_mix_f32 v103, v88, v15, 0 op_sel:[0,1,0] op_sel_hi:[1,1,0]
	v_add_f32_dpp v98, v98, v98 quad_perm:[2,3,0,1] row_mask:0xf bank_mask:0xf bound_ctrl:1
	v_add_f32_dpp v192, v192, v192 row_ror:8 row_mask:0xf bank_mask:0xf bound_ctrl:1
	v_cvt_f16_f32_e32 v192, v192
	global_store_short v83, v192, s[36:37]
	s_add_u32 s36, s36, s44
	s_addc_u32 s37, s37, s45
	s_cmp_gt_i32 s35, 15
	s_cbranch_scc0 .Lc_poll_B6
.Lc_ret_B6:
	ds_read_b128 v[56:59], v194 offset:48128
	ds_read_b128 v[72:75], v194 offset:46080
	ds_read_b128 v[64:67], v194 offset:46336
	ds_read_b128 v[76:79], v194 offset:47104
	ds_read_b128 v[68:71], v194 offset:47360
	ds_read_b128 v[40:43], v194 offset:48384
	ds_read_b128 v[52:55], v194 offset:46592
	ds_read_b128 v[44:47], v194 offset:46848
	ds_read_b128 v[60:63], v194 offset:47616
	ds_read_b128 v[48:51], v194 offset:47872
	ds_read_b64 v[92:93], v195 offset:48640
	v_fma_mix_f32 v84, v84, v4, v100 op_sel:[0,0,0] op_sel_hi:[0,1,0]
	v_fma_mix_f32 v85, v85, v4, v101 op_sel:[0,1,0] op_sel_hi:[0,1,0]
	v_add_f32_dpp v98, v98, v98 row_half_mirror row_mask:0xf bank_mask:0xf bound_ctrl:1
	v_fma_mix_f32 v86, v86, v5, v102 op_sel:[0,0,0] op_sel_hi:[0,1,0]
	v_fma_mix_f32 v87, v87, v5, v103 op_sel:[0,1,0] op_sel_hi:[0,1,0]
	v_add_f32_dpp v98, v98, v98 row_mirror row_mask:0xf bank_mask:0xf bound_ctrl:1
	v_fma_mix_f32 v84, -v98, v12, v84 op_sel:[0,0,0] op_sel_hi:[0,1,0]
	v_fma_mix_f32 v85, -v98, v12, v85 op_sel:[0,1,0] op_sel_hi:[0,1,0]
	v_fma_mix_f32 v86, -v98, v13, v86 op_sel:[0,0,0] op_sel_hi:[0,1,0]
	v_fma_mix_f32 v87, -v98, v13, v87 op_sel:[0,1,0] op_sel_hi:[0,1,0]
	v_fma_mix_f32 v99, v84, v10, 0 op_sel:[0,0,0] op_sel_hi:[0,1,0]
	v_fma_mix_f32 v96, v84, v0, 0 op_sel:[0,0,0] op_sel_hi:[0,1,0]
	v_fma_mix_f32 v99, v85, v10, v99 op_sel:[0,1,0] op_sel_hi:[0,1,0]
	v_fma_mix_f32 v96, v85, v0, v96 op_sel:[0,1,0] op_sel_hi:[0,1,0]
	v_fma_mix_f32 v99, v86, v11, v99 op_sel:[0,0,0] op_sel_hi:[0,1,0]
	v_fma_mix_f32 v96, v86, v1, v96 op_sel:[0,0,0] op_sel_hi:[0,1,0]
	v_fma_mix_f32 v99, v87, v11, v99 op_sel:[0,1,0] op_sel_hi:[0,1,0]
	v_fma_mix_f32 v96, v87, v1, v96 op_sel:[0,1,0] op_sel_hi:[0,1,0]
	v_fma_mix_f32 v101, v88, v18, 0 op_sel:[1,0,0] op_sel_hi:[1,1,0]
	v_fma_mix_f32 v102, v88, v18, 0 op_sel:[1,1,0] op_sel_hi:[1,1,0]
	v_add_f32_dpp v99, v99, v99 quad_perm:[1,0,3,2] row_mask:0xf bank_mask:0xf bound_ctrl:1
	v_fma_mix_f32 v103, v88, v19, 0 op_sel:[1,0,0] op_sel_hi:[1,1,0]
	v_fma_mix_f32 v104, v88, v19, 0 op_sel:[1,1,0] op_sel_hi:[1,1,0]
	v_add_f32_dpp v99, v99, v99 quad_perm:[2,3,0,1] row_mask:0xf bank_mask:0xf bound_ctrl:1
	v_fma_mix_f32 v84, v84, v8, v101 op_sel:[0,0,0] op_sel_hi:[0,1,0]
	v_fma_mix_f32 v85, v85, v8, v102 op_sel:[0,1,0] op_sel_hi:[0,1,0]
	v_add_f32_dpp v99, v99, v99 row_half_mirror row_mask:0xf bank_mask:0xf bound_ctrl:1
	v_fma_mix_f32 v86, v86, v9, v103 op_sel:[0,0,0] op_sel_hi:[0,1,0]
	v_fma_mix_f32 v87, v87, v9, v104 op_sel:[0,1,0] op_sel_hi:[0,1,0]
	v_add_f32_dpp v99, v99, v99 row_mirror row_mask:0xf bank_mask:0xf bound_ctrl:1
	v_fma_mix_f32 v84, -v99, v16, v84 op_sel:[0,0,0] op_sel_hi:[0,1,0]
	v_fma_mix_f32 v85, -v99, v16, v85 op_sel:[0,1,0] op_sel_hi:[0,1,0]
	v_fma_mix_f32 v86, -v99, v17, v86 op_sel:[0,0,0] op_sel_hi:[0,1,0]
	v_fma_mix_f32 v87, -v99, v17, v87 op_sel:[0,1,0] op_sel_hi:[0,1,0]
	v_fma_mix_f32 v100, v84, v26, 0 op_sel:[0,0,0] op_sel_hi:[0,1,0]
	v_fma_mix_f32 v97, v84, v2, 0 op_sel:[0,0,0] op_sel_hi:[0,1,0]
	v_fma_mix_f32 v100, v85, v26, v100 op_sel:[0,1,0] op_sel_hi:[0,1,0]
	v_fma_mix_f32 v97, v85, v2, v97 op_sel:[0,1,0] op_sel_hi:[0,1,0]
	v_fma_mix_f32 v100, v86, v27, v100 op_sel:[0,0,0] op_sel_hi:[0,1,0]
	v_fma_mix_f32 v97, v86, v3, v97 op_sel:[0,0,0] op_sel_hi:[0,1,0]
	v_fma_mix_f32 v100, v87, v27, v100 op_sel:[0,1,0] op_sel_hi:[0,1,0]
	v_fma_mix_f32 v97, v87, v3, v97 op_sel:[0,1,0] op_sel_hi:[0,1,0]
	v_fma_mix_f32 v102, v89, v34, 0 op_sel:[0,0,0] op_sel_hi:[1,1,0]
	v_fma_mix_f32 v103, v89, v34, 0 op_sel:[0,1,0] op_sel_hi:[1,1,0]
	v_add_f32_dpp v100, v100, v100 quad_perm:[1,0,3,2] row_mask:0xf bank_mask:0xf bound_ctrl:1
	v_fma_mix_f32 v104, v89, v35, 0 op_sel:[0,0,0] op_sel_hi:[1,1,0]
	v_fma_mix_f32 v105, v89, v35, 0 op_sel:[0,1,0] op_sel_hi:[1,1,0]
	v_add_f32_dpp v100, v100, v100 quad_perm:[2,3,0,1] row_mask:0xf bank_mask:0xf bound_ctrl:1
	v_fma_mix_f32 v84, v84, v24, v102 op_sel:[0,0,0] op_sel_hi:[0,1,0]
	v_fma_mix_f32 v85, v85, v24, v103 op_sel:[0,1,0] op_sel_hi:[0,1,0]
	v_add_f32_dpp v100, v100, v100 row_half_mirror row_mask:0xf bank_mask:0xf bound_ctrl:1
	v_fma_mix_f32 v86, v86, v25, v104 op_sel:[0,0,0] op_sel_hi:[0,1,0]
	v_fma_mix_f32 v87, v87, v25, v105 op_sel:[0,1,0] op_sel_hi:[0,1,0]
	v_add_f32_dpp v100, v100, v100 row_mirror row_mask:0xf bank_mask:0xf bound_ctrl:1
	v_fma_mix_f32 v84, -v100, v32, v84 op_sel:[0,0,0] op_sel_hi:[0,1,0]
	v_fma_mix_f32 v85, -v100, v32, v85 op_sel:[0,1,0] op_sel_hi:[0,1,0]
	v_fma_mix_f32 v86, -v100, v33, v86 op_sel:[0,0,0] op_sel_hi:[0,1,0]
	v_fma_mix_f32 v87, -v100, v33, v87 op_sel:[0,1,0] op_sel_hi:[0,1,0]
	v_fma_mix_f32 v101, v84, v30, 0 op_sel:[0,0,0] op_sel_hi:[0,1,0]
	v_fma_mix_f32 v98, v84, v20, 0 op_sel:[0,0,0] op_sel_hi:[0,1,0]
	v_fma_mix_f32 v101, v85, v30, v101 op_sel:[0,1,0] op_sel_hi:[0,1,0]
	v_fma_mix_f32 v98, v85, v20, v98 op_sel:[0,1,0] op_sel_hi:[0,1,0]
	v_fma_mix_f32 v101, v86, v31, v101 op_sel:[0,0,0] op_sel_hi:[0,1,0]
	v_fma_mix_f32 v98, v86, v21, v98 op_sel:[0,0,0] op_sel_hi:[0,1,0]
	v_fma_mix_f32 v101, v87, v31, v101 op_sel:[0,1,0] op_sel_hi:[0,1,0]
	v_fma_mix_f32 v98, v87, v21, v98 op_sel:[0,1,0] op_sel_hi:[0,1,0]
	v_fma_mix_f32 v103, v89, v38, 0 op_sel:[1,0,0] op_sel_hi:[1,1,0]
	v_fma_mix_f32 v104, v89, v38, 0 op_sel:[1,1,0] op_sel_hi:[1,1,0]
	v_add_f32_dpp v101, v101, v101 quad_perm:[1,0,3,2] row_mask:0xf bank_mask:0xf bound_ctrl:1
	v_fma_mix_f32 v105, v89, v39, 0 op_sel:[1,0,0] op_sel_hi:[1,1,0]
	v_fma_mix_f32 v119, v89, v39, 0 op_sel:[1,1,0] op_sel_hi:[1,1,0]
	v_add_f32_dpp v101, v101, v101 quad_perm:[2,3,0,1] row_mask:0xf bank_mask:0xf bound_ctrl:1
	v_fma_mix_f32 v84, v84, v28, v103 op_sel:[0,0,0] op_sel_hi:[0,1,0]
	v_fma_mix_f32 v85, v85, v28, v104 op_sel:[0,1,0] op_sel_hi:[0,1,0]
	v_add_f32_dpp v101, v101, v101 row_half_mirror row_mask:0xf bank_mask:0xf bound_ctrl:1
	v_fma_mix_f32 v86, v86, v29, v105 op_sel:[0,0,0] op_sel_hi:[0,1,0]
	v_fma_mix_f32 v87, v87, v29, v119 op_sel:[0,1,0] op_sel_hi:[0,1,0]
	v_add_f32_dpp v101, v101, v101 row_mirror row_mask:0xf bank_mask:0xf bound_ctrl:1
	v_fma_mix_f32 v84, -v101, v36, v84 op_sel:[0,0,0] op_sel_hi:[0,1,0]
	v_fma_mix_f32 v85, -v101, v36, v85 op_sel:[0,1,0] op_sel_hi:[0,1,0]
	v_fma_mix_f32 v86, -v101, v37, v86 op_sel:[0,0,0] op_sel_hi:[0,1,0]
	v_fma_mix_f32 v87, -v101, v37, v87 op_sel:[0,1,0] op_sel_hi:[0,1,0]
	v_fma_mix_f32 v99, v84, v22, 0 op_sel:[0,0,0] op_sel_hi:[0,1,0]
	v_add_u32_e32 v173, 15, v193
	v_fma_mix_f32 v99, v85, v22, v99 op_sel:[0,1,0] op_sel_hi:[0,1,0]
	ds_write_b32 v172, v173 offset:49216
	v_fma_mix_f32 v99, v86, v23, v99 op_sel:[0,0,0] op_sel_hi:[0,1,0]
	v_cndmask_b32_e64 v187, v97, v96, s[38:39]
	v_fma_mix_f32 v99, v87, v23, v99 op_sel:[0,1,0] op_sel_hi:[0,1,0]
	v_cndmask_b32_e64 v188, v96, v97, s[38:39]
	v_cndmask_b32_e64 v189, v99, v98, s[38:39]
	v_cndmask_b32_e64 v190, v98, v99, s[38:39]
	s_waitcnt lgkmcnt(1)
	v_fma_mix_f32 v98, v84, v74, 0 op_sel:[0,0,0] op_sel_hi:[0,1,0]
	v_fma_mix_f32 v98, v85, v74, v98 op_sel:[0,1,0] op_sel_hi:[0,1,0]
	v_add_f32_dpp v188, v188, v187 quad_perm:[1,0,3,2] row_mask:0xf bank_mask:0xf bound_ctrl:1
	v_add_f32_dpp v189, v190, v189 quad_perm:[1,0,3,2] row_mask:0xf bank_mask:0xf bound_ctrl:1
	v_fma_mix_f32 v98, v86, v75, v98 op_sel:[0,0,0] op_sel_hi:[0,1,0]
	v_fma_mix_f32 v98, v87, v75, v98 op_sel:[0,1,0] op_sel_hi:[0,1,0]
	v_cndmask_b32_e64 v191, v189, v188, s[40:41]
	v_cndmask_b32_e64 v192, v188, v189, s[40:41]
	v_fma_mix_f32 v100, v92, v78, 0 op_sel:[0,0,0] op_sel_hi:[1,1,0]
	v_fma_mix_f32 v101, v92, v78, 0 op_sel:[0,1,0] op_sel_hi:[1,1,0]
	v_add_f32_dpp v192, v192, v191 quad_perm:[2,3,0,1] row_mask:0xf bank_mask:0xf bound_ctrl:1
	v_add_f32_dpp v98, v98, v98 quad_perm:[1,0,3,2] row_mask:0xf bank_mask:0xf bound_ctrl:1
	v_fma_mix_f32 v102, v92, v79, 0 op_sel:[0,0,0] op_sel_hi:[1,1,0]
	v_add_f32_dpp v192, v192, v192 row_ror:4 row_mask:0xf bank_mask:0xf bound_ctrl:1
	v_fma_mix_f32 v103, v92, v79, 0 op_sel:[0,1,0] op_sel_hi:[1,1,0]
	v_add_f32_dpp v98, v98, v98 quad_perm:[2,3,0,1] row_mask:0xf bank_mask:0xf bound_ctrl:1
	v_add_f32_dpp v192, v192, v192 row_ror:8 row_mask:0xf bank_mask:0xf bound_ctrl:1
	v_cvt_f16_f32_e32 v192, v192
	global_store_short v83, v192, s[36:37]
	s_add_u32 s36, s36, s44
	s_addc_u32 s37, s37, s45
	s_cmp_gt_i32 s35, 16
	s_cbranch_scc0 .Lc_poll_A7
.Lc_ret_A7:
	ds_read_b128 v[0:3], v194 offset:2048
	ds_read_b128 v[4:7], v194 offset:0
	ds_read_b128 v[8:11], v194 offset:256
	ds_read_b128 v[12:15], v194 offset:1024
	ds_read_b128 v[16:19], v194 offset:1280
	ds_read_b128 v[20:23], v194 offset:2304
	ds_read_b128 v[24:27], v194 offset:512
	ds_read_b128 v[28:31], v194 offset:768
	ds_read_b128 v[32:35], v194 offset:1536
	ds_read_b128 v[36:39], v194 offset:1792
	ds_read_b64 v[88:89], v195 offset:2560
	v_fma_mix_f32 v84, v84, v72, v100 op_sel:[0,0,0] op_sel_hi:[0,1,0]
	v_fma_mix_f32 v85, v85, v72, v101 op_sel:[0,1,0] op_sel_hi:[0,1,0]
	v_add_f32_dpp v98, v98, v98 row_half_mirror row_mask:0xf bank_mask:0xf bound_ctrl:1
	v_fma_mix_f32 v86, v86, v73, v102 op_sel:[0,0,0] op_sel_hi:[0,1,0]
	v_fma_mix_f32 v87, v87, v73, v103 op_sel:[0,1,0] op_sel_hi:[0,1,0]
	v_add_f32_dpp v98, v98, v98 row_mirror row_mask:0xf bank_mask:0xf bound_ctrl:1
	v_fma_mix_f32 v84, -v98, v76, v84 op_sel:[0,0,0] op_sel_hi:[0,1,0]
	v_fma_mix_f32 v85, -v98, v76, v85 op_sel:[0,1,0] op_sel_hi:[0,1,0]
	v_fma_mix_f32 v86, -v98, v77, v86 op_sel:[0,0,0] op_sel_hi:[0,1,0]
	v_fma_mix_f32 v87, -v98, v77, v87 op_sel:[0,1,0] op_sel_hi:[0,1,0]
	v_fma_mix_f32 v73, v84, v66, 0 op_sel:[0,0,0] op_sel_hi:[0,1,0]
	v_fma_mix_f32 v97, v84, v56, 0 op_sel:[0,0,0] op_sel_hi:[0,1,0]
	v_fma_mix_f32 v73, v85, v66, v73 op_sel:[0,1,0] op_sel_hi:[0,1,0]
	v_fma_mix_f32 v56, v85, v56, v97 op_sel:[0,1,0] op_sel_hi:[0,1,0]
	v_fma_mix_f32 v73, v86, v67, v73 op_sel:[0,0,0] op_sel_hi:[0,1,0]
	v_fma_mix_f32 v56, v86, v57, v56 op_sel:[0,0,0] op_sel_hi:[0,1,0]
	v_fma_mix_f32 v73, v87, v67, v73 op_sel:[0,1,0] op_sel_hi:[0,1,0]
	v_fma_mix_f32 v56, v87, v57, v56 op_sel:[0,1,0] op_sel_hi:[0,1,0]
	v_fma_mix_f32 v75, v92, v70, 0 op_sel:[1,0,0] op_sel_hi:[1,1,0]
	v_fma_mix_f32 v76, v92, v70, 0 op_sel:[1,1,0] op_sel_hi:[1,1,0]
	v_add_f32_dpp v73, v73, v73 quad_perm:[1,0,3,2] row_mask:0xf bank_mask:0xf bound_ctrl:1
	v_fma_mix_f32 v77, v92, v71, 0 op_sel:[1,0,0] op_sel_hi:[1,1,0]
	v_fma_mix_f32 v78, v92, v71, 0 op_sel:[1,1,0] op_sel_hi:[1,1,0]
	v_add_f32_dpp v73, v73, v73 quad_perm:[2,3,0,1] row_mask:0xf bank_mask:0xf bound_ctrl:1
	v_fma_mix_f32 v84, v84, v64, v75 op_sel:[0,0,0] op_sel_hi:[0,1,0]
	v_fma_mix_f32 v85, v85, v64, v76 op_sel:[0,1,0] op_sel_hi:[0,1,0]
	v_add_f32_dpp v73, v73, v73 row_half_mirror row_mask:0xf bank_mask:0xf bound_ctrl:1
	v_fma_mix_f32 v86, v86, v65, v77 op_sel:[0,0,0] op_sel_hi:[0,1,0]
	v_fma_mix_f32 v87, v87, v65, v78 op_sel:[0,1,0] op_sel_hi:[0,1,0]
	v_add_f32_dpp v73, v73, v73 row_mirror row_mask:0xf bank_mask:0xf bound_ctrl:1
	v_fma_mix_f32 v84, -v73, v68, v84 op_sel:[0,0,0] op_sel_hi:[0,1,0]
	v_fma_mix_f32 v85, -v73, v68, v85 op_sel:[0,1,0] op_sel_hi:[0,1,0]
	v_fma_mix_f32 v86, -v73, v69, v86 op_sel:[0,0,0] op_sel_hi:[0,1,0]
	v_fma_mix_f32 v87, -v73, v69, v87 op_sel:[0,1,0] op_sel_hi:[0,1,0]
	v_fma_mix_f32 v64, v84, v54, 0 op_sel:[0,0,0] op_sel_hi:[0,1,0]
	v_fma_mix_f32 v57, v84, v58, 0 op_sel:[0,0,0] op_sel_hi:[0,1,0]
	v_fma_mix_f32 v64, v85, v54, v64 op_sel:[0,1,0] op_sel_hi:[0,1,0]
	v_fma_mix_f32 v57, v85, v58, v57 op_sel:[0,1,0] op_sel_hi:[0,1,0]
	v_fma_mix_f32 v64, v86, v55, v64 op_sel:[0,0,0] op_sel_hi:[0,1,0]
	v_fma_mix_f32 v57, v86, v59, v57 op_sel:[0,0,0] op_sel_hi:[0,1,0]
	v_fma_mix_f32 v64, v87, v55, v64 op_sel:[0,1,0] op_sel_hi:[0,1,0]
	v_fma_mix_f32 v57, v87, v59, v57 op_sel:[0,1,0] op_sel_hi:[0,1,0]
	v_fma_mix_f32 v66, v93, v62, 0 op_sel:[0,0,0] op_sel_hi:[1,1,0]
	v_fma_mix_f32 v67, v93, v62, 0 op_sel:[0,1,0] op_sel_hi:[1,1,0]
	v_add_f32_dpp v64, v64, v64 quad_perm:[1,0,3,2] row_mask:0xf bank_mask:0xf bound_ctrl:1
	v_fma_mix_f32 v68, v93, v63, 0 op_sel:[0,0,0] op_sel_hi:[1,1,0]
	v_fma_mix_f32 v69, v93, v63, 0 op_sel:[0,1,0] op_sel_hi:[1,1,0]
	v_add_f32_dpp v64, v64, v64 quad_perm:[2,3,0,1] row_mask:0xf bank_mask:0xf bound_ctrl:1
	v_fma_mix_f32 v84, v84, v52, v66 op_sel:[0,0,0] op_sel_hi:[0,1,0]
	v_fma_mix_f32 v85, v85, v52, v67 op_sel:[0,1,0] op_sel_hi:[0,1,0]
	v_add_f32_dpp v64, v64, v64 row_half_mirror row_mask:0xf bank_mask:0xf bound_ctrl:1
	v_fma_mix_f32 v86, v86, v53, v68 op_sel:[0,0,0] op_sel_hi:[0,1,0]
	v_fma_mix_f32 v87, v87, v53, v69 op_sel:[0,1,0] op_sel_hi:[0,1,0]
	v_add_f32_dpp v64, v64, v64 row_mirror row_mask:0xf bank_mask:0xf bound_ctrl:1
	v_fma_mix_f32 v84, -v64, v60, v84 op_sel:[0,0,0] op_sel_hi:[0,1,0]
	v_fma_mix_f32 v85, -v64, v60, v85 op_sel:[0,1,0] op_sel_hi:[0,1,0]
	v_fma_mix_f32 v86, -v64, v61, v86 op_sel:[0,0,0] op_sel_hi:[0,1,0]
	v_fma_mix_f32 v87, -v64, v61, v87 op_sel:[0,1,0] op_sel_hi:[0,1,0]
	v_fma_mix_f32 v53, v84, v46, 0 op_sel:[0,0,0] op_sel_hi:[0,1,0]
	v_fma_mix_f32 v59, v84, v40, 0 op_sel:[0,0,0] op_sel_hi:[0,1,0]
	v_fma_mix_f32 v53, v85, v46, v53 op_sel:[0,1,0] op_sel_hi:[0,1,0]
	v_fma_mix_f32 v40, v85, v40, v59 op_sel:[0,1,0] op_sel_hi:[0,1,0]
	v_fma_mix_f32 v53, v86, v47, v53 op_sel:[0,0,0] op_sel_hi:[0,1,0]
	v_fma_mix_f32 v40, v86, v41, v40 op_sel:[0,0,0] op_sel_hi:[0,1,0]
	v_fma_mix_f32 v53, v87, v47, v53 op_sel:[0,1,0] op_sel_hi:[0,1,0]
	v_fma_mix_f32 v40, v87, v41, v40 op_sel:[0,1,0] op_sel_hi:[0,1,0]
	v_fma_mix_f32 v55, v93, v50, 0 op_sel:[1,0,0] op_sel_hi:[1,1,0]
	v_fma_mix_f32 v58, v93, v50, 0 op_sel:[1,1,0] op_sel_hi:[1,1,0]
	v_add_f32_dpp v53, v53, v53 quad_perm:[1,0,3,2] row_mask:0xf bank_mask:0xf bound_ctrl:1
	v_fma_mix_f32 v59, v93, v51, 0 op_sel:[1,0,0] op_sel_hi:[1,1,0]
	v_fma_mix_f32 v60, v93, v51, 0 op_sel:[1,1,0] op_sel_hi:[1,1,0]
	v_add_f32_dpp v53, v53, v53 quad_perm:[2,3,0,1] row_mask:0xf bank_mask:0xf bound_ctrl:1
	v_fma_mix_f32 v84, v84, v44, v55 op_sel:[0,0,0] op_sel_hi:[0,1,0]
	v_fma_mix_f32 v85, v85, v44, v58 op_sel:[0,1,0] op_sel_hi:[0,1,0]
	v_add_f32_dpp v53, v53, v53 row_half_mirror row_mask:0xf bank_mask:0xf bound_ctrl:1
	v_fma_mix_f32 v86, v86, v45, v59 op_sel:[0,0,0] op_sel_hi:[0,1,0]
	v_fma_mix_f32 v87, v87, v45, v60 op_sel:[0,1,0] op_sel_hi:[0,1,0]
	v_add_f32_dpp v53, v53, v53 row_mirror row_mask:0xf bank_mask:0xf bound_ctrl:1
	v_fma_mix_f32 v84, -v53, v48, v84 op_sel:[0,0,0] op_sel_hi:[0,1,0]
	v_fma_mix_f32 v85, -v53, v48, v85 op_sel:[0,1,0] op_sel_hi:[0,1,0]
	v_fma_mix_f32 v86, -v53, v49, v86 op_sel:[0,0,0] op_sel_hi:[0,1,0]
	v_fma_mix_f32 v87, -v53, v49, v87 op_sel:[0,1,0] op_sel_hi:[0,1,0]
	v_fma_mix_f32 v41, v84, v42, 0 op_sel:[0,0,0] op_sel_hi:[0,1,0]
	v_add_u32_e32 v173, 16, v193
	v_fma_mix_f32 v41, v85, v42, v41 op_sel:[0,1,0] op_sel_hi:[0,1,0]
	ds_write_b32 v172, v173 offset:49216
	v_fma_mix_f32 v41, v86, v43, v41 op_sel:[0,0,0] op_sel_hi:[0,1,0]
	v_cndmask_b32_e64 v187, v57, v56, s[38:39]
	v_fma_mix_f32 v41, v87, v43, v41 op_sel:[0,1,0] op_sel_hi:[0,1,0]
	v_cndmask_b32_e64 v188, v56, v57, s[38:39]
	v_cndmask_b32_e64 v189, v41, v40, s[38:39]
	v_cndmask_b32_e64 v190, v40, v41, s[38:39]
	s_waitcnt lgkmcnt(1)
	v_fma_mix_f32 v98, v84, v6, 0 op_sel:[0,0,0] op_sel_hi:[0,1,0]
	v_fma_mix_f32 v98, v85, v6, v98 op_sel:[0,1,0] op_sel_hi:[0,1,0]
	v_add_f32_dpp v188, v188, v187 quad_perm:[1,0,3,2] row_mask:0xf bank_mask:0xf bound_ctrl:1
	v_add_f32_dpp v189, v190, v189 quad_perm:[1,0,3,2] row_mask:0xf bank_mask:0xf bound_ctrl:1
	v_fma_mix_f32 v98, v86, v7, v98 op_sel:[0,0,0] op_sel_hi:[0,1,0]
	v_fma_mix_f32 v98, v87, v7, v98 op_sel:[0,1,0] op_sel_hi:[0,1,0]
	v_cndmask_b32_e64 v191, v189, v188, s[40:41]
	v_cndmask_b32_e64 v192, v188, v189, s[40:41]
	v_fma_mix_f32 v100, v88, v14, 0 op_sel:[0,0,0] op_sel_hi:[1,1,0]
	v_fma_mix_f32 v101, v88, v14, 0 op_sel:[0,1,0] op_sel_hi:[1,1,0]
	v_add_f32_dpp v192, v192, v191 quad_perm:[2,3,0,1] row_mask:0xf bank_mask:0xf bound_ctrl:1
	v_add_f32_dpp v98, v98, v98 quad_perm:[1,0,3,2] row_mask:0xf bank_mask:0xf bound_ctrl:1
	v_fma_mix_f32 v102, v88, v15, 0 op_sel:[0,0,0] op_sel_hi:[1,1,0]
	v_add_f32_dpp v192, v192, v192 row_ror:4 row_mask:0xf bank_mask:0xf bound_ctrl:1
	v_fma_mix_f32 v103, v88, v15, 0 op_sel:[0,1,0] op_sel_hi:[1,1,0]
	v_add_f32_dpp v98, v98, v98 quad_perm:[2,3,0,1] row_mask:0xf bank_mask:0xf bound_ctrl:1
	v_add_f32_dpp v192, v192, v192 row_ror:8 row_mask:0xf bank_mask:0xf bound_ctrl:1
	v_cvt_f16_f32_e32 v192, v192
	global_store_short v83, v192, s[36:37]
	s_add_u32 s36, s36, s44
	s_addc_u32 s37, s37, s45
	s_cmp_gt_i32 s35, 17
	s_cbranch_scc0 .Lc_poll_B7
; #define RC_WAIT(gq) { if (pseen <= (gq)) { do { pseen = __builtin_amdgcn_readfirstlane(*pflag); if (pseen <= (gq)) __builtin_amdgcn_s_sleep(1); } while (pseen <= (gq)); } asm volatile("" ::: "memory"); }
; DEV void rwkv_consumer(const Params& p, const Ctx& cx, int l, int task, int lane, const char* ring, int widx) {
;     ...
;   for (int g = 0; g < RW_NG; g += 2) {
;     RC_WAIT(g + 1); RC_LOAD(B, g + 1);
;     RC_COMP(A, g);
.Lc_ret_B7:
	ds_read_b128 v[56:59], v194 offset:5120
	ds_read_b128 v[72:75], v194 offset:3072
	ds_read_b128 v[64:67], v194 offset:3328
	ds_read_b128 v[76:79], v194 offset:4096
	ds_read_b128 v[68:71], v194 offset:4352
	ds_read_b128 v[40:43], v194 offset:5376
	ds_read_b128 v[52:55], v194 offset:3584
	ds_read_b128 v[44:47], v194 offset:3840
	ds_read_b128 v[60:63], v194 offset:4608
	ds_read_b128 v[48:51], v194 offset:4864
	ds_read_b64 v[92:93], v195 offset:5632
	s_add_i32 s33, s33, 16
	s_sub_i32 s35, s35, 16
	v_mov_b32_e32 v193, s33
	s_cmp_eq_u32 s33, 64
	s_cbranch_scc1 .Lc_fix

.Lc_poll_A0:
.Lc_pollx_A0:
	ds_read_b32 v173, v161 offset:49152
	s_waitcnt lgkmcnt(0)
	v_readfirstlane_b32 s0, v173
	s_sub_i32 s35, s0, s33
	s_cmp_gt_i32 s35, 2
	s_cbranch_scc1 .Lc_ret_A0
	s_sleep 1
	s_branch .Lc_pollx_A0
.Lc_poll_B0:
.Lc_pollx_B0:
	ds_read_b32 v173, v161 offset:49152
	s_waitcnt lgkmcnt(0)
	v_readfirstlane_b32 s0, v173
	s_sub_i32 s35, s0, s33
	s_cmp_gt_i32 s35, 3
	s_cbranch_scc1 .Lc_ret_B0
	s_sleep 1
	s_branch .Lc_pollx_B0
.Lc_poll_A1:
.Lc_pollx_A1:
	ds_read_b32 v173, v161 offset:49152
	s_waitcnt lgkmcnt(0)
	v_readfirstlane_b32 s0, v173
	s_sub_i32 s35, s0, s33
	s_cmp_gt_i32 s35, 4
	s_cbranch_scc1 .Lc_ret_A1
	s_sleep 1
	s_branch .Lc_pollx_A1
.Lc_poll_B1:
.Lc_pollx_B1:
	ds_read_b32 v173, v161 offset:49152
	s_waitcnt lgkmcnt(0)
	v_readfirstlane_b32 s0, v173
	s_sub_i32 s35, s0, s33
	s_cmp_gt_i32 s35, 5
	s_cbranch_scc1 .Lc_ret_B1
	s_sleep 1
	s_branch .Lc_pollx_B1
.Lc_poll_A2:
.Lc_pollx_A2:
	ds_read_b32 v173, v161 offset:49152
	s_waitcnt lgkmcnt(0)
	v_readfirstlane_b32 s0, v173
	s_sub_i32 s35, s0, s33
	s_cmp_gt_i32 s35, 6
	s_cbranch_scc1 .Lc_ret_A2
	s_sleep 1
	s_branch .Lc_pollx_A2
.Lc_poll_B2:
.Lc_pollx_B2:
	ds_read_b32 v173, v161 offset:49152
	s_waitcnt lgkmcnt(0)
	v_readfirstlane_b32 s0, v173
	s_sub_i32 s35, s0, s33
	s_cmp_gt_i32 s35, 7
	s_cbranch_scc1 .Lc_ret_B2
	s_sleep 1
	s_branch .Lc_pollx_B2
.Lc_poll_A3:
.Lc_pollx_A3:
	ds_read_b32 v173, v161 offset:49152
	s_waitcnt lgkmcnt(0)
	v_readfirstlane_b32 s0, v173
	s_sub_i32 s35, s0, s33
	s_cmp_gt_i32 s35, 8
	s_cbranch_scc1 .Lc_ret_A3
	s_sleep 1
	s_branch .Lc_pollx_A3
.Lc_poll_B3:
.Lc_pollx_B3:
	ds_read_b32 v173, v161 offset:49152
	s_waitcnt lgkmcnt(0)
	v_readfirstlane_b32 s0, v173
	s_sub_i32 s35, s0, s33
	s_cmp_gt_i32 s35, 9
	s_cbranch_scc1 .Lc_ret_B3
	s_sleep 1
	s_branch .Lc_pollx_B3
.Lc_poll_A4:
.Lc_pollx_A4:
	ds_read_b32 v173, v161 offset:49152
	s_waitcnt lgkmcnt(0)
	v_readfirstlane_b32 s0, v173
	s_sub_i32 s35, s0, s33
	s_cmp_gt_i32 s35, 10
	s_cbranch_scc1 .Lc_ret_A4
	s_sleep 1
	s_branch .Lc_pollx_A4
.Lc_poll_B4:
.Lc_pollx_B4:
	ds_read_b32 v173, v161 offset:49152
	s_waitcnt lgkmcnt(0)
	v_readfirstlane_b32 s0, v173
	s_sub_i32 s35, s0, s33
	s_cmp_gt_i32 s35, 11
	s_cbranch_scc1 .Lc_ret_B4
	s_sleep 1
	s_branch .Lc_pollx_B4
.Lc_poll_A5:
.Lc_pollx_A5:
	ds_read_b32 v173, v161 offset:49152
	s_waitcnt lgkmcnt(0)
	v_readfirstlane_b32 s0, v173
	s_sub_i32 s35, s0, s33
	s_cmp_gt_i32 s35, 12
	s_cbranch_scc1 .Lc_ret_A5
	s_sleep 1
	s_branch .Lc_pollx_A5
.Lc_poll_B5:
.Lc_pollx_B5:
	ds_read_b32 v173, v161 offset:49152
	s_waitcnt lgkmcnt(0)
	v_readfirstlane_b32 s0, v173
	s_sub_i32 s35, s0, s33
	s_cmp_gt_i32 s35, 13
	s_cbranch_scc1 .Lc_ret_B5
	s_sleep 1
	s_branch .Lc_pollx_B5
.Lc_poll_A6:
.Lc_pollx_A6:
	ds_read_b32 v173, v161 offset:49152
	s_waitcnt lgkmcnt(0)
	v_readfirstlane_b32 s0, v173
	s_sub_i32 s35, s0, s33
	s_cmp_gt_i32 s35, 14
	s_cbranch_scc1 .Lc_ret_A6
	s_sleep 1
	s_branch .Lc_pollx_A6
.Lc_poll_B6:
.Lc_pollx_B6:
	ds_read_b32 v173, v161 offset:49152
	s_waitcnt lgkmcnt(0)
	v_readfirstlane_b32 s0, v173
	s_sub_i32 s35, s0, s33
	s_cmp_gt_i32 s35, 15
	s_cbranch_scc1 .Lc_ret_B6
	s_sleep 1
	s_branch .Lc_pollx_B6
.Lc_poll_A7:
	s_cmpk_ge_u32 s33, 0x1030
	s_cbranch_scc1 .Lc_ret_A7
.Lc_pollx_A7:
	ds_read_b32 v173, v161 offset:49152
	s_waitcnt lgkmcnt(0)
	v_readfirstlane_b32 s0, v173
	s_sub_i32 s35, s0, s33
	s_cmp_gt_i32 s35, 16
	s_cbranch_scc1 .Lc_ret_A7
	s_sleep 1
	s_branch .Lc_pollx_A7

.Lc_pollx_B7:
	ds_read_b32 v173, v161 offset:49152
	s_waitcnt lgkmcnt(0)
	v_readfirstlane_b32 s0, v173
	s_sub_i32 s35, s0, s33
	s_cmp_gt_i32 s35, 17
	s_cbranch_scc1 .Lc_ret_B7
	s_sleep 1
	s_branch .Lc_pollx_B7
